# v20 + K-loops: s_setprio 0 moved behind the barrier that closes each MFMA block (the MFMA wave reaches the barrier one slot earlier)
# speedup vs baseline: 1.0152x; 1.0006x over previous
; #define PG8_STAGE(bufoff, gbase, voff) do { _Pragma("unroll") for (int _i = 0; _i < 2; ++_i) \
;         __builtin_amdgcn_global_load_lds((const unsigned*)((const char*)(gbase) + (voff)[_i]), (PG8_LAS unsigned*)(lds + (bufoff) + ldsw + _i * 8192), 16, 0, 0); } while (0)
; #define PG8_WAIT_V(n) asm volatile("s_waitcnt vmcnt(" #n ")" ::: "memory")
; #define PG8_WAIT_L(n) asm volatile("s_waitcnt lgkmcnt(" #n ")" ::: "memory")
; #define PG8_BAR __builtin_amdgcn_s_barrier()
; #define PG8_SCHED __builtin_amdgcn_sched_barrier(0)
;     __device__ __forceinline__ int nt(const pg8::Unit& u) const { return u.kind == 0 ? ntiles : q_nt(u.kind - 1); }
; template <class Epi, class Sched, bool ALIGN_EPI = true, bool SP2 = true>
; __device__ __forceinline__ void gemm_phase(PG8_LAS unsigned char* lds, const int K  , const Sched& S, const Epi& E) {
;     ...
;             const bool last = (t == nt - 2);
;             const char* a1 = cA + (size_t)(t + 1) * kstep;
;             const char* a2 = last ? nA : cA + (size_t)(t + 2) * kstep; const char* b2 = last ? nB : cB + (size_t)(t + 2) * kstep;
;             const char* a3 = a2 + kstep; const char* b3 = b2 + kstep;
;             if constexpr (SP2) {
;             PG8_LDB(B0, 0, 0); PG8_LDB(B1, 0, 1); PG8_SCHED; PG8_LDA(At, 0, 0); PG8_STAGE(PG8_SA(1, 1), a1 + hstep, voffA);
;             PG8_WAIT_V(8); PG8_WAIT_L(0); PG8_BAR; PG8_MMA(0, 0, At, B0); PG8_MMA(0, 1, At, B1); PG8_BAR; PG8_SCHED;
;             PG8_LDA(At, 0, 1); PG8_STAGE(PG8_SB(0, 0), b2, voffB); PG8_STAGE(PG8_SB(0, 1), b2 + hstep, voffB); PG8_STAGE(PG8_SA(0, 0), a2, voffA);
;             PG8_WAIT_V(8); PG8_WAIT_L(0); PG8_BAR; PG8_MMA(1, 0, At, B0); PG8_MMA(1, 1, At, B1); PG8_BAR; PG8_SCHED;
.LBB0_219:
	ds_read_b128 v[148:151], v154
	ds_read_b128 v[160:163], v154 offset:1024
	ds_read_b128 v[164:167], v154 offset:2048
	ds_read_b128 v[168:171], v154 offset:3072
	ds_read_b128 v[172:175], v155
	ds_read_b128 v[176:179], v155 offset:1024
	ds_read_b128 v[180:183], v155 offset:2048
	ds_read_b128 v[184:187], v155 offset:3072
	s_add_u32 s22, s20, 0xfff80080
	s_addc_u32 s23, s21, -1
	s_cmp_eq_u32 s48, 28
	s_cselect_b32 s25, s13, s23
	s_cselect_b32 s24, s44, s22
	s_cselect_b32 s23, s11, s47
	s_cselect_b32 s22, s45, s46
	v_lshl_add_u64 v[220:221], s[20:21], 0, v[140:141]
	s_add_i32 m0, s19, 0xc000
	ds_read_b128 v[188:191], v156
	ds_read_b128 v[192:195], v156 offset:1024
	ds_read_b128 v[196:199], v156 offset:2048
	ds_read_b128 v[200:203], v156 offset:3072
	ds_read_b128 v[204:207], v156 offset:4096
	ds_read_b128 v[208:211], v156 offset:5120
	ds_read_b128 v[212:215], v156 offset:6144
	ds_read_b128 v[216:219], v156 offset:7168
	global_load_lds_dwordx4 v[220:221], off
	v_lshl_add_u64 v[220:221], s[20:21], 0, v[142:143]
	s_add_i32 m0, s19, 0xe000
	s_nop 0
	global_load_lds_dwordx4 v[220:221], off
	s_waitcnt vmcnt(8)
	s_waitcnt lgkmcnt(0)
	s_setprio 1
	s_barrier
	v_mfma_f32_16x16x32_bf16 v[126:129], v[148:151], v[188:191], v[126:129]
	v_mfma_f32_16x16x32_bf16 v[118:121], v[164:167], v[188:191], v[118:121]
	v_mfma_f32_16x16x32_bf16 v[110:113], v[148:151], v[196:199], v[110:113]
	v_mfma_f32_16x16x32_bf16 v[102:105], v[164:167], v[196:199], v[102:105]
	v_mfma_f32_16x16x32_bf16 v[94:97], v[148:151], v[204:207], v[94:97]
	v_mfma_f32_16x16x32_bf16 v[86:89], v[164:167], v[204:207], v[86:89]
	v_mfma_f32_16x16x32_bf16 v[78:81], v[148:151], v[212:215], v[78:81]
	v_mfma_f32_16x16x32_bf16 v[70:73], v[164:167], v[212:215], v[70:73]
	v_mfma_f32_16x16x32_bf16 v[126:129], v[160:163], v[192:195], v[126:129]
	v_mfma_f32_16x16x32_bf16 v[118:121], v[168:171], v[192:195], v[118:121]
	v_mfma_f32_16x16x32_bf16 v[110:113], v[160:163], v[200:203], v[110:113]
	v_mfma_f32_16x16x32_bf16 v[102:105], v[168:171], v[200:203], v[102:105]
	v_mfma_f32_16x16x32_bf16 v[94:97], v[160:163], v[208:211], v[94:97]
	v_mfma_f32_16x16x32_bf16 v[86:89], v[168:171], v[208:211], v[86:89]
	v_mfma_f32_16x16x32_bf16 v[78:81], v[160:163], v[216:219], v[78:81]
	v_mfma_f32_16x16x32_bf16 v[70:73], v[168:171], v[216:219], v[70:73]
	s_setprio 0
	s_setprio 1
	v_mfma_f32_16x16x32_bf16 v[122:125], v[172:175], v[188:191], v[122:125]
	v_mfma_f32_16x16x32_bf16 v[114:117], v[180:183], v[188:191], v[114:117]
	v_mfma_f32_16x16x32_bf16 v[106:109], v[172:175], v[196:199], v[106:109]
	v_mfma_f32_16x16x32_bf16 v[98:101], v[180:183], v[196:199], v[98:101]
	v_mfma_f32_16x16x32_bf16 v[90:93], v[172:175], v[204:207], v[90:93]
	v_mfma_f32_16x16x32_bf16 v[82:85], v[180:183], v[204:207], v[82:85]
	v_mfma_f32_16x16x32_bf16 v[74:77], v[172:175], v[212:215], v[74:77]
	v_mfma_f32_16x16x32_bf16 v[66:69], v[180:183], v[212:215], v[66:69]
	v_mfma_f32_16x16x32_bf16 v[122:125], v[176:179], v[192:195], v[122:125]
	v_mfma_f32_16x16x32_bf16 v[114:117], v[184:187], v[192:195], v[114:117]
	v_mfma_f32_16x16x32_bf16 v[106:109], v[176:179], v[200:203], v[106:109]
	v_mfma_f32_16x16x32_bf16 v[98:101], v[184:187], v[200:203], v[98:101]
	v_mfma_f32_16x16x32_bf16 v[90:93], v[176:179], v[208:211], v[90:93]
	v_mfma_f32_16x16x32_bf16 v[82:85], v[184:187], v[208:211], v[82:85]
	v_mfma_f32_16x16x32_bf16 v[74:77], v[176:179], v[216:219], v[74:77]
	v_mfma_f32_16x16x32_bf16 v[66:69], v[184:187], v[216:219], v[66:69]
	s_barrier
	s_setprio 0
	s_add_i32 s49, s39, s29
	v_lshl_add_u64 v[220:221], s[22:23], 0, v[136:137]
	s_mov_b32 m0, s49
	ds_read_b128 v[188:191], v156 offset:16384
	ds_read_b128 v[192:195], v156 offset:17408
	ds_read_b128 v[196:199], v156 offset:18432
	ds_read_b128 v[200:203], v156 offset:19456
	ds_read_b128 v[204:207], v156 offset:20480
	ds_read_b128 v[208:211], v156 offset:21504
	ds_read_b128 v[212:215], v156 offset:22528
	ds_read_b128 v[216:219], v156 offset:23552
	global_load_lds_dwordx4 v[220:221], off
	s_add_i32 m0, s49, 0x2000
	s_add_u32 s50, s22, 0x80000
	v_lshl_add_u64 v[222:223], s[22:23], 0, v[132:133]
	s_addc_u32 s51, s23, 0
	s_add_i32 s49, s40, s29
	global_load_lds_dwordx4 v[222:223], off
	v_lshl_add_u64 v[224:225], s[50:51], 0, v[136:137]
	s_mov_b32 m0, s49
	v_lshl_add_u64 v[226:227], s[24:25], 0, v[134:135]
	global_load_lds_dwordx4 v[224:225], off
	v_lshl_add_u64 v[224:225], s[50:51], 0, v[132:133]
	s_add_i32 m0, s49, 0x2000
	s_nop 0
	global_load_lds_dwordx4 v[224:225], off
	v_lshl_add_u64 v[224:225], s[24:25], 0, v[138:139]
	s_mov_b32 m0, s19
	s_nop 0
	global_load_lds_dwordx4 v[224:225], off
	s_mov_b32 m0, s31
	s_nop 0
	global_load_lds_dwordx4 v[226:227], off
	s_waitcnt vmcnt(8)
	s_waitcnt lgkmcnt(0)
	s_setprio 1
	s_barrier
; #define PG8_STAGE(bufoff, gbase, voff) do { _Pragma("unroll") for (int _i = 0; _i < 2; ++_i) \
;         __builtin_amdgcn_global_load_lds((const unsigned*)((const char*)(gbase) + (voff)[_i]), (PG8_LAS unsigned*)(lds + (bufoff) + ldsw + _i * 8192), 16, 0, 0); } while (0)
; #define PG8_WAIT_V(n) asm volatile("s_waitcnt vmcnt(" #n ")" ::: "memory")
; #define PG8_WAIT_L(n) asm volatile("s_waitcnt lgkmcnt(" #n ")" ::: "memory")
; #define PG8_BAR __builtin_amdgcn_s_barrier()
; #define PG8_SCHED __builtin_amdgcn_sched_barrier(0)
; template <class Epi, class Sched, bool ALIGN_EPI = true, bool SP2 = true>
; __device__ __forceinline__ void gemm_phase(PG8_LAS unsigned char* lds, const int K  , const Sched& S, const Epi& E) {
;     ...
;             PG8_WAIT_V(8); PG8_WAIT_L(0); PG8_BAR; PG8_MMA(1, 0, At, B0); PG8_MMA(1, 1, At, B1); PG8_BAR; PG8_SCHED;
;             PG8_LDB(B0, 1, 0); PG8_LDB(B1, 1, 1); PG8_SCHED; PG8_LDA(At, 1, 0); PG8_STAGE(PG8_SA(0, 1), a2 + hstep, voffA);
;             PG8_WAIT_V(8); PG8_WAIT_L(0); PG8_BAR; PG8_MMA(0, 0, At, B0); PG8_MMA(0, 1, At, B1); PG8_BAR; PG8_SCHED;
	v_mfma_f32_16x16x32_bf16 v[62:65], v[148:151], v[188:191], v[62:65]
	v_mfma_f32_16x16x32_bf16 v[54:57], v[164:167], v[188:191], v[54:57]
	v_mfma_f32_16x16x32_bf16 v[46:49], v[148:151], v[196:199], v[46:49]
	v_mfma_f32_16x16x32_bf16 v[38:41], v[164:167], v[196:199], v[38:41]
	v_mfma_f32_16x16x32_bf16 v[30:33], v[148:151], v[204:207], v[30:33]
	v_mfma_f32_16x16x32_bf16 v[22:25], v[164:167], v[204:207], v[22:25]
	v_mfma_f32_16x16x32_bf16 v[14:17], v[148:151], v[212:215], v[14:17]
	v_mfma_f32_16x16x32_bf16 v[6:9], v[164:167], v[212:215], v[6:9]
	v_mfma_f32_16x16x32_bf16 v[62:65], v[160:163], v[192:195], v[62:65]
	v_mfma_f32_16x16x32_bf16 v[54:57], v[168:171], v[192:195], v[54:57]
	v_mfma_f32_16x16x32_bf16 v[46:49], v[160:163], v[200:203], v[46:49]
	v_mfma_f32_16x16x32_bf16 v[38:41], v[168:171], v[200:203], v[38:41]
	v_mfma_f32_16x16x32_bf16 v[30:33], v[160:163], v[208:211], v[30:33]
	v_mfma_f32_16x16x32_bf16 v[22:25], v[168:171], v[208:211], v[22:25]
	v_mfma_f32_16x16x32_bf16 v[14:17], v[160:163], v[216:219], v[14:17]
	v_mfma_f32_16x16x32_bf16 v[6:9], v[168:171], v[216:219], v[6:9]
	s_setprio 0
	s_setprio 1
	v_mfma_f32_16x16x32_bf16 v[58:61], v[172:175], v[188:191], v[58:61]
	v_mfma_f32_16x16x32_bf16 v[50:53], v[180:183], v[188:191], v[50:53]
	v_mfma_f32_16x16x32_bf16 v[42:45], v[172:175], v[196:199], v[42:45]
	v_mfma_f32_16x16x32_bf16 v[34:37], v[180:183], v[196:199], v[34:37]
	v_mfma_f32_16x16x32_bf16 v[26:29], v[172:175], v[204:207], v[26:29]
	v_mfma_f32_16x16x32_bf16 v[18:21], v[180:183], v[204:207], v[18:21]
	v_mfma_f32_16x16x32_bf16 v[10:13], v[172:175], v[212:215], v[10:13]
	v_mfma_f32_16x16x32_bf16 v[2:5], v[180:183], v[212:215], v[2:5]
	v_mfma_f32_16x16x32_bf16 v[58:61], v[176:179], v[192:195], v[58:61]
	v_mfma_f32_16x16x32_bf16 v[50:53], v[184:187], v[192:195], v[50:53]
	v_mfma_f32_16x16x32_bf16 v[42:45], v[176:179], v[200:203], v[42:45]
	v_mfma_f32_16x16x32_bf16 v[34:37], v[184:187], v[200:203], v[34:37]
	v_mfma_f32_16x16x32_bf16 v[26:29], v[176:179], v[208:211], v[26:29]
	v_mfma_f32_16x16x32_bf16 v[18:21], v[184:187], v[208:211], v[18:21]
	v_mfma_f32_16x16x32_bf16 v[10:13], v[176:179], v[216:219], v[10:13]
	v_mfma_f32_16x16x32_bf16 v[2:5], v[184:187], v[216:219], v[2:5]
	s_barrier
	s_setprio 0
	s_add_i32 s49, 0, 0x18000
	v_add_u32_e32 v159, s49, v152
	s_add_i32 s50, 0, 0x1c000
	ds_read_b128 v[148:151], v159
	ds_read_b128 v[160:163], v159 offset:1024
	ds_read_b128 v[164:167], v159 offset:2048
	ds_read_b128 v[168:171], v159 offset:3072
	v_add_u32_e32 v159, s50, v152
	ds_read_b128 v[172:175], v159
	ds_read_b128 v[176:179], v159 offset:1024
	ds_read_b128 v[180:183], v159 offset:2048
	ds_read_b128 v[184:187], v159 offset:3072
	s_add_u32 s24, s24, 0x80000
	s_addc_u32 s25, s25, 0
	s_mov_b32 m0, s33
	v_lshl_add_u64 v[230:231], s[24:25], 0, v[138:139]
	ds_read_b128 v[188:191], v156 offset:32768
	ds_read_b128 v[192:195], v156 offset:33792
	ds_read_b128 v[196:199], v156 offset:34816
	ds_read_b128 v[200:203], v156 offset:35840
	ds_read_b128 v[204:207], v156 offset:36864
	ds_read_b128 v[208:211], v156 offset:37888
	ds_read_b128 v[212:215], v156 offset:38912
	ds_read_b128 v[216:219], v156 offset:39936
	global_load_lds_dwordx4 v[230:231], off
	v_lshl_add_u64 v[230:231], s[24:25], 0, v[134:135]
	s_mov_b32 m0, s34
	s_nop 0
	global_load_lds_dwordx4 v[230:231], off
	s_waitcnt vmcnt(8)
	s_waitcnt lgkmcnt(0)
	s_setprio 1
	s_barrier
	v_mfma_f32_16x16x32_bf16 v[126:129], v[148:151], v[188:191], v[126:129]
	v_mfma_f32_16x16x32_bf16 v[118:121], v[164:167], v[188:191], v[118:121]
	v_mfma_f32_16x16x32_bf16 v[110:113], v[148:151], v[196:199], v[110:113]
	v_mfma_f32_16x16x32_bf16 v[102:105], v[164:167], v[196:199], v[102:105]
	v_mfma_f32_16x16x32_bf16 v[94:97], v[148:151], v[204:207], v[94:97]
	v_mfma_f32_16x16x32_bf16 v[86:89], v[164:167], v[204:207], v[86:89]
	v_mfma_f32_16x16x32_bf16 v[78:81], v[148:151], v[212:215], v[78:81]
	v_mfma_f32_16x16x32_bf16 v[70:73], v[164:167], v[212:215], v[70:73]
	v_mfma_f32_16x16x32_bf16 v[126:129], v[160:163], v[192:195], v[126:129]
	v_mfma_f32_16x16x32_bf16 v[118:121], v[168:171], v[192:195], v[118:121]
	v_mfma_f32_16x16x32_bf16 v[110:113], v[160:163], v[200:203], v[110:113]
	v_mfma_f32_16x16x32_bf16 v[102:105], v[168:171], v[200:203], v[102:105]
	v_mfma_f32_16x16x32_bf16 v[94:97], v[160:163], v[208:211], v[94:97]
	v_mfma_f32_16x16x32_bf16 v[86:89], v[168:171], v[208:211], v[86:89]
	v_mfma_f32_16x16x32_bf16 v[78:81], v[160:163], v[216:219], v[78:81]
	v_mfma_f32_16x16x32_bf16 v[70:73], v[168:171], v[216:219], v[70:73]
	s_setprio 0
	s_setprio 1
	v_mfma_f32_16x16x32_bf16 v[122:125], v[172:175], v[188:191], v[122:125]
	v_mfma_f32_16x16x32_bf16 v[114:117], v[180:183], v[188:191], v[114:117]
	v_mfma_f32_16x16x32_bf16 v[106:109], v[172:175], v[196:199], v[106:109]
	v_mfma_f32_16x16x32_bf16 v[98:101], v[180:183], v[196:199], v[98:101]
	v_mfma_f32_16x16x32_bf16 v[90:93], v[172:175], v[204:207], v[90:93]
	v_mfma_f32_16x16x32_bf16 v[82:85], v[180:183], v[204:207], v[82:85]
	v_mfma_f32_16x16x32_bf16 v[74:77], v[172:175], v[212:215], v[74:77]
	v_mfma_f32_16x16x32_bf16 v[66:69], v[180:183], v[212:215], v[66:69]
	v_mfma_f32_16x16x32_bf16 v[122:125], v[176:179], v[192:195], v[122:125]
	v_mfma_f32_16x16x32_bf16 v[114:117], v[184:187], v[192:195], v[114:117]
	v_mfma_f32_16x16x32_bf16 v[106:109], v[176:179], v[200:203], v[106:109]
	v_mfma_f32_16x16x32_bf16 v[98:101], v[184:187], v[200:203], v[98:101]
	v_mfma_f32_16x16x32_bf16 v[90:93], v[176:179], v[208:211], v[90:93]
	v_mfma_f32_16x16x32_bf16 v[82:85], v[184:187], v[208:211], v[82:85]
	v_mfma_f32_16x16x32_bf16 v[74:77], v[176:179], v[216:219], v[74:77]
	v_mfma_f32_16x16x32_bf16 v[66:69], v[184:187], v[216:219], v[66:69]
	s_barrier
; #define PG8_STAGE(bufoff, gbase, voff) do { _Pragma("unroll") for (int _i = 0; _i < 2; ++_i) \
;         __builtin_amdgcn_global_load_lds((const unsigned*)((const char*)(gbase) + (voff)[_i]), (PG8_LAS unsigned*)(lds + (bufoff) + ldsw + _i * 8192), 16, 0, 0); } while (0)
; #define PG8_WAIT_V(n) asm volatile("s_waitcnt vmcnt(" #n ")" ::: "memory")
; #define PG8_WAIT_L(n) asm volatile("s_waitcnt lgkmcnt(" #n ")" ::: "memory")
; #define PG8_BAR __builtin_amdgcn_s_barrier()
; #define PG8_SCHED __builtin_amdgcn_sched_barrier(0)
; template <class Epi, class Sched, bool ALIGN_EPI = true, bool SP2 = true>
; __device__ __forceinline__ void gemm_phase(PG8_LAS unsigned char* lds, const int K  , const Sched& S, const Epi& E) {
;     ...
;             PG8_LDA(At, 1, 1); PG8_STAGE(PG8_SB(1, 0), b3, voffB); PG8_STAGE(PG8_SB(1, 1), b3 + hstep, voffB); PG8_STAGE(PG8_SA(1, 0), a3, voffA);
;             PG8_WAIT_V(8); PG8_WAIT_L(0); PG8_BAR; PG8_MMA(1, 0, At, B0); PG8_MMA(1, 1, At, B1); PG8_BAR; PG8_SCHED;
;     ...
;         if constexpr (ALIGN_EPI) { if (wr == 0) PG8_BAR; }
	s_setprio 0
	s_add_i32 s24, s49, s29
	v_lshl_add_u64 v[220:221], v[220:221], 0, s[6:7]
	s_mov_b32 m0, s24
	ds_read_b128 v[188:191], v156 offset:49152
	ds_read_b128 v[192:195], v156 offset:50176
	ds_read_b128 v[196:199], v156 offset:51200
	ds_read_b128 v[200:203], v156 offset:52224
	ds_read_b128 v[204:207], v156 offset:53248
	ds_read_b128 v[208:211], v156 offset:54272
	ds_read_b128 v[212:215], v156 offset:55296
	ds_read_b128 v[216:219], v156 offset:56320
	global_load_lds_dwordx4 v[220:221], off
	s_add_i32 m0, s24, 0x2000
	s_add_u32 s22, s22, 0x80080
	v_lshl_add_u64 v[220:221], v[222:223], 0, s[6:7]
	s_addc_u32 s23, s23, 0
	s_add_i32 s24, s50, s29
	global_load_lds_dwordx4 v[220:221], off
	v_lshl_add_u64 v[220:221], s[22:23], 0, v[136:137]
	s_mov_b32 m0, s24
	s_nop 0
	global_load_lds_dwordx4 v[220:221], off
	v_lshl_add_u64 v[220:221], s[22:23], 0, v[132:133]
	s_add_i32 m0, s24, 0x2000
	s_nop 0
	global_load_lds_dwordx4 v[220:221], off
	v_lshl_add_u64 v[220:221], v[224:225], 0, s[6:7]
	s_mov_b32 m0, s36
	s_nop 0
	global_load_lds_dwordx4 v[220:221], off
	v_lshl_add_u64 v[220:221], v[226:227], 0, s[6:7]
	s_mov_b32 m0, s37
	s_nop 0
	global_load_lds_dwordx4 v[220:221], off
	s_waitcnt vmcnt(8)
	s_waitcnt lgkmcnt(0)
	s_setprio 1
	s_barrier
	v_mfma_f32_16x16x32_bf16 v[62:65], v[148:151], v[188:191], v[62:65]
	v_mfma_f32_16x16x32_bf16 v[54:57], v[164:167], v[188:191], v[54:57]
	v_mfma_f32_16x16x32_bf16 v[46:49], v[148:151], v[196:199], v[46:49]
	v_mfma_f32_16x16x32_bf16 v[38:41], v[164:167], v[196:199], v[38:41]
	v_mfma_f32_16x16x32_bf16 v[30:33], v[148:151], v[204:207], v[30:33]
	v_mfma_f32_16x16x32_bf16 v[22:25], v[164:167], v[204:207], v[22:25]
	v_mfma_f32_16x16x32_bf16 v[14:17], v[148:151], v[212:215], v[14:17]
	v_mfma_f32_16x16x32_bf16 v[6:9], v[164:167], v[212:215], v[6:9]
	v_mfma_f32_16x16x32_bf16 v[62:65], v[160:163], v[192:195], v[62:65]
	v_mfma_f32_16x16x32_bf16 v[54:57], v[168:171], v[192:195], v[54:57]
	v_mfma_f32_16x16x32_bf16 v[46:49], v[160:163], v[200:203], v[46:49]
	v_mfma_f32_16x16x32_bf16 v[38:41], v[168:171], v[200:203], v[38:41]
	v_mfma_f32_16x16x32_bf16 v[30:33], v[160:163], v[208:211], v[30:33]
	v_mfma_f32_16x16x32_bf16 v[22:25], v[168:171], v[208:211], v[22:25]
	v_mfma_f32_16x16x32_bf16 v[14:17], v[160:163], v[216:219], v[14:17]
	v_mfma_f32_16x16x32_bf16 v[6:9], v[168:171], v[216:219], v[6:9]
	s_setprio 0
	s_setprio 1
	v_mfma_f32_16x16x32_bf16 v[58:61], v[172:175], v[188:191], v[58:61]
	v_mfma_f32_16x16x32_bf16 v[50:53], v[180:183], v[188:191], v[50:53]
	v_mfma_f32_16x16x32_bf16 v[42:45], v[172:175], v[196:199], v[42:45]
	v_mfma_f32_16x16x32_bf16 v[34:37], v[180:183], v[196:199], v[34:37]
	v_mfma_f32_16x16x32_bf16 v[26:29], v[172:175], v[204:207], v[26:29]
	v_mfma_f32_16x16x32_bf16 v[18:21], v[180:183], v[204:207], v[18:21]
	v_mfma_f32_16x16x32_bf16 v[10:13], v[172:175], v[212:215], v[10:13]
	v_mfma_f32_16x16x32_bf16 v[2:5], v[180:183], v[212:215], v[2:5]
	v_mfma_f32_16x16x32_bf16 v[58:61], v[176:179], v[192:195], v[58:61]
	v_mfma_f32_16x16x32_bf16 v[50:53], v[184:187], v[192:195], v[50:53]
	v_mfma_f32_16x16x32_bf16 v[42:45], v[176:179], v[200:203], v[42:45]
	v_mfma_f32_16x16x32_bf16 v[34:37], v[184:187], v[200:203], v[34:37]
	v_mfma_f32_16x16x32_bf16 v[26:29], v[176:179], v[208:211], v[26:29]
	v_mfma_f32_16x16x32_bf16 v[18:21], v[184:187], v[208:211], v[18:21]
	v_mfma_f32_16x16x32_bf16 v[10:13], v[176:179], v[216:219], v[10:13]
	v_mfma_f32_16x16x32_bf16 v[2:5], v[184:187], v[216:219], v[2:5]
	s_barrier
	s_setprio 0
	s_add_i32 s48, s48, 2
	s_add_u32 s20, s20, 0x100
	s_addc_u32 s21, s21, 0
	s_add_u32 s46, s46, 0x100
	s_addc_u32 s47, s47, 0
	s_cmp_gt_u32 s48, 29
	s_cbranch_scc0 .LBB0_219
	s_and_b64 vcc, exec, s[8:9]
	s_cbranch_vccz .LBB0_222
	s_barrier

; #define PG8_STAGE(bufoff, gbase, voff) do { _Pragma("unroll") for (int _i = 0; _i < 2; ++_i) \
;         __builtin_amdgcn_global_load_lds((const unsigned*)((const char*)(gbase) + (voff)[_i]), (PG8_LAS unsigned*)(lds + (bufoff) + ldsw + _i * 8192), 16, 0, 0); } while (0)
; #define PG8_WAIT_V(n) asm volatile("s_waitcnt vmcnt(" #n ")" ::: "memory")
; #define PG8_WAIT_L(n) asm volatile("s_waitcnt lgkmcnt(" #n ")" ::: "memory")
; #define PG8_BAR __builtin_amdgcn_s_barrier()
; #define PG8_SCHED __builtin_amdgcn_sched_barrier(0)
;     __device__ __forceinline__ int nt(const pg8::Unit& u) const { return u.kind == 0 ? ntiles : q_nt(u.kind - 1); }
; template <class Epi, class Sched, bool ALIGN_EPI = true, bool SP2 = true>
; __device__ __forceinline__ void gemm_phase(PG8_LAS unsigned char* lds, const int K  , const Sched& S, const Epi& E) {
;     ...
;             const bool last = (t == nt - 2);
;             const char* a1 = cA + (size_t)(t + 1) * kstep;
;             const char* a2 = last ? nA : cA + (size_t)(t + 2) * kstep; const char* b2 = last ? nB : cB + (size_t)(t + 2) * kstep;
;             const char* a3 = a2 + kstep; const char* b3 = b2 + kstep;
;             if constexpr (SP2) {
;             PG8_LDB(B0, 0, 0); PG8_LDB(B1, 0, 1); PG8_SCHED; PG8_LDA(At, 0, 0); PG8_STAGE(PG8_SA(1, 1), a1 + hstep, voffA);
;             PG8_WAIT_V(8); PG8_WAIT_L(0); PG8_BAR; PG8_MMA(0, 0, At, B0); PG8_MMA(0, 1, At, B1); PG8_BAR; PG8_SCHED;
;             PG8_LDA(At, 0, 1); PG8_STAGE(PG8_SB(0, 0), b2, voffB); PG8_STAGE(PG8_SB(0, 1), b2 + hstep, voffB); PG8_STAGE(PG8_SA(0, 0), a2, voffA);
;             PG8_WAIT_V(8); PG8_WAIT_L(0); PG8_BAR; PG8_MMA(1, 0, At, B0); PG8_MMA(1, 1, At, B1); PG8_BAR; PG8_SCHED;
.LBB0_393:
	ds_read_b128 v[18:21], v190
	ds_read_b128 v[22:25], v190 offset:1024
	ds_read_b128 v[26:29], v190 offset:2048
	ds_read_b128 v[30:33], v190 offset:3072
	ds_read_b128 v[2:5], v191
	ds_read_b128 v[6:9], v191 offset:1024
	ds_read_b128 v[10:13], v191 offset:2048
	ds_read_b128 v[14:17], v191 offset:3072
	s_add_i32 s50, s22, 2
	s_add_u32 s20, s18, 0xfff50080
	s_addc_u32 s21, s19, -1
	s_cmp_eq_u32 s47, s22
	s_cselect_b32 s22, s14, s20
	s_cselect_b32 s23, s15, s21
	s_cselect_b32 s21, s17, s49
	s_cselect_b32 s20, s16, s48
	v_lshl_add_u64 v[218:219], s[18:19], 0, v[170:171]
	s_add_i32 m0, s26, 0xc000
	ds_read_b128 v[178:181], v192
	ds_read_b128 v[182:185], v192 offset:1024
	ds_read_b128 v[194:197], v192 offset:2048
	ds_read_b128 v[198:201], v192 offset:3072
	ds_read_b128 v[202:205], v192 offset:4096
	ds_read_b128 v[206:209], v192 offset:5120
	ds_read_b128 v[210:213], v192 offset:6144
	ds_read_b128 v[214:217], v192 offset:7168
	global_load_lds_dwordx4 v[218:219], off
	v_lshl_add_u64 v[218:219], s[18:19], 0, v[172:173]
	s_add_i32 m0, s26, 0xe000
	s_nop 0
	global_load_lds_dwordx4 v[218:219], off
	s_waitcnt vmcnt(8)
	s_waitcnt lgkmcnt(0)
	s_setprio 1
	s_barrier
	v_mfma_scale_f32_16x16x128_f8f6f4 v[158:161], v[18:25], v[178:185], v[158:161], v186, v186 op_sel_hi:[0,0,0]
	v_mfma_scale_f32_16x16x128_f8f6f4 v[154:157], v[26:33], v[178:185], v[154:157], v186, v186 op_sel_hi:[0,0,0]
	v_mfma_scale_f32_16x16x128_f8f6f4 v[150:153], v[18:25], v[194:201], v[150:153], v186, v186 op_sel_hi:[0,0,0]
	v_mfma_scale_f32_16x16x128_f8f6f4 v[142:145], v[26:33], v[194:201], v[142:145], v186, v186 op_sel_hi:[0,0,0]
	v_mfma_scale_f32_16x16x128_f8f6f4 v[134:137], v[18:25], v[202:209], v[134:137], v186, v186 op_sel_hi:[0,0,0]
	v_mfma_scale_f32_16x16x128_f8f6f4 v[126:129], v[26:33], v[202:209], v[126:129], v186, v186 op_sel_hi:[0,0,0]
	v_mfma_scale_f32_16x16x128_f8f6f4 v[118:121], v[18:25], v[210:217], v[118:121], v186, v186 op_sel_hi:[0,0,0]
	v_mfma_scale_f32_16x16x128_f8f6f4 v[110:113], v[26:33], v[210:217], v[110:113], v186, v186 op_sel_hi:[0,0,0]
	s_setprio 0
	s_setprio 1
	v_mfma_scale_f32_16x16x128_f8f6f4 v[146:149], v[2:9], v[178:185], v[146:149], v186, v186 op_sel_hi:[0,0,0]
	v_mfma_scale_f32_16x16x128_f8f6f4 v[138:141], v[10:17], v[178:185], v[138:141], v186, v186 op_sel_hi:[0,0,0]
	v_mfma_scale_f32_16x16x128_f8f6f4 v[130:133], v[2:9], v[194:201], v[130:133], v186, v186 op_sel_hi:[0,0,0]
	v_mfma_scale_f32_16x16x128_f8f6f4 v[122:125], v[10:17], v[194:201], v[122:125], v186, v186 op_sel_hi:[0,0,0]
	v_mfma_scale_f32_16x16x128_f8f6f4 v[114:117], v[2:9], v[202:209], v[114:117], v186, v186 op_sel_hi:[0,0,0]
	v_mfma_scale_f32_16x16x128_f8f6f4 v[106:109], v[10:17], v[202:209], v[106:109], v186, v186 op_sel_hi:[0,0,0]
	v_mfma_scale_f32_16x16x128_f8f6f4 v[102:105], v[2:9], v[210:217], v[102:105], v186, v186 op_sel_hi:[0,0,0]
	v_mfma_scale_f32_16x16x128_f8f6f4 v[98:101], v[10:17], v[210:217], v[98:101], v186, v186 op_sel_hi:[0,0,0]
	s_barrier
	s_setprio 0
	s_add_i32 s51, s37, s25
	v_lshl_add_u64 v[178:179], s[20:21], 0, v[164:165]
	s_mov_b32 m0, s51
	ds_read_b128 v[194:197], v192 offset:16384
	ds_read_b128 v[198:201], v192 offset:17408
	ds_read_b128 v[202:205], v192 offset:18432
	ds_read_b128 v[206:209], v192 offset:19456
	ds_read_b128 v[210:213], v192 offset:20480
	ds_read_b128 v[214:217], v192 offset:21504
	ds_read_b128 v[218:221], v192 offset:22528
	ds_read_b128 v[222:225], v192 offset:23552
	global_load_lds_dwordx4 v[178:179], off
	s_add_i32 m0, s51, 0x2000
	s_add_u32 s68, s20, 0xb0000
	v_lshl_add_u64 v[180:181], s[20:21], 0, v[168:169]
	s_addc_u32 s69, s21, 0
	s_add_i32 s51, s38, s25
	global_load_lds_dwordx4 v[180:181], off
	v_lshl_add_u64 v[182:183], s[68:69], 0, v[164:165]
	s_mov_b32 m0, s51
	v_lshl_add_u64 v[184:185], s[22:23], 0, v[166:167]
	global_load_lds_dwordx4 v[182:183], off
	v_lshl_add_u64 v[182:183], s[68:69], 0, v[168:169]
	s_add_i32 m0, s51, 0x2000
	s_nop 0
	global_load_lds_dwordx4 v[182:183], off
	v_lshl_add_u64 v[182:183], s[22:23], 0, v[162:163]
	s_mov_b32 m0, s26
	s_nop 0
	global_load_lds_dwordx4 v[182:183], off
	s_mov_b32 m0, s27
	s_nop 0
	global_load_lds_dwordx4 v[184:185], off
	s_waitcnt vmcnt(8)
	s_waitcnt lgkmcnt(0)
	s_setprio 1
	s_barrier
	v_mfma_scale_f32_16x16x128_f8f6f4 v[94:97], v[18:25], v[194:201], v[94:97], v186, v186 op_sel_hi:[0,0,0]
	v_mfma_scale_f32_16x16x128_f8f6f4 v[90:93], v[26:33], v[194:201], v[90:93], v186, v186 op_sel_hi:[0,0,0]
	v_mfma_scale_f32_16x16x128_f8f6f4 v[86:89], v[18:25], v[202:209], v[86:89], v186, v186 op_sel_hi:[0,0,0]
	v_mfma_scale_f32_16x16x128_f8f6f4 v[78:81], v[26:33], v[202:209], v[78:81], v186, v186 op_sel_hi:[0,0,0]
	v_mfma_scale_f32_16x16x128_f8f6f4 v[70:73], v[18:25], v[210:217], v[70:73], v186, v186 op_sel_hi:[0,0,0]
	v_mfma_scale_f32_16x16x128_f8f6f4 v[62:65], v[26:33], v[210:217], v[62:65], v186, v186 op_sel_hi:[0,0,0]
	v_mfma_scale_f32_16x16x128_f8f6f4 v[54:57], v[18:25], v[218:225], v[54:57], v186, v186 op_sel_hi:[0,0,0]
	v_mfma_scale_f32_16x16x128_f8f6f4 v[46:49], v[26:33], v[218:225], v[46:49], v186, v186 op_sel_hi:[0,0,0]
	s_setprio 0
	s_setprio 1
	v_mfma_scale_f32_16x16x128_f8f6f4 v[82:85], v[2:9], v[194:201], v[82:85], v186, v186 op_sel_hi:[0,0,0]
	v_mfma_scale_f32_16x16x128_f8f6f4 v[74:77], v[10:17], v[194:201], v[74:77], v186, v186 op_sel_hi:[0,0,0]
	v_mfma_scale_f32_16x16x128_f8f6f4 v[66:69], v[2:9], v[202:209], v[66:69], v186, v186 op_sel_hi:[0,0,0]
	v_mfma_scale_f32_16x16x128_f8f6f4 v[58:61], v[10:17], v[202:209], v[58:61], v186, v186 op_sel_hi:[0,0,0]
	v_mfma_scale_f32_16x16x128_f8f6f4 v[50:53], v[2:9], v[210:217], v[50:53], v186, v186 op_sel_hi:[0,0,0]
	v_mfma_scale_f32_16x16x128_f8f6f4 v[42:45], v[10:17], v[210:217], v[42:45], v186, v186 op_sel_hi:[0,0,0]
	v_mfma_scale_f32_16x16x128_f8f6f4 v[38:41], v[2:9], v[218:225], v[38:41], v186, v186 op_sel_hi:[0,0,0]
	v_mfma_scale_f32_16x16x128_f8f6f4 v[34:37], v[10:17], v[218:225], v[34:37], v186, v186 op_sel_hi:[0,0,0]
	s_barrier
; #define PG8_STAGE(bufoff, gbase, voff) do { _Pragma("unroll") for (int _i = 0; _i < 2; ++_i) \
;         __builtin_amdgcn_global_load_lds((const unsigned*)((const char*)(gbase) + (voff)[_i]), (PG8_LAS unsigned*)(lds + (bufoff) + ldsw + _i * 8192), 16, 0, 0); } while (0)
; #define PG8_WAIT_V(n) asm volatile("s_waitcnt vmcnt(" #n ")" ::: "memory")
; #define PG8_WAIT_L(n) asm volatile("s_waitcnt lgkmcnt(" #n ")" ::: "memory")
; #define PG8_BAR __builtin_amdgcn_s_barrier()
; #define PG8_SCHED __builtin_amdgcn_sched_barrier(0)
; template <class Epi, class Sched, bool ALIGN_EPI = true, bool SP2 = true>
; __device__ __forceinline__ void gemm_phase(PG8_LAS unsigned char* lds, const int K  , const Sched& S, const Epi& E) {
;     ...
;             PG8_LDB(B0, 1, 0); PG8_LDB(B1, 1, 1); PG8_SCHED; PG8_LDA(At, 1, 0); PG8_STAGE(PG8_SA(0, 1), a2 + hstep, voffA);
;             PG8_WAIT_V(8); PG8_WAIT_L(0); PG8_BAR; PG8_MMA(0, 0, At, B0); PG8_MMA(0, 1, At, B1); PG8_BAR; PG8_SCHED;
;             PG8_LDA(At, 1, 1); PG8_STAGE(PG8_SB(1, 0), b3, voffB); PG8_STAGE(PG8_SB(1, 1), b3 + hstep, voffB); PG8_STAGE(PG8_SA(1, 0), a3, voffA);
;             PG8_WAIT_V(8); PG8_WAIT_L(0); PG8_BAR; PG8_MMA(1, 0, At, B0); PG8_MMA(1, 1, At, B1); PG8_BAR; PG8_SCHED;
;     ...
;         if constexpr (Epi::FP8) asm volatile("s_nop 15\n\ts_nop 15\n\ts_nop 15\n\ts_nop 15\n\ts_nop 15" ::: "memory");
;         if constexpr (ALIGN_EPI) { if (wr == 0) PG8_BAR; }
	s_setprio 0
	s_add_i32 s51, 0, 0x18000
	s_add_i32 s68, 0, 0x1c000
	v_add_u32_e32 v14, s51, v188
	v_add_u32_e32 v30, s68, v188
	ds_read_b128 v[2:5], v14
	ds_read_b128 v[6:9], v14 offset:1024
	ds_read_b128 v[10:13], v14 offset:2048
	ds_read_b128 v[14:17], v14 offset:3072
	ds_read_b128 v[18:21], v30
	ds_read_b128 v[22:25], v30 offset:1024
	ds_read_b128 v[26:29], v30 offset:2048
	ds_read_b128 v[30:33], v30 offset:3072
	s_add_u32 s22, s22, 0xb0000
	s_addc_u32 s23, s23, 0
	s_mov_b32 m0, s28
	v_lshl_add_u64 v[226:227], s[22:23], 0, v[162:163]
	ds_read_b128 v[194:197], v192 offset:32768
	ds_read_b128 v[198:201], v192 offset:33792
	ds_read_b128 v[202:205], v192 offset:34816
	ds_read_b128 v[206:209], v192 offset:35840
	ds_read_b128 v[210:213], v192 offset:36864
	ds_read_b128 v[214:217], v192 offset:37888
	ds_read_b128 v[218:221], v192 offset:38912
	ds_read_b128 v[222:225], v192 offset:39936
	global_load_lds_dwordx4 v[226:227], off
	v_lshl_add_u64 v[226:227], s[22:23], 0, v[166:167]
	s_mov_b32 m0, s29
	s_nop 0
	global_load_lds_dwordx4 v[226:227], off
	s_waitcnt vmcnt(8)
	s_waitcnt lgkmcnt(0)
	s_setprio 1
	s_barrier
	v_mfma_scale_f32_16x16x128_f8f6f4 v[158:161], v[2:9], v[194:201], v[158:161], v186, v186 op_sel_hi:[0,0,0]
	v_mfma_scale_f32_16x16x128_f8f6f4 v[154:157], v[10:17], v[194:201], v[154:157], v186, v186 op_sel_hi:[0,0,0]
	v_mfma_scale_f32_16x16x128_f8f6f4 v[150:153], v[2:9], v[202:209], v[150:153], v186, v186 op_sel_hi:[0,0,0]
	v_mfma_scale_f32_16x16x128_f8f6f4 v[142:145], v[10:17], v[202:209], v[142:145], v186, v186 op_sel_hi:[0,0,0]
	v_mfma_scale_f32_16x16x128_f8f6f4 v[134:137], v[2:9], v[210:217], v[134:137], v186, v186 op_sel_hi:[0,0,0]
	v_mfma_scale_f32_16x16x128_f8f6f4 v[126:129], v[10:17], v[210:217], v[126:129], v186, v186 op_sel_hi:[0,0,0]
	v_mfma_scale_f32_16x16x128_f8f6f4 v[118:121], v[2:9], v[218:225], v[118:121], v186, v186 op_sel_hi:[0,0,0]
	v_mfma_scale_f32_16x16x128_f8f6f4 v[110:113], v[10:17], v[218:225], v[110:113], v186, v186 op_sel_hi:[0,0,0]
	s_setprio 0
	s_setprio 1
	v_mfma_scale_f32_16x16x128_f8f6f4 v[146:149], v[18:25], v[194:201], v[146:149], v186, v186 op_sel_hi:[0,0,0]
	v_mfma_scale_f32_16x16x128_f8f6f4 v[138:141], v[26:33], v[194:201], v[138:141], v186, v186 op_sel_hi:[0,0,0]
	v_mfma_scale_f32_16x16x128_f8f6f4 v[130:133], v[18:25], v[202:209], v[130:133], v186, v186 op_sel_hi:[0,0,0]
	v_mfma_scale_f32_16x16x128_f8f6f4 v[122:125], v[26:33], v[202:209], v[122:125], v186, v186 op_sel_hi:[0,0,0]
	v_mfma_scale_f32_16x16x128_f8f6f4 v[114:117], v[18:25], v[210:217], v[114:117], v186, v186 op_sel_hi:[0,0,0]
	v_mfma_scale_f32_16x16x128_f8f6f4 v[106:109], v[26:33], v[210:217], v[106:109], v186, v186 op_sel_hi:[0,0,0]
	v_mfma_scale_f32_16x16x128_f8f6f4 v[102:105], v[18:25], v[218:225], v[102:105], v186, v186 op_sel_hi:[0,0,0]
	v_mfma_scale_f32_16x16x128_f8f6f4 v[98:101], v[26:33], v[218:225], v[98:101], v186, v186 op_sel_hi:[0,0,0]
	s_barrier
	s_setprio 0
	s_add_i32 s22, s51, s25
	v_lshl_add_u64 v[178:179], v[178:179], 0, s[8:9]
	s_mov_b32 m0, s22
	ds_read_b128 v[194:197], v192 offset:49152
	ds_read_b128 v[198:201], v192 offset:50176
	ds_read_b128 v[202:205], v192 offset:51200
	ds_read_b128 v[206:209], v192 offset:52224
	ds_read_b128 v[210:213], v192 offset:53248
	ds_read_b128 v[214:217], v192 offset:54272
	ds_read_b128 v[218:221], v192 offset:55296
	ds_read_b128 v[222:225], v192 offset:56320
	global_load_lds_dwordx4 v[178:179], off
	s_add_i32 m0, s22, 0x2000
	s_add_u32 s20, s20, 0xb0080
	v_lshl_add_u64 v[178:179], v[180:181], 0, s[8:9]
	s_addc_u32 s21, s21, 0
	s_add_i32 s22, s68, s25
	global_load_lds_dwordx4 v[178:179], off
	v_lshl_add_u64 v[178:179], s[20:21], 0, v[164:165]
	s_mov_b32 m0, s22
	s_nop 0
	global_load_lds_dwordx4 v[178:179], off
	v_lshl_add_u64 v[178:179], s[20:21], 0, v[168:169]
	s_add_i32 m0, s22, 0x2000
	s_nop 0
	global_load_lds_dwordx4 v[178:179], off
	v_lshl_add_u64 v[178:179], v[182:183], 0, s[8:9]
	s_mov_b32 m0, s33
	s_nop 0
	global_load_lds_dwordx4 v[178:179], off
	v_lshl_add_u64 v[178:179], v[184:185], 0, s[8:9]
	s_mov_b32 m0, s34
	s_nop 0
	global_load_lds_dwordx4 v[178:179], off
	s_waitcnt vmcnt(8)
	s_waitcnt lgkmcnt(0)
	s_setprio 1
	s_barrier
	v_mfma_scale_f32_16x16x128_f8f6f4 v[94:97], v[2:9], v[194:201], v[94:97], v186, v186 op_sel_hi:[0,0,0]
	v_mfma_scale_f32_16x16x128_f8f6f4 v[90:93], v[10:17], v[194:201], v[90:93], v186, v186 op_sel_hi:[0,0,0]
	v_mfma_scale_f32_16x16x128_f8f6f4 v[86:89], v[2:9], v[202:209], v[86:89], v186, v186 op_sel_hi:[0,0,0]
	v_mfma_scale_f32_16x16x128_f8f6f4 v[78:81], v[10:17], v[202:209], v[78:81], v186, v186 op_sel_hi:[0,0,0]
	v_mfma_scale_f32_16x16x128_f8f6f4 v[70:73], v[2:9], v[210:217], v[70:73], v186, v186 op_sel_hi:[0,0,0]
	v_mfma_scale_f32_16x16x128_f8f6f4 v[62:65], v[10:17], v[210:217], v[62:65], v186, v186 op_sel_hi:[0,0,0]
	v_mfma_scale_f32_16x16x128_f8f6f4 v[54:57], v[2:9], v[218:225], v[54:57], v186, v186 op_sel_hi:[0,0,0]
	v_mfma_scale_f32_16x16x128_f8f6f4 v[46:49], v[10:17], v[218:225], v[46:49], v186, v186 op_sel_hi:[0,0,0]
	s_setprio 0
	s_setprio 1
	v_mfma_scale_f32_16x16x128_f8f6f4 v[82:85], v[18:25], v[194:201], v[82:85], v186, v186 op_sel_hi:[0,0,0]
	v_mfma_scale_f32_16x16x128_f8f6f4 v[74:77], v[26:33], v[194:201], v[74:77], v186, v186 op_sel_hi:[0,0,0]
	v_mfma_scale_f32_16x16x128_f8f6f4 v[66:69], v[18:25], v[202:209], v[66:69], v186, v186 op_sel_hi:[0,0,0]
	v_mfma_scale_f32_16x16x128_f8f6f4 v[58:61], v[26:33], v[202:209], v[58:61], v186, v186 op_sel_hi:[0,0,0]
	v_mfma_scale_f32_16x16x128_f8f6f4 v[50:53], v[18:25], v[210:217], v[50:53], v186, v186 op_sel_hi:[0,0,0]
	v_mfma_scale_f32_16x16x128_f8f6f4 v[42:45], v[26:33], v[210:217], v[42:45], v186, v186 op_sel_hi:[0,0,0]
	v_mfma_scale_f32_16x16x128_f8f6f4 v[38:41], v[18:25], v[218:225], v[38:41], v186, v186 op_sel_hi:[0,0,0]
	v_mfma_scale_f32_16x16x128_f8f6f4 v[34:37], v[26:33], v[218:225], v[34:37], v186, v186 op_sel_hi:[0,0,0]
	s_barrier
	s_setprio 0
	s_add_u32 s18, s18, 0x100
	s_addc_u32 s19, s19, 0
	s_add_u32 s48, s48, 0x100
	s_addc_u32 s49, s49, 0
	s_cmp_ge_u32 s50, s4
	s_mov_b32 s22, s50
	s_cbranch_scc0 .LBB0_393
	s_nop 15
	s_nop 15
	s_nop 15
	s_nop 15
	s_nop 15
	s_and_b64 vcc, exec, s[10:11]
	s_cbranch_vccz .LBB0_396
	s_barrier

; #define PG8_STAGE(bufoff, gbase, voff) do { _Pragma("unroll") for (int _i = 0; _i < 2; ++_i) \
;         __builtin_amdgcn_global_load_lds((const unsigned*)((const char*)(gbase) + (voff)[_i]), (PG8_LAS unsigned*)(lds + (bufoff) + ldsw + _i * 8192), 16, 0, 0); } while (0)
; #define PG8_WAIT_V(n) asm volatile("s_waitcnt vmcnt(" #n ")" ::: "memory")
; #define PG8_WAIT_L(n) asm volatile("s_waitcnt lgkmcnt(" #n ")" ::: "memory")
; #define PG8_BAR __builtin_amdgcn_s_barrier()
; #define PG8_SCHED __builtin_amdgcn_sched_barrier(0)
;     __device__ __forceinline__ int nt(const pg8::Unit& u) const { return u.kind == 0 ? ntiles : q_nt(u.kind - 1); }
; template <class Epi, class Sched, bool ALIGN_EPI = true, bool SP2 = true>
; __device__ __forceinline__ void gemm_phase(PG8_LAS unsigned char* lds, const int K  , const Sched& S, const Epi& E) {
;     ...
;             const bool last = (t == nt - 2);
;             const char* a1 = cA + (size_t)(t + 1) * kstep;
;             const char* a2 = last ? nA : cA + (size_t)(t + 2) * kstep; const char* b2 = last ? nB : cB + (size_t)(t + 2) * kstep;
;             const char* a3 = a2 + kstep; const char* b3 = b2 + kstep;
;             if constexpr (SP2) {
;             PG8_LDB(B0, 0, 0); PG8_LDB(B1, 0, 1); PG8_SCHED; PG8_LDA(At, 0, 0); PG8_STAGE(PG8_SA(1, 1), a1 + hstep, voffA);
;             PG8_WAIT_V(8); PG8_WAIT_L(0); PG8_BAR; PG8_MMA(0, 0, At, B0); PG8_MMA(0, 1, At, B1); PG8_BAR; PG8_SCHED;
;             PG8_LDA(At, 0, 1); PG8_STAGE(PG8_SB(0, 0), b2, voffB); PG8_STAGE(PG8_SB(0, 1), b2 + hstep, voffB); PG8_STAGE(PG8_SA(0, 0), a2, voffA);
;             PG8_WAIT_V(8); PG8_WAIT_L(0); PG8_BAR; PG8_MMA(1, 0, At, B0); PG8_MMA(1, 1, At, B1); PG8_BAR; PG8_SCHED;
.LBB0_537:
	ds_read_b128 v[150:153], v156
	ds_read_b128 v[160:163], v156 offset:1024
	ds_read_b128 v[164:167], v156 offset:2048
	ds_read_b128 v[168:171], v156 offset:3072
	ds_read_b128 v[172:175], v157
	ds_read_b128 v[176:179], v157 offset:1024
	ds_read_b128 v[180:183], v157 offset:2048
	ds_read_b128 v[184:187], v157 offset:3072
	s_add_u32 s22, s20, 0xfff80080
	s_addc_u32 s23, s21, -1
	s_cmp_eq_u32 s47, 28
	s_cselect_b32 s25, s13, s23
	s_cselect_b32 s24, s19, s22
	s_cselect_b32 s23, s11, s46
	s_cselect_b32 s22, s44, s45
	v_lshl_add_u64 v[220:221], s[20:21], 0, v[142:143]
	s_add_i32 m0, s31, 0xc000
	ds_read_b128 v[188:191], v158
	ds_read_b128 v[192:195], v158 offset:1024
	ds_read_b128 v[196:199], v158 offset:2048
	ds_read_b128 v[200:203], v158 offset:3072
	ds_read_b128 v[204:207], v158 offset:4096
	ds_read_b128 v[208:211], v158 offset:5120
	ds_read_b128 v[212:215], v158 offset:6144
	ds_read_b128 v[216:219], v158 offset:7168
	global_load_lds_dwordx4 v[220:221], off
	v_lshl_add_u64 v[220:221], s[20:21], 0, v[144:145]
	s_add_i32 m0, s31, 0xe000
	s_nop 0
	global_load_lds_dwordx4 v[220:221], off
	s_waitcnt vmcnt(8)
	s_waitcnt lgkmcnt(0)
	s_setprio 1
	s_barrier
	v_mfma_f32_16x16x32_bf16 v[126:129], v[150:153], v[188:191], v[126:129]
	v_mfma_f32_16x16x32_bf16 v[122:125], v[164:167], v[188:191], v[122:125]
	v_mfma_f32_16x16x32_bf16 v[118:121], v[150:153], v[196:199], v[118:121]
	v_mfma_f32_16x16x32_bf16 v[110:113], v[164:167], v[196:199], v[110:113]
	v_mfma_f32_16x16x32_bf16 v[102:105], v[150:153], v[204:207], v[102:105]
	v_mfma_f32_16x16x32_bf16 v[94:97], v[164:167], v[204:207], v[94:97]
	v_mfma_f32_16x16x32_bf16 v[86:89], v[150:153], v[212:215], v[86:89]
	v_mfma_f32_16x16x32_bf16 v[78:81], v[164:167], v[212:215], v[78:81]
	v_mfma_f32_16x16x32_bf16 v[126:129], v[160:163], v[192:195], v[126:129]
	v_mfma_f32_16x16x32_bf16 v[122:125], v[168:171], v[192:195], v[122:125]
	v_mfma_f32_16x16x32_bf16 v[118:121], v[160:163], v[200:203], v[118:121]
	v_mfma_f32_16x16x32_bf16 v[110:113], v[168:171], v[200:203], v[110:113]
	v_mfma_f32_16x16x32_bf16 v[102:105], v[160:163], v[208:211], v[102:105]
	v_mfma_f32_16x16x32_bf16 v[94:97], v[168:171], v[208:211], v[94:97]
	v_mfma_f32_16x16x32_bf16 v[86:89], v[160:163], v[216:219], v[86:89]
	v_mfma_f32_16x16x32_bf16 v[78:81], v[168:171], v[216:219], v[78:81]
	s_setprio 0
	s_setprio 1
	v_mfma_f32_16x16x32_bf16 v[114:117], v[172:175], v[188:191], v[114:117]
	v_mfma_f32_16x16x32_bf16 v[106:109], v[180:183], v[188:191], v[106:109]
	v_mfma_f32_16x16x32_bf16 v[98:101], v[172:175], v[196:199], v[98:101]
	v_mfma_f32_16x16x32_bf16 v[90:93], v[180:183], v[196:199], v[90:93]
	v_mfma_f32_16x16x32_bf16 v[82:85], v[172:175], v[204:207], v[82:85]
	v_mfma_f32_16x16x32_bf16 v[74:77], v[180:183], v[204:207], v[74:77]
	v_mfma_f32_16x16x32_bf16 v[70:73], v[172:175], v[212:215], v[70:73]
	v_mfma_f32_16x16x32_bf16 v[66:69], v[180:183], v[212:215], v[66:69]
	v_mfma_f32_16x16x32_bf16 v[114:117], v[176:179], v[192:195], v[114:117]
	v_mfma_f32_16x16x32_bf16 v[106:109], v[184:187], v[192:195], v[106:109]
	v_mfma_f32_16x16x32_bf16 v[98:101], v[176:179], v[200:203], v[98:101]
	v_mfma_f32_16x16x32_bf16 v[90:93], v[184:187], v[200:203], v[90:93]
	v_mfma_f32_16x16x32_bf16 v[82:85], v[176:179], v[208:211], v[82:85]
	v_mfma_f32_16x16x32_bf16 v[74:77], v[184:187], v[208:211], v[74:77]
	v_mfma_f32_16x16x32_bf16 v[70:73], v[176:179], v[216:219], v[70:73]
	v_mfma_f32_16x16x32_bf16 v[66:69], v[184:187], v[216:219], v[66:69]
	s_barrier
	s_setprio 0
	s_add_i32 s48, s40, s29
	v_lshl_add_u64 v[220:221], s[22:23], 0, v[136:137]
	s_mov_b32 m0, s48
	ds_read_b128 v[188:191], v158 offset:16384
	ds_read_b128 v[192:195], v158 offset:17408
	ds_read_b128 v[196:199], v158 offset:18432
	ds_read_b128 v[200:203], v158 offset:19456
	ds_read_b128 v[204:207], v158 offset:20480
	ds_read_b128 v[208:211], v158 offset:21504
	ds_read_b128 v[212:215], v158 offset:22528
	ds_read_b128 v[216:219], v158 offset:23552
	global_load_lds_dwordx4 v[220:221], off
	s_add_i32 m0, s48, 0x2000
	s_add_u32 s48, s22, 0x80000
	v_lshl_add_u64 v[222:223], s[22:23], 0, v[132:133]
	s_addc_u32 s49, s23, 0
	s_add_i32 s50, s41, s29
	global_load_lds_dwordx4 v[222:223], off
	v_lshl_add_u64 v[224:225], s[48:49], 0, v[136:137]
	s_mov_b32 m0, s50
	v_lshl_add_u64 v[226:227], s[24:25], 0, v[134:135]
	global_load_lds_dwordx4 v[224:225], off
	v_lshl_add_u64 v[224:225], s[48:49], 0, v[132:133]
	s_add_i32 m0, s50, 0x2000
	s_nop 0
	global_load_lds_dwordx4 v[224:225], off
	v_lshl_add_u64 v[224:225], s[24:25], 0, v[138:139]
	s_mov_b32 m0, s31
	s_nop 0
	global_load_lds_dwordx4 v[224:225], off
	s_mov_b32 m0, s33
	s_nop 0
	global_load_lds_dwordx4 v[226:227], off
	s_waitcnt vmcnt(8)
	s_waitcnt lgkmcnt(0)
	s_setprio 1
	s_barrier
; #define PG8_STAGE(bufoff, gbase, voff) do { _Pragma("unroll") for (int _i = 0; _i < 2; ++_i) \
;         __builtin_amdgcn_global_load_lds((const unsigned*)((const char*)(gbase) + (voff)[_i]), (PG8_LAS unsigned*)(lds + (bufoff) + ldsw + _i * 8192), 16, 0, 0); } while (0)
; #define PG8_WAIT_V(n) asm volatile("s_waitcnt vmcnt(" #n ")" ::: "memory")
; #define PG8_WAIT_L(n) asm volatile("s_waitcnt lgkmcnt(" #n ")" ::: "memory")
; #define PG8_BAR __builtin_amdgcn_s_barrier()
; #define PG8_SCHED __builtin_amdgcn_sched_barrier(0)
; template <class Epi, class Sched, bool ALIGN_EPI = true, bool SP2 = true>
; __device__ __forceinline__ void gemm_phase(PG8_LAS unsigned char* lds, const int K  , const Sched& S, const Epi& E) {
;     ...
;             PG8_WAIT_V(8); PG8_WAIT_L(0); PG8_BAR; PG8_MMA(1, 0, At, B0); PG8_MMA(1, 1, At, B1); PG8_BAR; PG8_SCHED;
;             PG8_LDB(B0, 1, 0); PG8_LDB(B1, 1, 1); PG8_SCHED; PG8_LDA(At, 1, 0); PG8_STAGE(PG8_SA(0, 1), a2 + hstep, voffA);
;             PG8_WAIT_V(8); PG8_WAIT_L(0); PG8_BAR; PG8_MMA(0, 0, At, B0); PG8_MMA(0, 1, At, B1); PG8_BAR; PG8_SCHED;
	v_mfma_f32_16x16x32_bf16 v[62:65], v[150:153], v[188:191], v[62:65]
	v_mfma_f32_16x16x32_bf16 v[58:61], v[164:167], v[188:191], v[58:61]
	v_mfma_f32_16x16x32_bf16 v[54:57], v[150:153], v[196:199], v[54:57]
	v_mfma_f32_16x16x32_bf16 v[46:49], v[164:167], v[196:199], v[46:49]
	v_mfma_f32_16x16x32_bf16 v[38:41], v[150:153], v[204:207], v[38:41]
	v_mfma_f32_16x16x32_bf16 v[30:33], v[164:167], v[204:207], v[30:33]
	v_mfma_f32_16x16x32_bf16 v[22:25], v[150:153], v[212:215], v[22:25]
	v_mfma_f32_16x16x32_bf16 v[14:17], v[164:167], v[212:215], v[14:17]
	v_mfma_f32_16x16x32_bf16 v[62:65], v[160:163], v[192:195], v[62:65]
	v_mfma_f32_16x16x32_bf16 v[58:61], v[168:171], v[192:195], v[58:61]
	v_mfma_f32_16x16x32_bf16 v[54:57], v[160:163], v[200:203], v[54:57]
	v_mfma_f32_16x16x32_bf16 v[46:49], v[168:171], v[200:203], v[46:49]
	v_mfma_f32_16x16x32_bf16 v[38:41], v[160:163], v[208:211], v[38:41]
	v_mfma_f32_16x16x32_bf16 v[30:33], v[168:171], v[208:211], v[30:33]
	v_mfma_f32_16x16x32_bf16 v[22:25], v[160:163], v[216:219], v[22:25]
	v_mfma_f32_16x16x32_bf16 v[14:17], v[168:171], v[216:219], v[14:17]
	s_setprio 0
	s_setprio 1
	v_mfma_f32_16x16x32_bf16 v[50:53], v[172:175], v[188:191], v[50:53]
	v_mfma_f32_16x16x32_bf16 v[42:45], v[180:183], v[188:191], v[42:45]
	v_mfma_f32_16x16x32_bf16 v[34:37], v[172:175], v[196:199], v[34:37]
	v_mfma_f32_16x16x32_bf16 v[26:29], v[180:183], v[196:199], v[26:29]
	v_mfma_f32_16x16x32_bf16 v[18:21], v[172:175], v[204:207], v[18:21]
	v_mfma_f32_16x16x32_bf16 v[10:13], v[180:183], v[204:207], v[10:13]
	v_mfma_f32_16x16x32_bf16 v[6:9], v[172:175], v[212:215], v[6:9]
	v_mfma_f32_16x16x32_bf16 v[2:5], v[180:183], v[212:215], v[2:5]
	v_mfma_f32_16x16x32_bf16 v[50:53], v[176:179], v[192:195], v[50:53]
	v_mfma_f32_16x16x32_bf16 v[42:45], v[184:187], v[192:195], v[42:45]
	v_mfma_f32_16x16x32_bf16 v[34:37], v[176:179], v[200:203], v[34:37]
	v_mfma_f32_16x16x32_bf16 v[26:29], v[184:187], v[200:203], v[26:29]
	v_mfma_f32_16x16x32_bf16 v[18:21], v[176:179], v[208:211], v[18:21]
	v_mfma_f32_16x16x32_bf16 v[10:13], v[184:187], v[208:211], v[10:13]
	v_mfma_f32_16x16x32_bf16 v[6:9], v[176:179], v[216:219], v[6:9]
	v_mfma_f32_16x16x32_bf16 v[2:5], v[184:187], v[216:219], v[2:5]
	s_barrier
	s_setprio 0
	s_add_i32 s48, 0, 0x18000
	v_add_u32_e32 v140, s48, v154
	s_add_i32 s49, 0, 0x1c000
	ds_read_b128 v[150:153], v140
	ds_read_b128 v[160:163], v140 offset:1024
	ds_read_b128 v[164:167], v140 offset:2048
	ds_read_b128 v[168:171], v140 offset:3072
	v_add_u32_e32 v140, s49, v154
	ds_read_b128 v[172:175], v140
	ds_read_b128 v[176:179], v140 offset:1024
	ds_read_b128 v[180:183], v140 offset:2048
	ds_read_b128 v[184:187], v140 offset:3072
	s_add_u32 s24, s24, 0x80000
	s_addc_u32 s25, s25, 0
	s_mov_b32 m0, s34
	v_lshl_add_u64 v[230:231], s[24:25], 0, v[138:139]
	ds_read_b128 v[188:191], v158 offset:32768
	ds_read_b128 v[192:195], v158 offset:33792
	ds_read_b128 v[196:199], v158 offset:34816
	ds_read_b128 v[200:203], v158 offset:35840
	ds_read_b128 v[204:207], v158 offset:36864
	ds_read_b128 v[208:211], v158 offset:37888
	ds_read_b128 v[212:215], v158 offset:38912
	ds_read_b128 v[216:219], v158 offset:39936
	global_load_lds_dwordx4 v[230:231], off
	v_lshl_add_u64 v[230:231], s[24:25], 0, v[134:135]
	s_mov_b32 m0, s35
	s_nop 0
	global_load_lds_dwordx4 v[230:231], off
	s_waitcnt vmcnt(8)
	s_waitcnt lgkmcnt(0)
	s_setprio 1
	s_barrier
	v_mfma_f32_16x16x32_bf16 v[126:129], v[150:153], v[188:191], v[126:129]
	v_mfma_f32_16x16x32_bf16 v[122:125], v[164:167], v[188:191], v[122:125]
	v_mfma_f32_16x16x32_bf16 v[118:121], v[150:153], v[196:199], v[118:121]
	v_mfma_f32_16x16x32_bf16 v[110:113], v[164:167], v[196:199], v[110:113]
	v_mfma_f32_16x16x32_bf16 v[102:105], v[150:153], v[204:207], v[102:105]
	v_mfma_f32_16x16x32_bf16 v[94:97], v[164:167], v[204:207], v[94:97]
	v_mfma_f32_16x16x32_bf16 v[86:89], v[150:153], v[212:215], v[86:89]
	v_mfma_f32_16x16x32_bf16 v[78:81], v[164:167], v[212:215], v[78:81]
	v_mfma_f32_16x16x32_bf16 v[126:129], v[160:163], v[192:195], v[126:129]
	v_mfma_f32_16x16x32_bf16 v[122:125], v[168:171], v[192:195], v[122:125]
	v_mfma_f32_16x16x32_bf16 v[118:121], v[160:163], v[200:203], v[118:121]
	v_mfma_f32_16x16x32_bf16 v[110:113], v[168:171], v[200:203], v[110:113]
	v_mfma_f32_16x16x32_bf16 v[102:105], v[160:163], v[208:211], v[102:105]
	v_mfma_f32_16x16x32_bf16 v[94:97], v[168:171], v[208:211], v[94:97]
	v_mfma_f32_16x16x32_bf16 v[86:89], v[160:163], v[216:219], v[86:89]
	v_mfma_f32_16x16x32_bf16 v[78:81], v[168:171], v[216:219], v[78:81]
	s_setprio 0
	s_setprio 1
	v_mfma_f32_16x16x32_bf16 v[114:117], v[172:175], v[188:191], v[114:117]
	v_mfma_f32_16x16x32_bf16 v[106:109], v[180:183], v[188:191], v[106:109]
	v_mfma_f32_16x16x32_bf16 v[98:101], v[172:175], v[196:199], v[98:101]
	v_mfma_f32_16x16x32_bf16 v[90:93], v[180:183], v[196:199], v[90:93]
	v_mfma_f32_16x16x32_bf16 v[82:85], v[172:175], v[204:207], v[82:85]
	v_mfma_f32_16x16x32_bf16 v[74:77], v[180:183], v[204:207], v[74:77]
	v_mfma_f32_16x16x32_bf16 v[70:73], v[172:175], v[212:215], v[70:73]
	v_mfma_f32_16x16x32_bf16 v[66:69], v[180:183], v[212:215], v[66:69]
	v_mfma_f32_16x16x32_bf16 v[114:117], v[176:179], v[192:195], v[114:117]
	v_mfma_f32_16x16x32_bf16 v[106:109], v[184:187], v[192:195], v[106:109]
	v_mfma_f32_16x16x32_bf16 v[98:101], v[176:179], v[200:203], v[98:101]
	v_mfma_f32_16x16x32_bf16 v[90:93], v[184:187], v[200:203], v[90:93]
	v_mfma_f32_16x16x32_bf16 v[82:85], v[176:179], v[208:211], v[82:85]
	v_mfma_f32_16x16x32_bf16 v[74:77], v[184:187], v[208:211], v[74:77]
	v_mfma_f32_16x16x32_bf16 v[70:73], v[176:179], v[216:219], v[70:73]
	v_mfma_f32_16x16x32_bf16 v[66:69], v[184:187], v[216:219], v[66:69]
	s_barrier
; #define PG8_STAGE(bufoff, gbase, voff) do { _Pragma("unroll") for (int _i = 0; _i < 2; ++_i) \
;         __builtin_amdgcn_global_load_lds((const unsigned*)((const char*)(gbase) + (voff)[_i]), (PG8_LAS unsigned*)(lds + (bufoff) + ldsw + _i * 8192), 16, 0, 0); } while (0)
; #define PG8_WAIT_V(n) asm volatile("s_waitcnt vmcnt(" #n ")" ::: "memory")
; #define PG8_WAIT_L(n) asm volatile("s_waitcnt lgkmcnt(" #n ")" ::: "memory")
; #define PG8_BAR __builtin_amdgcn_s_barrier()
; #define PG8_SCHED __builtin_amdgcn_sched_barrier(0)
; template <class Epi, class Sched, bool ALIGN_EPI = true, bool SP2 = true>
; __device__ __forceinline__ void gemm_phase(PG8_LAS unsigned char* lds, const int K  , const Sched& S, const Epi& E) {
;     ...
;             PG8_LDA(At, 1, 1); PG8_STAGE(PG8_SB(1, 0), b3, voffB); PG8_STAGE(PG8_SB(1, 1), b3 + hstep, voffB); PG8_STAGE(PG8_SA(1, 0), a3, voffA);
;             PG8_WAIT_V(8); PG8_WAIT_L(0); PG8_BAR; PG8_MMA(1, 0, At, B0); PG8_MMA(1, 1, At, B1); PG8_BAR; PG8_SCHED;
;     ...
;         if constexpr (ALIGN_EPI) { if (wr == 0) PG8_BAR; }
	s_setprio 0
	s_add_i32 s24, s48, s29
	v_lshl_add_u64 v[220:221], v[220:221], 0, s[6:7]
	s_mov_b32 m0, s24
	ds_read_b128 v[188:191], v158 offset:49152
	ds_read_b128 v[192:195], v158 offset:50176
	ds_read_b128 v[196:199], v158 offset:51200
	ds_read_b128 v[200:203], v158 offset:52224
	ds_read_b128 v[204:207], v158 offset:53248
	ds_read_b128 v[208:211], v158 offset:54272
	ds_read_b128 v[212:215], v158 offset:55296
	ds_read_b128 v[216:219], v158 offset:56320
	global_load_lds_dwordx4 v[220:221], off
	s_add_i32 m0, s24, 0x2000
	s_add_u32 s22, s22, 0x80080
	v_lshl_add_u64 v[220:221], v[222:223], 0, s[6:7]
	s_addc_u32 s23, s23, 0
	s_add_i32 s24, s49, s29
	global_load_lds_dwordx4 v[220:221], off
	v_lshl_add_u64 v[220:221], s[22:23], 0, v[136:137]
	s_mov_b32 m0, s24
	s_nop 0
	global_load_lds_dwordx4 v[220:221], off
	v_lshl_add_u64 v[220:221], s[22:23], 0, v[132:133]
	s_add_i32 m0, s24, 0x2000
	s_nop 0
	global_load_lds_dwordx4 v[220:221], off
	v_lshl_add_u64 v[220:221], v[224:225], 0, s[6:7]
	s_mov_b32 m0, s37
	s_nop 0
	global_load_lds_dwordx4 v[220:221], off
	v_lshl_add_u64 v[220:221], v[226:227], 0, s[6:7]
	s_mov_b32 m0, s38
	s_nop 0
	global_load_lds_dwordx4 v[220:221], off
	s_waitcnt vmcnt(8)
	s_waitcnt lgkmcnt(0)
	s_setprio 1
	s_barrier
	v_mfma_f32_16x16x32_bf16 v[62:65], v[150:153], v[188:191], v[62:65]
	v_mfma_f32_16x16x32_bf16 v[58:61], v[164:167], v[188:191], v[58:61]
	v_mfma_f32_16x16x32_bf16 v[54:57], v[150:153], v[196:199], v[54:57]
	v_mfma_f32_16x16x32_bf16 v[46:49], v[164:167], v[196:199], v[46:49]
	v_mfma_f32_16x16x32_bf16 v[38:41], v[150:153], v[204:207], v[38:41]
	v_mfma_f32_16x16x32_bf16 v[30:33], v[164:167], v[204:207], v[30:33]
	v_mfma_f32_16x16x32_bf16 v[22:25], v[150:153], v[212:215], v[22:25]
	v_mfma_f32_16x16x32_bf16 v[14:17], v[164:167], v[212:215], v[14:17]
	v_mfma_f32_16x16x32_bf16 v[62:65], v[160:163], v[192:195], v[62:65]
	v_mfma_f32_16x16x32_bf16 v[58:61], v[168:171], v[192:195], v[58:61]
	v_mfma_f32_16x16x32_bf16 v[54:57], v[160:163], v[200:203], v[54:57]
	v_mfma_f32_16x16x32_bf16 v[46:49], v[168:171], v[200:203], v[46:49]
	v_mfma_f32_16x16x32_bf16 v[38:41], v[160:163], v[208:211], v[38:41]
	v_mfma_f32_16x16x32_bf16 v[30:33], v[168:171], v[208:211], v[30:33]
	v_mfma_f32_16x16x32_bf16 v[22:25], v[160:163], v[216:219], v[22:25]
	v_mfma_f32_16x16x32_bf16 v[14:17], v[168:171], v[216:219], v[14:17]
	s_setprio 0
	s_setprio 1
	v_mfma_f32_16x16x32_bf16 v[50:53], v[172:175], v[188:191], v[50:53]
	v_mfma_f32_16x16x32_bf16 v[42:45], v[180:183], v[188:191], v[42:45]
	v_mfma_f32_16x16x32_bf16 v[34:37], v[172:175], v[196:199], v[34:37]
	v_mfma_f32_16x16x32_bf16 v[26:29], v[180:183], v[196:199], v[26:29]
	v_mfma_f32_16x16x32_bf16 v[18:21], v[172:175], v[204:207], v[18:21]
	v_mfma_f32_16x16x32_bf16 v[10:13], v[180:183], v[204:207], v[10:13]
	v_mfma_f32_16x16x32_bf16 v[6:9], v[172:175], v[212:215], v[6:9]
	v_mfma_f32_16x16x32_bf16 v[2:5], v[180:183], v[212:215], v[2:5]
	v_mfma_f32_16x16x32_bf16 v[50:53], v[176:179], v[192:195], v[50:53]
	v_mfma_f32_16x16x32_bf16 v[42:45], v[184:187], v[192:195], v[42:45]
	v_mfma_f32_16x16x32_bf16 v[34:37], v[176:179], v[200:203], v[34:37]
	v_mfma_f32_16x16x32_bf16 v[26:29], v[184:187], v[200:203], v[26:29]
	v_mfma_f32_16x16x32_bf16 v[18:21], v[176:179], v[208:211], v[18:21]
	v_mfma_f32_16x16x32_bf16 v[10:13], v[184:187], v[208:211], v[10:13]
	v_mfma_f32_16x16x32_bf16 v[6:9], v[176:179], v[216:219], v[6:9]
	v_mfma_f32_16x16x32_bf16 v[2:5], v[184:187], v[216:219], v[2:5]
	s_barrier
	s_setprio 0
	s_add_i32 s47, s47, 2
	s_add_u32 s20, s20, 0x100
	s_addc_u32 s21, s21, 0
	s_add_u32 s45, s45, 0x100
	s_addc_u32 s46, s46, 0
	s_cmp_gt_u32 s47, 29
	s_cbranch_scc0 .LBB0_537
	s_and_b64 vcc, exec, s[8:9]
	s_cbranch_vccz .LBB0_540
	s_barrier

; #define PG8_STAGE(bufoff, gbase, voff) do { _Pragma("unroll") for (int _i = 0; _i < 2; ++_i) \
;         __builtin_amdgcn_global_load_lds((const unsigned*)((const char*)(gbase) + (voff)[_i]), (PG8_LAS unsigned*)(lds + (bufoff) + ldsw + _i * 8192), 16, 0, 0); } while (0)
; #define PG8_WAIT_V(n) asm volatile("s_waitcnt vmcnt(" #n ")" ::: "memory")
; #define PG8_WAIT_L(n) asm volatile("s_waitcnt lgkmcnt(" #n ")" ::: "memory")
; #define PG8_BAR __builtin_amdgcn_s_barrier()
; #define PG8_SCHED __builtin_amdgcn_sched_barrier(0)
;     __device__ __forceinline__ int nt(const pg8::Unit& u) const { return u.kind == 0 ? ntiles : q_nt(u.kind - 1); }
; template <class Epi, class Sched, bool ALIGN_EPI = true, bool SP2 = true>
; __device__ __forceinline__ void gemm_phase(PG8_LAS unsigned char* lds, const int K  , const Sched& S, const Epi& E) {
;     ...
;             const bool last = (t == nt - 2);
;             const char* a1 = cA + (size_t)(t + 1) * kstep;
;             const char* a2 = last ? nA : cA + (size_t)(t + 2) * kstep; const char* b2 = last ? nB : cB + (size_t)(t + 2) * kstep;
;             const char* a3 = a2 + kstep; const char* b3 = b2 + kstep;
;             if constexpr (SP2) {
;             PG8_LDB(B0, 0, 0); PG8_LDB(B1, 0, 1); PG8_SCHED; PG8_LDA(At, 0, 0); PG8_STAGE(PG8_SA(1, 1), a1 + hstep, voffA);
;             PG8_WAIT_V(8); PG8_WAIT_L(0); PG8_BAR; PG8_MMA(0, 0, At, B0); PG8_MMA(0, 1, At, B1); PG8_BAR; PG8_SCHED;
;             PG8_LDA(At, 0, 1); PG8_STAGE(PG8_SB(0, 0), b2, voffB); PG8_STAGE(PG8_SB(0, 1), b2 + hstep, voffB); PG8_STAGE(PG8_SA(0, 0), a2, voffA);
;             PG8_WAIT_V(8); PG8_WAIT_L(0); PG8_BAR; PG8_MMA(1, 0, At, B0); PG8_MMA(1, 1, At, B1); PG8_BAR; PG8_SCHED;
.LBB0_955:
	s_waitcnt vmcnt(0)
	ds_read_b128 v[130:133], v232
	ds_read_b128 v[134:137], v232 offset:1024
	ds_read_b128 v[138:141], v232 offset:2048
	ds_read_b128 v[142:145], v232 offset:3072
	ds_read_b128 v[146:149], v233
	ds_read_b128 v[150:153], v233 offset:1024
	ds_read_b128 v[154:157], v233 offset:2048
	ds_read_b128 v[158:161], v233 offset:3072
	s_add_i32 s73, s28, 2
	s_add_u32 s26, s24, 0xfff80080
	s_addc_u32 s27, s25, -1
	s_cmp_eq_u32 s13, s28
	s_cselect_b32 s28, s16, s26
	s_cselect_b32 s29, s17, s27
	s_cselect_b32 s27, s19, s21
	s_cselect_b32 s26, s18, s15
	v_lshl_add_u64 v[194:195], s[24:25], 0, v[214:215]
	s_add_i32 m0, s23, 0xc000
	ds_read_b128 v[162:165], v234
	ds_read_b128 v[166:169], v234 offset:1024
	ds_read_b128 v[170:173], v234 offset:2048
	ds_read_b128 v[174:177], v234 offset:3072
	ds_read_b128 v[178:181], v234 offset:4096
	ds_read_b128 v[182:185], v234 offset:5120
	ds_read_b128 v[186:189], v234 offset:6144
	ds_read_b128 v[190:193], v234 offset:7168
	global_load_lds_dwordx4 v[194:195], off
	v_lshl_add_u64 v[194:195], s[24:25], 0, v[216:217]
	s_add_i32 m0, s23, 0xe000
	s_nop 0
	global_load_lds_dwordx4 v[194:195], off
	s_waitcnt vmcnt(8)
	s_waitcnt lgkmcnt(0)
	s_setprio 1
	s_barrier
	v_mfma_f32_16x16x32_bf16 v[126:129], v[130:133], v[162:165], v[126:129]
	v_mfma_f32_16x16x32_bf16 v[122:125], v[138:141], v[162:165], v[122:125]
	v_mfma_f32_16x16x32_bf16 v[118:121], v[130:133], v[170:173], v[118:121]
	v_mfma_f32_16x16x32_bf16 v[110:113], v[138:141], v[170:173], v[110:113]
	v_mfma_f32_16x16x32_bf16 v[102:105], v[130:133], v[178:181], v[102:105]
	v_mfma_f32_16x16x32_bf16 v[94:97], v[138:141], v[178:181], v[94:97]
	v_mfma_f32_16x16x32_bf16 v[86:89], v[130:133], v[186:189], v[86:89]
	v_mfma_f32_16x16x32_bf16 v[78:81], v[138:141], v[186:189], v[78:81]
	v_mfma_f32_16x16x32_bf16 v[126:129], v[134:137], v[166:169], v[126:129]
	v_mfma_f32_16x16x32_bf16 v[122:125], v[142:145], v[166:169], v[122:125]
	v_mfma_f32_16x16x32_bf16 v[118:121], v[134:137], v[174:177], v[118:121]
	v_mfma_f32_16x16x32_bf16 v[110:113], v[142:145], v[174:177], v[110:113]
	v_mfma_f32_16x16x32_bf16 v[102:105], v[134:137], v[182:185], v[102:105]
	v_mfma_f32_16x16x32_bf16 v[94:97], v[142:145], v[182:185], v[94:97]
	v_mfma_f32_16x16x32_bf16 v[86:89], v[134:137], v[190:193], v[86:89]
	v_mfma_f32_16x16x32_bf16 v[78:81], v[142:145], v[190:193], v[78:81]
	s_setprio 0
	s_setprio 1
	v_mfma_f32_16x16x32_bf16 v[114:117], v[146:149], v[162:165], v[114:117]
	v_mfma_f32_16x16x32_bf16 v[106:109], v[154:157], v[162:165], v[106:109]
	v_mfma_f32_16x16x32_bf16 v[98:101], v[146:149], v[170:173], v[98:101]
	v_mfma_f32_16x16x32_bf16 v[90:93], v[154:157], v[170:173], v[90:93]
	v_mfma_f32_16x16x32_bf16 v[82:85], v[146:149], v[178:181], v[82:85]
	v_mfma_f32_16x16x32_bf16 v[74:77], v[154:157], v[178:181], v[74:77]
	v_mfma_f32_16x16x32_bf16 v[70:73], v[146:149], v[186:189], v[70:73]
	v_mfma_f32_16x16x32_bf16 v[66:69], v[154:157], v[186:189], v[66:69]
	v_mfma_f32_16x16x32_bf16 v[114:117], v[150:153], v[166:169], v[114:117]
	v_mfma_f32_16x16x32_bf16 v[106:109], v[158:161], v[166:169], v[106:109]
	v_mfma_f32_16x16x32_bf16 v[98:101], v[150:153], v[174:177], v[98:101]
	v_mfma_f32_16x16x32_bf16 v[90:93], v[158:161], v[174:177], v[90:93]
	v_mfma_f32_16x16x32_bf16 v[82:85], v[150:153], v[182:185], v[82:85]
	v_mfma_f32_16x16x32_bf16 v[74:77], v[158:161], v[182:185], v[74:77]
	v_mfma_f32_16x16x32_bf16 v[70:73], v[150:153], v[190:193], v[70:73]
	v_mfma_f32_16x16x32_bf16 v[66:69], v[158:161], v[190:193], v[66:69]
	s_barrier
	s_setprio 0
	s_add_i32 s74, s47, s33
	v_lshl_add_u64 v[194:195], s[26:27], 0, v[208:209]
	s_mov_b32 m0, s74
	ds_read_b128 v[162:165], v234 offset:16384
	ds_read_b128 v[166:169], v234 offset:17408
	ds_read_b128 v[170:173], v234 offset:18432
	ds_read_b128 v[174:177], v234 offset:19456
	ds_read_b128 v[178:181], v234 offset:20480
	ds_read_b128 v[182:185], v234 offset:21504
	ds_read_b128 v[186:189], v234 offset:22528
	ds_read_b128 v[190:193], v234 offset:23552
	global_load_lds_dwordx4 v[194:195], off
	s_add_i32 m0, s74, 0x2000
	s_add_u32 s74, s26, 0x80000
	v_lshl_add_u64 v[196:197], s[26:27], 0, v[212:213]
	s_addc_u32 s75, s27, 0
	s_add_i32 s76, s48, s33
	global_load_lds_dwordx4 v[196:197], off
	v_lshl_add_u64 v[198:199], s[74:75], 0, v[208:209]
	s_mov_b32 m0, s76
	v_lshl_add_u64 v[200:201], s[28:29], 0, v[210:211]
	global_load_lds_dwordx4 v[198:199], off
	v_lshl_add_u64 v[198:199], s[74:75], 0, v[212:213]
	s_add_i32 m0, s76, 0x2000
	s_nop 0
	global_load_lds_dwordx4 v[198:199], off
	v_lshl_add_u64 v[198:199], s[28:29], 0, v[206:207]
	s_mov_b32 m0, s23
	s_nop 0
	global_load_lds_dwordx4 v[198:199], off
	s_mov_b32 m0, s34
	s_nop 0
	global_load_lds_dwordx4 v[200:201], off
	s_waitcnt vmcnt(8)
	s_waitcnt lgkmcnt(0)
	s_setprio 1
	s_barrier
; #define PG8_STAGE(bufoff, gbase, voff) do { _Pragma("unroll") for (int _i = 0; _i < 2; ++_i) \
;         __builtin_amdgcn_global_load_lds((const unsigned*)((const char*)(gbase) + (voff)[_i]), (PG8_LAS unsigned*)(lds + (bufoff) + ldsw + _i * 8192), 16, 0, 0); } while (0)
; #define PG8_WAIT_V(n) asm volatile("s_waitcnt vmcnt(" #n ")" ::: "memory")
; #define PG8_WAIT_L(n) asm volatile("s_waitcnt lgkmcnt(" #n ")" ::: "memory")
; #define PG8_BAR __builtin_amdgcn_s_barrier()
; #define PG8_SCHED __builtin_amdgcn_sched_barrier(0)
; template <class Epi, class Sched, bool ALIGN_EPI = true, bool SP2 = true>
; __device__ __forceinline__ void gemm_phase(PG8_LAS unsigned char* lds, const int K  , const Sched& S, const Epi& E) {
;     ...
;             PG8_WAIT_V(8); PG8_WAIT_L(0); PG8_BAR; PG8_MMA(1, 0, At, B0); PG8_MMA(1, 1, At, B1); PG8_BAR; PG8_SCHED;
;             PG8_LDB(B0, 1, 0); PG8_LDB(B1, 1, 1); PG8_SCHED; PG8_LDA(At, 1, 0); PG8_STAGE(PG8_SA(0, 1), a2 + hstep, voffA);
;             PG8_WAIT_V(8); PG8_WAIT_L(0); PG8_BAR; PG8_MMA(0, 0, At, B0); PG8_MMA(0, 1, At, B1); PG8_BAR; PG8_SCHED;
	v_mfma_f32_16x16x32_bf16 v[62:65], v[130:133], v[162:165], v[62:65]
	v_mfma_f32_16x16x32_bf16 v[58:61], v[138:141], v[162:165], v[58:61]
	v_mfma_f32_16x16x32_bf16 v[54:57], v[130:133], v[170:173], v[54:57]
	v_mfma_f32_16x16x32_bf16 v[46:49], v[138:141], v[170:173], v[46:49]
	v_mfma_f32_16x16x32_bf16 v[38:41], v[130:133], v[178:181], v[38:41]
	v_mfma_f32_16x16x32_bf16 v[30:33], v[138:141], v[178:181], v[30:33]
	v_mfma_f32_16x16x32_bf16 v[22:25], v[130:133], v[186:189], v[22:25]
	v_mfma_f32_16x16x32_bf16 v[14:17], v[138:141], v[186:189], v[14:17]
	v_mfma_f32_16x16x32_bf16 v[62:65], v[134:137], v[166:169], v[62:65]
	v_mfma_f32_16x16x32_bf16 v[58:61], v[142:145], v[166:169], v[58:61]
	v_mfma_f32_16x16x32_bf16 v[54:57], v[134:137], v[174:177], v[54:57]
	v_mfma_f32_16x16x32_bf16 v[46:49], v[142:145], v[174:177], v[46:49]
	v_mfma_f32_16x16x32_bf16 v[38:41], v[134:137], v[182:185], v[38:41]
	v_mfma_f32_16x16x32_bf16 v[30:33], v[142:145], v[182:185], v[30:33]
	v_mfma_f32_16x16x32_bf16 v[22:25], v[134:137], v[190:193], v[22:25]
	v_mfma_f32_16x16x32_bf16 v[14:17], v[142:145], v[190:193], v[14:17]
	s_setprio 0
	s_setprio 1
	v_mfma_f32_16x16x32_bf16 v[50:53], v[146:149], v[162:165], v[50:53]
	v_mfma_f32_16x16x32_bf16 v[42:45], v[154:157], v[162:165], v[42:45]
	v_mfma_f32_16x16x32_bf16 v[34:37], v[146:149], v[170:173], v[34:37]
	v_mfma_f32_16x16x32_bf16 v[26:29], v[154:157], v[170:173], v[26:29]
	v_mfma_f32_16x16x32_bf16 v[18:21], v[146:149], v[178:181], v[18:21]
	v_mfma_f32_16x16x32_bf16 v[10:13], v[154:157], v[178:181], v[10:13]
	v_mfma_f32_16x16x32_bf16 v[6:9], v[146:149], v[186:189], v[6:9]
	v_mfma_f32_16x16x32_bf16 v[2:5], v[154:157], v[186:189], v[2:5]
	v_mfma_f32_16x16x32_bf16 v[50:53], v[150:153], v[166:169], v[50:53]
	v_mfma_f32_16x16x32_bf16 v[42:45], v[158:161], v[166:169], v[42:45]
	v_mfma_f32_16x16x32_bf16 v[34:37], v[150:153], v[174:177], v[34:37]
	v_mfma_f32_16x16x32_bf16 v[26:29], v[158:161], v[174:177], v[26:29]
	v_mfma_f32_16x16x32_bf16 v[18:21], v[150:153], v[182:185], v[18:21]
	v_mfma_f32_16x16x32_bf16 v[10:13], v[158:161], v[182:185], v[10:13]
	v_mfma_f32_16x16x32_bf16 v[6:9], v[150:153], v[190:193], v[6:9]
	v_mfma_f32_16x16x32_bf16 v[2:5], v[158:161], v[190:193], v[2:5]
	s_barrier
	s_setprio 0
	s_add_i32 s74, 0, 0x18000
	s_add_i32 s75, 0, 0x1c000
	v_add_u32_e32 v142, s74, v230
	v_add_u32_e32 v158, s75, v230
	ds_read_b128 v[130:133], v142
	ds_read_b128 v[134:137], v142 offset:1024
	ds_read_b128 v[138:141], v142 offset:2048
	ds_read_b128 v[142:145], v142 offset:3072
	ds_read_b128 v[146:149], v158
	ds_read_b128 v[150:153], v158 offset:1024
	ds_read_b128 v[154:157], v158 offset:2048
	ds_read_b128 v[158:161], v158 offset:3072
	s_add_u32 s28, s28, 0x80000
	s_addc_u32 s29, s29, 0
	s_mov_b32 m0, s35
	v_lshl_add_u64 v[202:203], s[28:29], 0, v[206:207]
	ds_read_b128 v[162:165], v234 offset:32768
	ds_read_b128 v[166:169], v234 offset:33792
	ds_read_b128 v[170:173], v234 offset:34816
	ds_read_b128 v[174:177], v234 offset:35840
	ds_read_b128 v[178:181], v234 offset:36864
	ds_read_b128 v[182:185], v234 offset:37888
	ds_read_b128 v[186:189], v234 offset:38912
	ds_read_b128 v[190:193], v234 offset:39936
	global_load_lds_dwordx4 v[202:203], off
	v_lshl_add_u64 v[202:203], s[28:29], 0, v[210:211]
	s_mov_b32 m0, s36
	s_nop 0
	global_load_lds_dwordx4 v[202:203], off
	s_waitcnt vmcnt(8)
	s_waitcnt lgkmcnt(0)
	s_setprio 1
	s_barrier
	v_mfma_f32_16x16x32_bf16 v[126:129], v[130:133], v[162:165], v[126:129]
	v_mfma_f32_16x16x32_bf16 v[122:125], v[138:141], v[162:165], v[122:125]
	v_mfma_f32_16x16x32_bf16 v[118:121], v[130:133], v[170:173], v[118:121]
	v_mfma_f32_16x16x32_bf16 v[110:113], v[138:141], v[170:173], v[110:113]
	v_mfma_f32_16x16x32_bf16 v[102:105], v[130:133], v[178:181], v[102:105]
	v_mfma_f32_16x16x32_bf16 v[94:97], v[138:141], v[178:181], v[94:97]
	v_mfma_f32_16x16x32_bf16 v[86:89], v[130:133], v[186:189], v[86:89]
	v_mfma_f32_16x16x32_bf16 v[78:81], v[138:141], v[186:189], v[78:81]
	v_mfma_f32_16x16x32_bf16 v[126:129], v[134:137], v[166:169], v[126:129]
	v_mfma_f32_16x16x32_bf16 v[122:125], v[142:145], v[166:169], v[122:125]
	v_mfma_f32_16x16x32_bf16 v[118:121], v[134:137], v[174:177], v[118:121]
	v_mfma_f32_16x16x32_bf16 v[110:113], v[142:145], v[174:177], v[110:113]
	v_mfma_f32_16x16x32_bf16 v[102:105], v[134:137], v[182:185], v[102:105]
	v_mfma_f32_16x16x32_bf16 v[94:97], v[142:145], v[182:185], v[94:97]
	v_mfma_f32_16x16x32_bf16 v[86:89], v[134:137], v[190:193], v[86:89]
	v_mfma_f32_16x16x32_bf16 v[78:81], v[142:145], v[190:193], v[78:81]
	s_setprio 0
	s_setprio 1
	v_mfma_f32_16x16x32_bf16 v[114:117], v[146:149], v[162:165], v[114:117]
	v_mfma_f32_16x16x32_bf16 v[106:109], v[154:157], v[162:165], v[106:109]
	v_mfma_f32_16x16x32_bf16 v[98:101], v[146:149], v[170:173], v[98:101]
	v_mfma_f32_16x16x32_bf16 v[90:93], v[154:157], v[170:173], v[90:93]
	v_mfma_f32_16x16x32_bf16 v[82:85], v[146:149], v[178:181], v[82:85]
	v_mfma_f32_16x16x32_bf16 v[74:77], v[154:157], v[178:181], v[74:77]
	v_mfma_f32_16x16x32_bf16 v[70:73], v[146:149], v[186:189], v[70:73]
	v_mfma_f32_16x16x32_bf16 v[66:69], v[154:157], v[186:189], v[66:69]
	v_mfma_f32_16x16x32_bf16 v[114:117], v[150:153], v[166:169], v[114:117]
	v_mfma_f32_16x16x32_bf16 v[106:109], v[158:161], v[166:169], v[106:109]
	v_mfma_f32_16x16x32_bf16 v[98:101], v[150:153], v[174:177], v[98:101]
	v_mfma_f32_16x16x32_bf16 v[90:93], v[158:161], v[174:177], v[90:93]
	v_mfma_f32_16x16x32_bf16 v[82:85], v[150:153], v[182:185], v[82:85]
	v_mfma_f32_16x16x32_bf16 v[74:77], v[158:161], v[182:185], v[74:77]
	v_mfma_f32_16x16x32_bf16 v[70:73], v[150:153], v[190:193], v[70:73]
	v_mfma_f32_16x16x32_bf16 v[66:69], v[158:161], v[190:193], v[66:69]
	s_barrier
; #define PG8_STAGE(bufoff, gbase, voff) do { _Pragma("unroll") for (int _i = 0; _i < 2; ++_i) \
;         __builtin_amdgcn_global_load_lds((const unsigned*)((const char*)(gbase) + (voff)[_i]), (PG8_LAS unsigned*)(lds + (bufoff) + ldsw + _i * 8192), 16, 0, 0); } while (0)
; #define PG8_WAIT_V(n) asm volatile("s_waitcnt vmcnt(" #n ")" ::: "memory")
; #define PG8_WAIT_L(n) asm volatile("s_waitcnt lgkmcnt(" #n ")" ::: "memory")
; #define PG8_BAR __builtin_amdgcn_s_barrier()
; #define PG8_SCHED __builtin_amdgcn_sched_barrier(0)
; template <class Epi, class Sched, bool ALIGN_EPI = true, bool SP2 = true>
; __device__ __forceinline__ void gemm_phase(PG8_LAS unsigned char* lds, const int K  , const Sched& S, const Epi& E) {
;     ...
;             PG8_WAIT_V(8); PG8_WAIT_L(0); PG8_BAR; PG8_MMA(0, 0, At, B0); PG8_MMA(0, 1, At, B1); PG8_BAR; PG8_SCHED;
;             PG8_LDA(At, 1, 1); PG8_STAGE(PG8_SB(1, 0), b3, voffB); PG8_STAGE(PG8_SB(1, 1), b3 + hstep, voffB); PG8_STAGE(PG8_SA(1, 0), a3, voffA);
;             PG8_WAIT_V(8); PG8_WAIT_L(0); PG8_BAR; PG8_MMA(1, 0, At, B0); PG8_MMA(1, 1, At, B1); PG8_BAR; PG8_SCHED;
;     ...
;         if constexpr (Epi::FP8) asm volatile("s_nop 15\n\ts_nop 15\n\ts_nop 15\n\ts_nop 15\n\ts_nop 15" ::: "memory");
;         if constexpr (ALIGN_EPI) { if (wr == 0) PG8_BAR; }
	s_setprio 0
	s_add_i32 s28, s74, s33
	v_lshl_add_u64 v[194:195], v[194:195], 0, s[8:9]
	s_mov_b32 m0, s28
	ds_read_b128 v[162:165], v234 offset:49152
	ds_read_b128 v[166:169], v234 offset:50176
	ds_read_b128 v[170:173], v234 offset:51200
	ds_read_b128 v[174:177], v234 offset:52224
	ds_read_b128 v[178:181], v234 offset:53248
	ds_read_b128 v[182:185], v234 offset:54272
	ds_read_b128 v[186:189], v234 offset:55296
	ds_read_b128 v[190:193], v234 offset:56320
	global_load_lds_dwordx4 v[194:195], off
	s_add_i32 m0, s28, 0x2000
	s_add_u32 s26, s26, 0x80080
	v_lshl_add_u64 v[194:195], v[196:197], 0, s[8:9]
	s_addc_u32 s27, s27, 0
	s_add_i32 s28, s75, s33
	global_load_lds_dwordx4 v[194:195], off
	v_lshl_add_u64 v[194:195], s[26:27], 0, v[208:209]
	s_mov_b32 m0, s28
	s_nop 0
	global_load_lds_dwordx4 v[194:195], off
	v_lshl_add_u64 v[194:195], s[26:27], 0, v[212:213]
	s_add_i32 m0, s28, 0x2000
	s_nop 0
	global_load_lds_dwordx4 v[194:195], off
	v_lshl_add_u64 v[194:195], v[198:199], 0, s[8:9]
	s_mov_b32 m0, s42
	s_nop 0
	global_load_lds_dwordx4 v[194:195], off
	v_lshl_add_u64 v[194:195], v[200:201], 0, s[8:9]
	s_mov_b32 m0, s43
	s_nop 0
	global_load_lds_dwordx4 v[194:195], off
	s_waitcnt vmcnt(8)
	s_waitcnt lgkmcnt(0)
	s_setprio 1
	s_barrier
	v_mfma_f32_16x16x32_bf16 v[62:65], v[130:133], v[162:165], v[62:65]
	v_mfma_f32_16x16x32_bf16 v[58:61], v[138:141], v[162:165], v[58:61]
	v_mfma_f32_16x16x32_bf16 v[54:57], v[130:133], v[170:173], v[54:57]
	v_mfma_f32_16x16x32_bf16 v[46:49], v[138:141], v[170:173], v[46:49]
	v_mfma_f32_16x16x32_bf16 v[38:41], v[130:133], v[178:181], v[38:41]
	v_mfma_f32_16x16x32_bf16 v[30:33], v[138:141], v[178:181], v[30:33]
	v_mfma_f32_16x16x32_bf16 v[22:25], v[130:133], v[186:189], v[22:25]
	v_mfma_f32_16x16x32_bf16 v[14:17], v[138:141], v[186:189], v[14:17]
	v_mfma_f32_16x16x32_bf16 v[62:65], v[134:137], v[166:169], v[62:65]
	v_mfma_f32_16x16x32_bf16 v[58:61], v[142:145], v[166:169], v[58:61]
	v_mfma_f32_16x16x32_bf16 v[54:57], v[134:137], v[174:177], v[54:57]
	v_mfma_f32_16x16x32_bf16 v[46:49], v[142:145], v[174:177], v[46:49]
	v_mfma_f32_16x16x32_bf16 v[38:41], v[134:137], v[182:185], v[38:41]
	v_mfma_f32_16x16x32_bf16 v[30:33], v[142:145], v[182:185], v[30:33]
	v_mfma_f32_16x16x32_bf16 v[22:25], v[134:137], v[190:193], v[22:25]
	v_mfma_f32_16x16x32_bf16 v[14:17], v[142:145], v[190:193], v[14:17]
	s_setprio 0
	s_setprio 1
	v_mfma_f32_16x16x32_bf16 v[50:53], v[146:149], v[162:165], v[50:53]
	v_mfma_f32_16x16x32_bf16 v[42:45], v[154:157], v[162:165], v[42:45]
	v_mfma_f32_16x16x32_bf16 v[34:37], v[146:149], v[170:173], v[34:37]
	v_mfma_f32_16x16x32_bf16 v[26:29], v[154:157], v[170:173], v[26:29]
	v_mfma_f32_16x16x32_bf16 v[18:21], v[146:149], v[178:181], v[18:21]
	v_mfma_f32_16x16x32_bf16 v[10:13], v[154:157], v[178:181], v[10:13]
	v_mfma_f32_16x16x32_bf16 v[6:9], v[146:149], v[186:189], v[6:9]
	v_mfma_f32_16x16x32_bf16 v[2:5], v[154:157], v[186:189], v[2:5]
	v_mfma_f32_16x16x32_bf16 v[50:53], v[150:153], v[166:169], v[50:53]
	v_mfma_f32_16x16x32_bf16 v[42:45], v[158:161], v[166:169], v[42:45]
	v_mfma_f32_16x16x32_bf16 v[34:37], v[150:153], v[174:177], v[34:37]
	v_mfma_f32_16x16x32_bf16 v[26:29], v[158:161], v[174:177], v[26:29]
	v_mfma_f32_16x16x32_bf16 v[18:21], v[150:153], v[182:185], v[18:21]
	v_mfma_f32_16x16x32_bf16 v[10:13], v[158:161], v[182:185], v[10:13]
	v_mfma_f32_16x16x32_bf16 v[6:9], v[150:153], v[190:193], v[6:9]
	v_mfma_f32_16x16x32_bf16 v[2:5], v[158:161], v[190:193], v[2:5]
	s_barrier
	s_setprio 0
	s_add_u32 s24, s24, 0x100
	s_addc_u32 s25, s25, 0
	s_add_u32 s15, s15, 0x100
	s_addc_u32 s21, s21, 0
	s_cmp_ge_u32 s73, s4
	s_mov_b32 s28, s73
	s_cbranch_scc0 .LBB0_955
	s_and_b64 vcc, exec, s[10:11]
	s_cbranch_vccz .LBB0_958
	s_barrier

; #define PG8_STAGE(bufoff, gbase, voff) do { _Pragma("unroll") for (int _i = 0; _i < 2; ++_i) \
;         __builtin_amdgcn_global_load_lds((const unsigned*)((const char*)(gbase) + (voff)[_i]), (PG8_LAS unsigned*)(lds + (bufoff) + ldsw + _i * 8192), 16, 0, 0); } while (0)
; #define PG8_WAIT_V(n) asm volatile("s_waitcnt vmcnt(" #n ")" ::: "memory")
; #define PG8_WAIT_L(n) asm volatile("s_waitcnt lgkmcnt(" #n ")" ::: "memory")
; #define PG8_BAR __builtin_amdgcn_s_barrier()
; #define PG8_SCHED __builtin_amdgcn_sched_barrier(0)
;     __device__ __forceinline__ int nt(const pg8::Unit& u) const { return u.kind == 0 ? ntiles : q_nt(u.kind - 1); }
; template <class Epi, class Sched, bool ALIGN_EPI = true, bool SP2 = true>
; __device__ __forceinline__ void gemm_phase(PG8_LAS unsigned char* lds, const int K  , const Sched& S, const Epi& E) {
;     ...
;         for (int t = 0; t < nt; t += 2) {
;             const bool last = (t == nt - 2);
;             const char* a1 = cA + (size_t)(t + 1) * kstep;
;             const char* a2 = last ? nA : cA + (size_t)(t + 2) * kstep; const char* b2 = last ? nB : cB + (size_t)(t + 2) * kstep;
;             const char* a3 = a2 + kstep; const char* b3 = b2 + kstep;
;             if constexpr (SP2) {
;             PG8_LDB(B0, 0, 0); PG8_LDB(B1, 0, 1); PG8_SCHED; PG8_LDA(At, 0, 0); PG8_STAGE(PG8_SA(1, 1), a1 + hstep, voffA);
;             PG8_WAIT_V(8); PG8_WAIT_L(0); PG8_BAR; PG8_MMA(0, 0, At, B0); PG8_MMA(0, 1, At, B1); PG8_BAR; PG8_SCHED;
;             PG8_LDA(At, 0, 1); PG8_STAGE(PG8_SB(0, 0), b2, voffB); PG8_STAGE(PG8_SB(0, 1), b2 + hstep, voffB); PG8_STAGE(PG8_SA(0, 0), a2, voffA);
.LBB0_1099:
	ds_read_b128 v[148:151], v154
	ds_read_b128 v[160:163], v154 offset:1024
	ds_read_b128 v[164:167], v154 offset:2048
	ds_read_b128 v[168:171], v154 offset:3072
	ds_read_b128 v[172:175], v155
	ds_read_b128 v[176:179], v155 offset:1024
	ds_read_b128 v[180:183], v155 offset:2048
	ds_read_b128 v[184:187], v155 offset:3072
	s_add_u32 s24, s22, 0xfff80080
	s_addc_u32 s25, s23, -1
	s_cmp_eq_u32 s48, 28
	s_cselect_b32 s27, s15, s25
	s_cselect_b32 s26, s44, s24
	s_cselect_b32 s25, s11, s47
	s_cselect_b32 s24, s45, s46
	v_lshl_add_u64 v[220:221], s[22:23], 0, v[140:141]
	s_add_i32 m0, s21, 0xc000
	ds_read_b128 v[188:191], v156
	ds_read_b128 v[192:195], v156 offset:1024
	ds_read_b128 v[196:199], v156 offset:2048
	ds_read_b128 v[200:203], v156 offset:3072
	ds_read_b128 v[204:207], v156 offset:4096
	ds_read_b128 v[208:211], v156 offset:5120
	ds_read_b128 v[212:215], v156 offset:6144
	ds_read_b128 v[216:219], v156 offset:7168
	global_load_lds_dwordx4 v[220:221], off
	v_lshl_add_u64 v[220:221], s[22:23], 0, v[142:143]
	s_add_i32 m0, s21, 0xe000
	s_nop 0
	global_load_lds_dwordx4 v[220:221], off
	s_waitcnt vmcnt(8)
	s_waitcnt lgkmcnt(0)
	s_setprio 1
	s_barrier
	v_mfma_f32_16x16x32_bf16 v[126:129], v[148:151], v[188:191], v[126:129]
	v_mfma_f32_16x16x32_bf16 v[118:121], v[164:167], v[188:191], v[118:121]
	v_mfma_f32_16x16x32_bf16 v[110:113], v[148:151], v[196:199], v[110:113]
	v_mfma_f32_16x16x32_bf16 v[102:105], v[164:167], v[196:199], v[102:105]
	v_mfma_f32_16x16x32_bf16 v[94:97], v[148:151], v[204:207], v[94:97]
	v_mfma_f32_16x16x32_bf16 v[86:89], v[164:167], v[204:207], v[86:89]
	v_mfma_f32_16x16x32_bf16 v[78:81], v[148:151], v[212:215], v[78:81]
	v_mfma_f32_16x16x32_bf16 v[70:73], v[164:167], v[212:215], v[70:73]
	v_mfma_f32_16x16x32_bf16 v[126:129], v[160:163], v[192:195], v[126:129]
	v_mfma_f32_16x16x32_bf16 v[118:121], v[168:171], v[192:195], v[118:121]
	v_mfma_f32_16x16x32_bf16 v[110:113], v[160:163], v[200:203], v[110:113]
	v_mfma_f32_16x16x32_bf16 v[102:105], v[168:171], v[200:203], v[102:105]
	v_mfma_f32_16x16x32_bf16 v[94:97], v[160:163], v[208:211], v[94:97]
	v_mfma_f32_16x16x32_bf16 v[86:89], v[168:171], v[208:211], v[86:89]
	v_mfma_f32_16x16x32_bf16 v[78:81], v[160:163], v[216:219], v[78:81]
	v_mfma_f32_16x16x32_bf16 v[70:73], v[168:171], v[216:219], v[70:73]
	s_setprio 0
	s_setprio 1
	v_mfma_f32_16x16x32_bf16 v[122:125], v[172:175], v[188:191], v[122:125]
	v_mfma_f32_16x16x32_bf16 v[114:117], v[180:183], v[188:191], v[114:117]
	v_mfma_f32_16x16x32_bf16 v[106:109], v[172:175], v[196:199], v[106:109]
	v_mfma_f32_16x16x32_bf16 v[98:101], v[180:183], v[196:199], v[98:101]
	v_mfma_f32_16x16x32_bf16 v[90:93], v[172:175], v[204:207], v[90:93]
	v_mfma_f32_16x16x32_bf16 v[82:85], v[180:183], v[204:207], v[82:85]
	v_mfma_f32_16x16x32_bf16 v[74:77], v[172:175], v[212:215], v[74:77]
	v_mfma_f32_16x16x32_bf16 v[66:69], v[180:183], v[212:215], v[66:69]
	v_mfma_f32_16x16x32_bf16 v[122:125], v[176:179], v[192:195], v[122:125]
	v_mfma_f32_16x16x32_bf16 v[114:117], v[184:187], v[192:195], v[114:117]
	v_mfma_f32_16x16x32_bf16 v[106:109], v[176:179], v[200:203], v[106:109]
	v_mfma_f32_16x16x32_bf16 v[98:101], v[184:187], v[200:203], v[98:101]
	v_mfma_f32_16x16x32_bf16 v[90:93], v[176:179], v[208:211], v[90:93]
	v_mfma_f32_16x16x32_bf16 v[82:85], v[184:187], v[208:211], v[82:85]
	v_mfma_f32_16x16x32_bf16 v[74:77], v[176:179], v[216:219], v[74:77]
	v_mfma_f32_16x16x32_bf16 v[66:69], v[184:187], v[216:219], v[66:69]
	s_barrier
	s_setprio 0
	s_add_i32 s49, s39, s29
	v_lshl_add_u64 v[220:221], s[24:25], 0, v[136:137]
	s_mov_b32 m0, s49
	ds_read_b128 v[188:191], v156 offset:16384
	ds_read_b128 v[192:195], v156 offset:17408
	ds_read_b128 v[196:199], v156 offset:18432
	ds_read_b128 v[200:203], v156 offset:19456
	ds_read_b128 v[204:207], v156 offset:20480
	ds_read_b128 v[208:211], v156 offset:21504
	ds_read_b128 v[212:215], v156 offset:22528
	ds_read_b128 v[216:219], v156 offset:23552
	global_load_lds_dwordx4 v[220:221], off
	s_add_i32 m0, s49, 0x2000
	s_add_u32 s50, s24, 0x80000
	v_lshl_add_u64 v[222:223], s[24:25], 0, v[132:133]
	s_addc_u32 s51, s25, 0
	s_add_i32 s49, s40, s29
	global_load_lds_dwordx4 v[222:223], off
	v_lshl_add_u64 v[224:225], s[50:51], 0, v[136:137]
	s_mov_b32 m0, s49
	v_lshl_add_u64 v[226:227], s[26:27], 0, v[134:135]
	global_load_lds_dwordx4 v[224:225], off
	v_lshl_add_u64 v[224:225], s[50:51], 0, v[132:133]
	s_add_i32 m0, s49, 0x2000
	s_nop 0
	global_load_lds_dwordx4 v[224:225], off
	v_lshl_add_u64 v[224:225], s[26:27], 0, v[138:139]
	s_mov_b32 m0, s21
	s_nop 0
	global_load_lds_dwordx4 v[224:225], off
	s_mov_b32 m0, s31
	s_nop 0
	global_load_lds_dwordx4 v[226:227], off
	s_waitcnt vmcnt(8)
	s_waitcnt lgkmcnt(0)
	s_setprio 1
	s_barrier
; #define PG8_STAGE(bufoff, gbase, voff) do { _Pragma("unroll") for (int _i = 0; _i < 2; ++_i) \
;         __builtin_amdgcn_global_load_lds((const unsigned*)((const char*)(gbase) + (voff)[_i]), (PG8_LAS unsigned*)(lds + (bufoff) + ldsw + _i * 8192), 16, 0, 0); } while (0)
; #define PG8_WAIT_V(n) asm volatile("s_waitcnt vmcnt(" #n ")" ::: "memory")
; #define PG8_WAIT_L(n) asm volatile("s_waitcnt lgkmcnt(" #n ")" ::: "memory")
; #define PG8_BAR __builtin_amdgcn_s_barrier()
; #define PG8_SCHED __builtin_amdgcn_sched_barrier(0)
; template <class Epi, class Sched, bool ALIGN_EPI = true, bool SP2 = true>
; __device__ __forceinline__ void gemm_phase(PG8_LAS unsigned char* lds, const int K  , const Sched& S, const Epi& E) {
;     ...
;             PG8_WAIT_V(8); PG8_WAIT_L(0); PG8_BAR; PG8_MMA(1, 0, At, B0); PG8_MMA(1, 1, At, B1); PG8_BAR; PG8_SCHED;
;             PG8_LDB(B0, 1, 0); PG8_LDB(B1, 1, 1); PG8_SCHED; PG8_LDA(At, 1, 0); PG8_STAGE(PG8_SA(0, 1), a2 + hstep, voffA);
;             PG8_WAIT_V(8); PG8_WAIT_L(0); PG8_BAR; PG8_MMA(0, 0, At, B0); PG8_MMA(0, 1, At, B1); PG8_BAR; PG8_SCHED;
	v_mfma_f32_16x16x32_bf16 v[62:65], v[148:151], v[188:191], v[62:65]
	v_mfma_f32_16x16x32_bf16 v[54:57], v[164:167], v[188:191], v[54:57]
	v_mfma_f32_16x16x32_bf16 v[46:49], v[148:151], v[196:199], v[46:49]
	v_mfma_f32_16x16x32_bf16 v[38:41], v[164:167], v[196:199], v[38:41]
	v_mfma_f32_16x16x32_bf16 v[30:33], v[148:151], v[204:207], v[30:33]
	v_mfma_f32_16x16x32_bf16 v[22:25], v[164:167], v[204:207], v[22:25]
	v_mfma_f32_16x16x32_bf16 v[14:17], v[148:151], v[212:215], v[14:17]
	v_mfma_f32_16x16x32_bf16 v[6:9], v[164:167], v[212:215], v[6:9]
	v_mfma_f32_16x16x32_bf16 v[62:65], v[160:163], v[192:195], v[62:65]
	v_mfma_f32_16x16x32_bf16 v[54:57], v[168:171], v[192:195], v[54:57]
	v_mfma_f32_16x16x32_bf16 v[46:49], v[160:163], v[200:203], v[46:49]
	v_mfma_f32_16x16x32_bf16 v[38:41], v[168:171], v[200:203], v[38:41]
	v_mfma_f32_16x16x32_bf16 v[30:33], v[160:163], v[208:211], v[30:33]
	v_mfma_f32_16x16x32_bf16 v[22:25], v[168:171], v[208:211], v[22:25]
	v_mfma_f32_16x16x32_bf16 v[14:17], v[160:163], v[216:219], v[14:17]
	v_mfma_f32_16x16x32_bf16 v[6:9], v[168:171], v[216:219], v[6:9]
	s_setprio 0
	s_setprio 1
	v_mfma_f32_16x16x32_bf16 v[58:61], v[172:175], v[188:191], v[58:61]
	v_mfma_f32_16x16x32_bf16 v[50:53], v[180:183], v[188:191], v[50:53]
	v_mfma_f32_16x16x32_bf16 v[42:45], v[172:175], v[196:199], v[42:45]
	v_mfma_f32_16x16x32_bf16 v[34:37], v[180:183], v[196:199], v[34:37]
	v_mfma_f32_16x16x32_bf16 v[26:29], v[172:175], v[204:207], v[26:29]
	v_mfma_f32_16x16x32_bf16 v[18:21], v[180:183], v[204:207], v[18:21]
	v_mfma_f32_16x16x32_bf16 v[10:13], v[172:175], v[212:215], v[10:13]
	v_mfma_f32_16x16x32_bf16 v[2:5], v[180:183], v[212:215], v[2:5]
	v_mfma_f32_16x16x32_bf16 v[58:61], v[176:179], v[192:195], v[58:61]
	v_mfma_f32_16x16x32_bf16 v[50:53], v[184:187], v[192:195], v[50:53]
	v_mfma_f32_16x16x32_bf16 v[42:45], v[176:179], v[200:203], v[42:45]
	v_mfma_f32_16x16x32_bf16 v[34:37], v[184:187], v[200:203], v[34:37]
	v_mfma_f32_16x16x32_bf16 v[26:29], v[176:179], v[208:211], v[26:29]
	v_mfma_f32_16x16x32_bf16 v[18:21], v[184:187], v[208:211], v[18:21]
	v_mfma_f32_16x16x32_bf16 v[10:13], v[176:179], v[216:219], v[10:13]
	v_mfma_f32_16x16x32_bf16 v[2:5], v[184:187], v[216:219], v[2:5]
	s_barrier
	s_setprio 0
	s_add_i32 s49, 0, 0x18000
	v_add_u32_e32 v159, s49, v152
	s_add_i32 s50, 0, 0x1c000
	ds_read_b128 v[148:151], v159
	ds_read_b128 v[160:163], v159 offset:1024
	ds_read_b128 v[164:167], v159 offset:2048
	ds_read_b128 v[168:171], v159 offset:3072
	v_add_u32_e32 v159, s50, v152
	ds_read_b128 v[172:175], v159
	ds_read_b128 v[176:179], v159 offset:1024
	ds_read_b128 v[180:183], v159 offset:2048
	ds_read_b128 v[184:187], v159 offset:3072
	s_add_u32 s26, s26, 0x80000
	s_addc_u32 s27, s27, 0
	s_mov_b32 m0, s33
	v_lshl_add_u64 v[230:231], s[26:27], 0, v[138:139]
	ds_read_b128 v[188:191], v156 offset:32768
	ds_read_b128 v[192:195], v156 offset:33792
	ds_read_b128 v[196:199], v156 offset:34816
	ds_read_b128 v[200:203], v156 offset:35840
	ds_read_b128 v[204:207], v156 offset:36864
	ds_read_b128 v[208:211], v156 offset:37888
	ds_read_b128 v[212:215], v156 offset:38912
	ds_read_b128 v[216:219], v156 offset:39936
	global_load_lds_dwordx4 v[230:231], off
	v_lshl_add_u64 v[230:231], s[26:27], 0, v[134:135]
	s_mov_b32 m0, s34
	s_nop 0
	global_load_lds_dwordx4 v[230:231], off
	s_waitcnt vmcnt(8)
	s_waitcnt lgkmcnt(0)
	s_setprio 1
	s_barrier
	v_mfma_f32_16x16x32_bf16 v[126:129], v[148:151], v[188:191], v[126:129]
	v_mfma_f32_16x16x32_bf16 v[118:121], v[164:167], v[188:191], v[118:121]
	v_mfma_f32_16x16x32_bf16 v[110:113], v[148:151], v[196:199], v[110:113]
	v_mfma_f32_16x16x32_bf16 v[102:105], v[164:167], v[196:199], v[102:105]
	v_mfma_f32_16x16x32_bf16 v[94:97], v[148:151], v[204:207], v[94:97]
	v_mfma_f32_16x16x32_bf16 v[86:89], v[164:167], v[204:207], v[86:89]
	v_mfma_f32_16x16x32_bf16 v[78:81], v[148:151], v[212:215], v[78:81]
	v_mfma_f32_16x16x32_bf16 v[70:73], v[164:167], v[212:215], v[70:73]
	v_mfma_f32_16x16x32_bf16 v[126:129], v[160:163], v[192:195], v[126:129]
	v_mfma_f32_16x16x32_bf16 v[118:121], v[168:171], v[192:195], v[118:121]
	v_mfma_f32_16x16x32_bf16 v[110:113], v[160:163], v[200:203], v[110:113]
	v_mfma_f32_16x16x32_bf16 v[102:105], v[168:171], v[200:203], v[102:105]
	v_mfma_f32_16x16x32_bf16 v[94:97], v[160:163], v[208:211], v[94:97]
	v_mfma_f32_16x16x32_bf16 v[86:89], v[168:171], v[208:211], v[86:89]
	v_mfma_f32_16x16x32_bf16 v[78:81], v[160:163], v[216:219], v[78:81]
	v_mfma_f32_16x16x32_bf16 v[70:73], v[168:171], v[216:219], v[70:73]
	s_setprio 0
	s_setprio 1
	v_mfma_f32_16x16x32_bf16 v[122:125], v[172:175], v[188:191], v[122:125]
	v_mfma_f32_16x16x32_bf16 v[114:117], v[180:183], v[188:191], v[114:117]
	v_mfma_f32_16x16x32_bf16 v[106:109], v[172:175], v[196:199], v[106:109]
	v_mfma_f32_16x16x32_bf16 v[98:101], v[180:183], v[196:199], v[98:101]
	v_mfma_f32_16x16x32_bf16 v[90:93], v[172:175], v[204:207], v[90:93]
	v_mfma_f32_16x16x32_bf16 v[82:85], v[180:183], v[204:207], v[82:85]
	v_mfma_f32_16x16x32_bf16 v[74:77], v[172:175], v[212:215], v[74:77]
	v_mfma_f32_16x16x32_bf16 v[66:69], v[180:183], v[212:215], v[66:69]
	v_mfma_f32_16x16x32_bf16 v[122:125], v[176:179], v[192:195], v[122:125]
	v_mfma_f32_16x16x32_bf16 v[114:117], v[184:187], v[192:195], v[114:117]
	v_mfma_f32_16x16x32_bf16 v[106:109], v[176:179], v[200:203], v[106:109]
	v_mfma_f32_16x16x32_bf16 v[98:101], v[184:187], v[200:203], v[98:101]
	v_mfma_f32_16x16x32_bf16 v[90:93], v[176:179], v[208:211], v[90:93]
	v_mfma_f32_16x16x32_bf16 v[82:85], v[184:187], v[208:211], v[82:85]
	v_mfma_f32_16x16x32_bf16 v[74:77], v[176:179], v[216:219], v[74:77]
	v_mfma_f32_16x16x32_bf16 v[66:69], v[184:187], v[216:219], v[66:69]
	s_barrier
; #define PG8_STAGE(bufoff, gbase, voff) do { _Pragma("unroll") for (int _i = 0; _i < 2; ++_i) \
;         __builtin_amdgcn_global_load_lds((const unsigned*)((const char*)(gbase) + (voff)[_i]), (PG8_LAS unsigned*)(lds + (bufoff) + ldsw + _i * 8192), 16, 0, 0); } while (0)
; #define PG8_WAIT_V(n) asm volatile("s_waitcnt vmcnt(" #n ")" ::: "memory")
; #define PG8_WAIT_L(n) asm volatile("s_waitcnt lgkmcnt(" #n ")" ::: "memory")
; #define PG8_BAR __builtin_amdgcn_s_barrier()
; #define PG8_SCHED __builtin_amdgcn_sched_barrier(0)
; template <class Epi, class Sched, bool ALIGN_EPI = true, bool SP2 = true>
; __device__ __forceinline__ void gemm_phase(PG8_LAS unsigned char* lds, const int K  , const Sched& S, const Epi& E) {
;     ...
;             PG8_WAIT_V(8); PG8_WAIT_L(0); PG8_BAR; PG8_MMA(0, 0, At, B0); PG8_MMA(0, 1, At, B1); PG8_BAR; PG8_SCHED;
;             PG8_LDA(At, 1, 1); PG8_STAGE(PG8_SB(1, 0), b3, voffB); PG8_STAGE(PG8_SB(1, 1), b3 + hstep, voffB); PG8_STAGE(PG8_SA(1, 0), a3, voffA);
;             PG8_WAIT_V(8); PG8_WAIT_L(0); PG8_BAR; PG8_MMA(1, 0, At, B0); PG8_MMA(1, 1, At, B1); PG8_BAR; PG8_SCHED;
;     ...
;         if constexpr (Epi::FP8) asm volatile("s_nop 15\n\ts_nop 15\n\ts_nop 15\n\ts_nop 15\n\ts_nop 15" ::: "memory");
;         if constexpr (ALIGN_EPI) { if (wr == 0) PG8_BAR; }
	s_setprio 0
	s_add_i32 s26, s49, s29
	v_lshl_add_u64 v[220:221], v[220:221], 0, s[4:5]
	s_mov_b32 m0, s26
	ds_read_b128 v[188:191], v156 offset:49152
	ds_read_b128 v[192:195], v156 offset:50176
	ds_read_b128 v[196:199], v156 offset:51200
	ds_read_b128 v[200:203], v156 offset:52224
	ds_read_b128 v[204:207], v156 offset:53248
	ds_read_b128 v[208:211], v156 offset:54272
	ds_read_b128 v[212:215], v156 offset:55296
	ds_read_b128 v[216:219], v156 offset:56320
	global_load_lds_dwordx4 v[220:221], off
	s_add_i32 m0, s26, 0x2000
	s_add_u32 s24, s24, 0x80080
	v_lshl_add_u64 v[220:221], v[222:223], 0, s[4:5]
	s_addc_u32 s25, s25, 0
	s_add_i32 s26, s50, s29
	global_load_lds_dwordx4 v[220:221], off
	v_lshl_add_u64 v[220:221], s[24:25], 0, v[136:137]
	s_mov_b32 m0, s26
	s_nop 0
	global_load_lds_dwordx4 v[220:221], off
	v_lshl_add_u64 v[220:221], s[24:25], 0, v[132:133]
	s_add_i32 m0, s26, 0x2000
	s_nop 0
	global_load_lds_dwordx4 v[220:221], off
	v_lshl_add_u64 v[220:221], v[224:225], 0, s[4:5]
	s_mov_b32 m0, s36
	s_nop 0
	global_load_lds_dwordx4 v[220:221], off
	v_lshl_add_u64 v[220:221], v[226:227], 0, s[4:5]
	s_mov_b32 m0, s37
	s_nop 0
	global_load_lds_dwordx4 v[220:221], off
	s_waitcnt vmcnt(8)
	s_waitcnt lgkmcnt(0)
	s_setprio 1
	s_barrier
	v_mfma_f32_16x16x32_bf16 v[62:65], v[148:151], v[188:191], v[62:65]
	v_mfma_f32_16x16x32_bf16 v[54:57], v[164:167], v[188:191], v[54:57]
	v_mfma_f32_16x16x32_bf16 v[46:49], v[148:151], v[196:199], v[46:49]
	v_mfma_f32_16x16x32_bf16 v[38:41], v[164:167], v[196:199], v[38:41]
	v_mfma_f32_16x16x32_bf16 v[30:33], v[148:151], v[204:207], v[30:33]
	v_mfma_f32_16x16x32_bf16 v[22:25], v[164:167], v[204:207], v[22:25]
	v_mfma_f32_16x16x32_bf16 v[14:17], v[148:151], v[212:215], v[14:17]
	v_mfma_f32_16x16x32_bf16 v[6:9], v[164:167], v[212:215], v[6:9]
	v_mfma_f32_16x16x32_bf16 v[62:65], v[160:163], v[192:195], v[62:65]
	v_mfma_f32_16x16x32_bf16 v[54:57], v[168:171], v[192:195], v[54:57]
	v_mfma_f32_16x16x32_bf16 v[46:49], v[160:163], v[200:203], v[46:49]
	v_mfma_f32_16x16x32_bf16 v[38:41], v[168:171], v[200:203], v[38:41]
	v_mfma_f32_16x16x32_bf16 v[30:33], v[160:163], v[208:211], v[30:33]
	v_mfma_f32_16x16x32_bf16 v[22:25], v[168:171], v[208:211], v[22:25]
	v_mfma_f32_16x16x32_bf16 v[14:17], v[160:163], v[216:219], v[14:17]
	v_mfma_f32_16x16x32_bf16 v[6:9], v[168:171], v[216:219], v[6:9]
	s_setprio 0
	s_setprio 1
	v_mfma_f32_16x16x32_bf16 v[58:61], v[172:175], v[188:191], v[58:61]
	v_mfma_f32_16x16x32_bf16 v[50:53], v[180:183], v[188:191], v[50:53]
	v_mfma_f32_16x16x32_bf16 v[42:45], v[172:175], v[196:199], v[42:45]
	v_mfma_f32_16x16x32_bf16 v[34:37], v[180:183], v[196:199], v[34:37]
	v_mfma_f32_16x16x32_bf16 v[26:29], v[172:175], v[204:207], v[26:29]
	v_mfma_f32_16x16x32_bf16 v[18:21], v[180:183], v[204:207], v[18:21]
	v_mfma_f32_16x16x32_bf16 v[10:13], v[172:175], v[212:215], v[10:13]
	v_mfma_f32_16x16x32_bf16 v[2:5], v[180:183], v[212:215], v[2:5]
	v_mfma_f32_16x16x32_bf16 v[58:61], v[176:179], v[192:195], v[58:61]
	v_mfma_f32_16x16x32_bf16 v[50:53], v[184:187], v[192:195], v[50:53]
	v_mfma_f32_16x16x32_bf16 v[42:45], v[176:179], v[200:203], v[42:45]
	v_mfma_f32_16x16x32_bf16 v[34:37], v[184:187], v[200:203], v[34:37]
	v_mfma_f32_16x16x32_bf16 v[26:29], v[176:179], v[208:211], v[26:29]
	v_mfma_f32_16x16x32_bf16 v[18:21], v[184:187], v[208:211], v[18:21]
	v_mfma_f32_16x16x32_bf16 v[10:13], v[176:179], v[216:219], v[10:13]
	v_mfma_f32_16x16x32_bf16 v[2:5], v[184:187], v[216:219], v[2:5]
	s_barrier
	s_setprio 0
	s_add_i32 s48, s48, 2
	s_add_u32 s22, s22, 0x100
	s_addc_u32 s23, s23, 0
	s_add_u32 s46, s46, 0x100
	s_addc_u32 s47, s47, 0
	s_cmp_gt_u32 s48, 29
	s_cbranch_scc0 .LBB0_1099
	s_and_b64 vcc, exec, s[8:9]
	s_cbranch_vccz .LBB0_1102
	s_barrier

; #define PG8_STAGE(bufoff, gbase, voff) do { _Pragma("unroll") for (int _i = 0; _i < 2; ++_i) \
;         __builtin_amdgcn_global_load_lds((const unsigned*)((const char*)(gbase) + (voff)[_i]), (PG8_LAS unsigned*)(lds + (bufoff) + ldsw + _i * 8192), 16, 0, 0); } while (0)
; #define PG8_WAIT_V(n) asm volatile("s_waitcnt vmcnt(" #n ")" ::: "memory")
; #define PG8_WAIT_L(n) asm volatile("s_waitcnt lgkmcnt(" #n ")" ::: "memory")
; #define PG8_BAR __builtin_amdgcn_s_barrier()
; #define PG8_SCHED __builtin_amdgcn_sched_barrier(0)
;     __device__ __forceinline__ int nt(const pg8::Unit& u) const { return u.kind == 0 ? ntiles : q_nt(u.kind - 1); }
; template <class Epi, class Sched, bool ALIGN_EPI = true, bool SP2 = true>
; __device__ __forceinline__ void gemm_phase(PG8_LAS unsigned char* lds, const int K  , const Sched& S, const Epi& E) {
;     ...
;         for (int t = 0; t < nt; t += 2) {
;             const bool last = (t == nt - 2);
;             const char* a1 = cA + (size_t)(t + 1) * kstep;
;             const char* a2 = last ? nA : cA + (size_t)(t + 2) * kstep; const char* b2 = last ? nB : cB + (size_t)(t + 2) * kstep;
;             const char* a3 = a2 + kstep; const char* b3 = b2 + kstep;
;             if constexpr (SP2) {
;             PG8_LDB(B0, 0, 0); PG8_LDB(B1, 0, 1); PG8_SCHED; PG8_LDA(At, 0, 0); PG8_STAGE(PG8_SA(1, 1), a1 + hstep, voffA);
;             PG8_WAIT_V(8); PG8_WAIT_L(0); PG8_BAR; PG8_MMA(0, 0, At, B0); PG8_MMA(0, 1, At, B1); PG8_BAR; PG8_SCHED;
;             PG8_LDA(At, 0, 1); PG8_STAGE(PG8_SB(0, 0), b2, voffB); PG8_STAGE(PG8_SB(0, 1), b2 + hstep, voffB); PG8_STAGE(PG8_SA(0, 0), a2, voffA);
;             PG8_WAIT_V(8); PG8_WAIT_L(0); PG8_BAR; PG8_MMA(1, 0, At, B0); PG8_MMA(1, 1, At, B1); PG8_BAR; PG8_SCHED;
.LBB0_1304:
	ds_read_b128 v[18:21], v233
	ds_read_b128 v[22:25], v233 offset:1024
	ds_read_b128 v[26:29], v233 offset:2048
	ds_read_b128 v[30:33], v233 offset:3072
	ds_read_b128 v[2:5], v234
	ds_read_b128 v[6:9], v234 offset:1024
	ds_read_b128 v[10:13], v234 offset:2048
	ds_read_b128 v[14:17], v234 offset:3072
	s_add_i32 s74, s22, 2
	s_add_u32 s20, s18, 0xfff50080
	s_addc_u32 s21, s19, -1
	s_cmp_eq_u32 s71, s22
	s_cselect_b32 s22, s14, s20
	s_cselect_b32 s23, s15, s21
	s_cselect_b32 s21, s17, s73
	s_cselect_b32 s20, s16, s72
	v_lshl_add_u64 v[186:187], s[18:19], 0, v[198:199]
	s_add_i32 m0, s26, 0xc000
	ds_read_b128 v[162:165], v235
	ds_read_b128 v[166:169], v235 offset:1024
	ds_read_b128 v[170:173], v235 offset:2048
	ds_read_b128 v[174:177], v235 offset:3072
	ds_read_b128 v[178:181], v235 offset:4096
	ds_read_b128 v[182:185], v235 offset:5120
	ds_read_b128 v[206:209], v235 offset:6144
	ds_read_b128 v[210:213], v235 offset:7168
	global_load_lds_dwordx4 v[186:187], off
	v_lshl_add_u64 v[186:187], s[18:19], 0, v[200:201]
	s_add_i32 m0, s26, 0xe000
	s_nop 0
	global_load_lds_dwordx4 v[186:187], off
	s_waitcnt vmcnt(8)
	s_waitcnt lgkmcnt(0)
	s_setprio 1
	s_barrier
	v_mfma_scale_f32_16x16x128_f8f6f4 v[158:161], v[18:25], v[162:169], v[158:161], v229, v229 op_sel_hi:[0,0,0]
	v_mfma_scale_f32_16x16x128_f8f6f4 v[154:157], v[26:33], v[162:169], v[154:157], v229, v229 op_sel_hi:[0,0,0]
	v_mfma_scale_f32_16x16x128_f8f6f4 v[150:153], v[18:25], v[170:177], v[150:153], v229, v229 op_sel_hi:[0,0,0]
	v_mfma_scale_f32_16x16x128_f8f6f4 v[142:145], v[26:33], v[170:177], v[142:145], v229, v229 op_sel_hi:[0,0,0]
	v_mfma_scale_f32_16x16x128_f8f6f4 v[134:137], v[18:25], v[178:185], v[134:137], v229, v229 op_sel_hi:[0,0,0]
	v_mfma_scale_f32_16x16x128_f8f6f4 v[126:129], v[26:33], v[178:185], v[126:129], v229, v229 op_sel_hi:[0,0,0]
	v_mfma_scale_f32_16x16x128_f8f6f4 v[118:121], v[18:25], v[206:213], v[118:121], v229, v229 op_sel_hi:[0,0,0]
	v_mfma_scale_f32_16x16x128_f8f6f4 v[110:113], v[26:33], v[206:213], v[110:113], v229, v229 op_sel_hi:[0,0,0]
	s_setprio 0
	s_setprio 1
	v_mfma_scale_f32_16x16x128_f8f6f4 v[146:149], v[2:9], v[162:169], v[146:149], v229, v229 op_sel_hi:[0,0,0]
	v_mfma_scale_f32_16x16x128_f8f6f4 v[138:141], v[10:17], v[162:169], v[138:141], v229, v229 op_sel_hi:[0,0,0]
	v_mfma_scale_f32_16x16x128_f8f6f4 v[130:133], v[2:9], v[170:177], v[130:133], v229, v229 op_sel_hi:[0,0,0]
	v_mfma_scale_f32_16x16x128_f8f6f4 v[122:125], v[10:17], v[170:177], v[122:125], v229, v229 op_sel_hi:[0,0,0]
	v_mfma_scale_f32_16x16x128_f8f6f4 v[114:117], v[2:9], v[178:185], v[114:117], v229, v229 op_sel_hi:[0,0,0]
	v_mfma_scale_f32_16x16x128_f8f6f4 v[106:109], v[10:17], v[178:185], v[106:109], v229, v229 op_sel_hi:[0,0,0]
	v_mfma_scale_f32_16x16x128_f8f6f4 v[102:105], v[2:9], v[206:213], v[102:105], v229, v229 op_sel_hi:[0,0,0]
	v_mfma_scale_f32_16x16x128_f8f6f4 v[98:101], v[10:17], v[206:213], v[98:101], v229, v229 op_sel_hi:[0,0,0]
	s_barrier
	s_setprio 0
	s_add_i32 s75, s40, s25
	v_lshl_add_u64 v[162:163], s[20:21], 0, v[192:193]
	s_mov_b32 m0, s75
	ds_read_b128 v[170:173], v235 offset:16384
	ds_read_b128 v[174:177], v235 offset:17408
	ds_read_b128 v[178:181], v235 offset:18432
	ds_read_b128 v[182:185], v235 offset:19456
	ds_read_b128 v[206:209], v235 offset:20480
	ds_read_b128 v[210:213], v235 offset:21504
	ds_read_b128 v[214:217], v235 offset:22528
	ds_read_b128 v[218:221], v235 offset:23552
	global_load_lds_dwordx4 v[162:163], off
	s_add_i32 m0, s75, 0x2000
	s_add_u32 s76, s20, 0xb0000
	v_lshl_add_u64 v[164:165], s[20:21], 0, v[196:197]
	s_addc_u32 s77, s21, 0
	s_add_i32 s75, s41, s25
	global_load_lds_dwordx4 v[164:165], off
	v_lshl_add_u64 v[166:167], s[76:77], 0, v[192:193]
	s_mov_b32 m0, s75
	v_lshl_add_u64 v[168:169], s[22:23], 0, v[194:195]
	global_load_lds_dwordx4 v[166:167], off
	v_lshl_add_u64 v[166:167], s[76:77], 0, v[196:197]
	s_add_i32 m0, s75, 0x2000
	s_nop 0
	global_load_lds_dwordx4 v[166:167], off
	v_lshl_add_u64 v[166:167], s[22:23], 0, v[190:191]
	s_mov_b32 m0, s26
	s_nop 0
	global_load_lds_dwordx4 v[166:167], off
	s_mov_b32 m0, s27
	s_nop 0
	global_load_lds_dwordx4 v[168:169], off
	s_waitcnt vmcnt(8)
	s_waitcnt lgkmcnt(0)
	s_setprio 1
	s_barrier
	v_mfma_scale_f32_16x16x128_f8f6f4 v[94:97], v[18:25], v[170:177], v[94:97], v229, v229 op_sel_hi:[0,0,0]
	v_mfma_scale_f32_16x16x128_f8f6f4 v[90:93], v[26:33], v[170:177], v[90:93], v229, v229 op_sel_hi:[0,0,0]
	v_mfma_scale_f32_16x16x128_f8f6f4 v[86:89], v[18:25], v[178:185], v[86:89], v229, v229 op_sel_hi:[0,0,0]
	v_mfma_scale_f32_16x16x128_f8f6f4 v[78:81], v[26:33], v[178:185], v[78:81], v229, v229 op_sel_hi:[0,0,0]
	v_mfma_scale_f32_16x16x128_f8f6f4 v[70:73], v[18:25], v[206:213], v[70:73], v229, v229 op_sel_hi:[0,0,0]
	v_mfma_scale_f32_16x16x128_f8f6f4 v[62:65], v[26:33], v[206:213], v[62:65], v229, v229 op_sel_hi:[0,0,0]
	v_mfma_scale_f32_16x16x128_f8f6f4 v[54:57], v[18:25], v[214:221], v[54:57], v229, v229 op_sel_hi:[0,0,0]
	v_mfma_scale_f32_16x16x128_f8f6f4 v[46:49], v[26:33], v[214:221], v[46:49], v229, v229 op_sel_hi:[0,0,0]
	s_setprio 0
	s_setprio 1
	v_mfma_scale_f32_16x16x128_f8f6f4 v[82:85], v[2:9], v[170:177], v[82:85], v229, v229 op_sel_hi:[0,0,0]
	v_mfma_scale_f32_16x16x128_f8f6f4 v[74:77], v[10:17], v[170:177], v[74:77], v229, v229 op_sel_hi:[0,0,0]
	v_mfma_scale_f32_16x16x128_f8f6f4 v[66:69], v[2:9], v[178:185], v[66:69], v229, v229 op_sel_hi:[0,0,0]
	v_mfma_scale_f32_16x16x128_f8f6f4 v[58:61], v[10:17], v[178:185], v[58:61], v229, v229 op_sel_hi:[0,0,0]
	v_mfma_scale_f32_16x16x128_f8f6f4 v[50:53], v[2:9], v[206:213], v[50:53], v229, v229 op_sel_hi:[0,0,0]
	v_mfma_scale_f32_16x16x128_f8f6f4 v[42:45], v[10:17], v[206:213], v[42:45], v229, v229 op_sel_hi:[0,0,0]
	v_mfma_scale_f32_16x16x128_f8f6f4 v[38:41], v[2:9], v[214:221], v[38:41], v229, v229 op_sel_hi:[0,0,0]
	v_mfma_scale_f32_16x16x128_f8f6f4 v[34:37], v[10:17], v[214:221], v[34:37], v229, v229 op_sel_hi:[0,0,0]
	s_barrier
; #define PG8_STAGE(bufoff, gbase, voff) do { _Pragma("unroll") for (int _i = 0; _i < 2; ++_i) \
;         __builtin_amdgcn_global_load_lds((const unsigned*)((const char*)(gbase) + (voff)[_i]), (PG8_LAS unsigned*)(lds + (bufoff) + ldsw + _i * 8192), 16, 0, 0); } while (0)
; #define PG8_WAIT_V(n) asm volatile("s_waitcnt vmcnt(" #n ")" ::: "memory")
; #define PG8_WAIT_L(n) asm volatile("s_waitcnt lgkmcnt(" #n ")" ::: "memory")
; #define PG8_BAR __builtin_amdgcn_s_barrier()
; #define PG8_SCHED __builtin_amdgcn_sched_barrier(0)
; template <class Epi, class Sched, bool ALIGN_EPI = true, bool SP2 = true>
; __device__ __forceinline__ void gemm_phase(PG8_LAS unsigned char* lds, const int K  , const Sched& S, const Epi& E) {
;     ...
;             PG8_LDB(B0, 1, 0); PG8_LDB(B1, 1, 1); PG8_SCHED; PG8_LDA(At, 1, 0); PG8_STAGE(PG8_SA(0, 1), a2 + hstep, voffA);
;             PG8_WAIT_V(8); PG8_WAIT_L(0); PG8_BAR; PG8_MMA(0, 0, At, B0); PG8_MMA(0, 1, At, B1); PG8_BAR; PG8_SCHED;
;             PG8_LDA(At, 1, 1); PG8_STAGE(PG8_SB(1, 0), b3, voffB); PG8_STAGE(PG8_SB(1, 1), b3 + hstep, voffB); PG8_STAGE(PG8_SA(1, 0), a3, voffA);
;             PG8_WAIT_V(8); PG8_WAIT_L(0); PG8_BAR; PG8_MMA(1, 0, At, B0); PG8_MMA(1, 1, At, B1); PG8_BAR; PG8_SCHED;
;     ...
;         if constexpr (Epi::FP8) asm volatile("s_nop 15\n\ts_nop 15\n\ts_nop 15\n\ts_nop 15\n\ts_nop 15" ::: "memory");
;         if constexpr (ALIGN_EPI) { if (wr == 0) PG8_BAR; }
	s_setprio 0
	s_add_i32 s75, 0, 0x18000
	s_add_i32 s76, 0, 0x1c000
	v_add_u32_e32 v14, s75, v231
	v_add_u32_e32 v30, s76, v231
	ds_read_b128 v[2:5], v14
	ds_read_b128 v[6:9], v14 offset:1024
	ds_read_b128 v[10:13], v14 offset:2048
	ds_read_b128 v[14:17], v14 offset:3072
	ds_read_b128 v[18:21], v30
	ds_read_b128 v[22:25], v30 offset:1024
	ds_read_b128 v[26:29], v30 offset:2048
	ds_read_b128 v[30:33], v30 offset:3072
	s_add_u32 s22, s22, 0xb0000
	s_addc_u32 s23, s23, 0
	s_mov_b32 m0, s28
	v_lshl_add_u64 v[186:187], s[22:23], 0, v[190:191]
	ds_read_b128 v[170:173], v235 offset:32768
	ds_read_b128 v[174:177], v235 offset:33792
	ds_read_b128 v[178:181], v235 offset:34816
	ds_read_b128 v[182:185], v235 offset:35840
	ds_read_b128 v[206:209], v235 offset:36864
	ds_read_b128 v[210:213], v235 offset:37888
	ds_read_b128 v[214:217], v235 offset:38912
	ds_read_b128 v[218:221], v235 offset:39936
	global_load_lds_dwordx4 v[186:187], off
	v_lshl_add_u64 v[186:187], s[22:23], 0, v[194:195]
	s_mov_b32 m0, s29
	s_nop 0
	global_load_lds_dwordx4 v[186:187], off
	s_waitcnt vmcnt(8)
	s_waitcnt lgkmcnt(0)
	s_setprio 1
	s_barrier
	v_mfma_scale_f32_16x16x128_f8f6f4 v[158:161], v[2:9], v[170:177], v[158:161], v229, v229 op_sel_hi:[0,0,0]
	v_mfma_scale_f32_16x16x128_f8f6f4 v[154:157], v[10:17], v[170:177], v[154:157], v229, v229 op_sel_hi:[0,0,0]
	v_mfma_scale_f32_16x16x128_f8f6f4 v[150:153], v[2:9], v[178:185], v[150:153], v229, v229 op_sel_hi:[0,0,0]
	v_mfma_scale_f32_16x16x128_f8f6f4 v[142:145], v[10:17], v[178:185], v[142:145], v229, v229 op_sel_hi:[0,0,0]
	v_mfma_scale_f32_16x16x128_f8f6f4 v[134:137], v[2:9], v[206:213], v[134:137], v229, v229 op_sel_hi:[0,0,0]
	v_mfma_scale_f32_16x16x128_f8f6f4 v[126:129], v[10:17], v[206:213], v[126:129], v229, v229 op_sel_hi:[0,0,0]
	v_mfma_scale_f32_16x16x128_f8f6f4 v[118:121], v[2:9], v[214:221], v[118:121], v229, v229 op_sel_hi:[0,0,0]
	v_mfma_scale_f32_16x16x128_f8f6f4 v[110:113], v[10:17], v[214:221], v[110:113], v229, v229 op_sel_hi:[0,0,0]
	s_setprio 0
	s_setprio 1
	v_mfma_scale_f32_16x16x128_f8f6f4 v[146:149], v[18:25], v[170:177], v[146:149], v229, v229 op_sel_hi:[0,0,0]
	v_mfma_scale_f32_16x16x128_f8f6f4 v[138:141], v[26:33], v[170:177], v[138:141], v229, v229 op_sel_hi:[0,0,0]
	v_mfma_scale_f32_16x16x128_f8f6f4 v[130:133], v[18:25], v[178:185], v[130:133], v229, v229 op_sel_hi:[0,0,0]
	v_mfma_scale_f32_16x16x128_f8f6f4 v[122:125], v[26:33], v[178:185], v[122:125], v229, v229 op_sel_hi:[0,0,0]
	v_mfma_scale_f32_16x16x128_f8f6f4 v[114:117], v[18:25], v[206:213], v[114:117], v229, v229 op_sel_hi:[0,0,0]
	v_mfma_scale_f32_16x16x128_f8f6f4 v[106:109], v[26:33], v[206:213], v[106:109], v229, v229 op_sel_hi:[0,0,0]
	v_mfma_scale_f32_16x16x128_f8f6f4 v[102:105], v[18:25], v[214:221], v[102:105], v229, v229 op_sel_hi:[0,0,0]
	v_mfma_scale_f32_16x16x128_f8f6f4 v[98:101], v[26:33], v[214:221], v[98:101], v229, v229 op_sel_hi:[0,0,0]
	s_barrier
	s_setprio 0
	s_add_i32 s22, s75, s25
	v_lshl_add_u64 v[162:163], v[162:163], 0, s[8:9]
	s_mov_b32 m0, s22
	ds_read_b128 v[170:173], v235 offset:49152
	ds_read_b128 v[174:177], v235 offset:50176
	ds_read_b128 v[178:181], v235 offset:51200
	ds_read_b128 v[182:185], v235 offset:52224
	ds_read_b128 v[206:209], v235 offset:53248
	ds_read_b128 v[210:213], v235 offset:54272
	ds_read_b128 v[214:217], v235 offset:55296
	ds_read_b128 v[218:221], v235 offset:56320
	global_load_lds_dwordx4 v[162:163], off
	s_add_i32 m0, s22, 0x2000
	s_add_u32 s20, s20, 0xb0080
	v_lshl_add_u64 v[162:163], v[164:165], 0, s[8:9]
	s_addc_u32 s21, s21, 0
	s_add_i32 s22, s76, s25
	global_load_lds_dwordx4 v[162:163], off
	v_lshl_add_u64 v[162:163], s[20:21], 0, v[192:193]
	s_mov_b32 m0, s22
	s_nop 0
	global_load_lds_dwordx4 v[162:163], off
	v_lshl_add_u64 v[162:163], s[20:21], 0, v[196:197]
	s_add_i32 m0, s22, 0x2000
	s_nop 0
	global_load_lds_dwordx4 v[162:163], off
	v_lshl_add_u64 v[162:163], v[166:167], 0, s[8:9]
	s_mov_b32 m0, s36
	s_nop 0
	global_load_lds_dwordx4 v[162:163], off
	v_lshl_add_u64 v[162:163], v[168:169], 0, s[8:9]
	s_mov_b32 m0, s37
	s_nop 0
	global_load_lds_dwordx4 v[162:163], off
	s_waitcnt vmcnt(8)
	s_waitcnt lgkmcnt(0)
	s_setprio 1
	s_barrier
	v_mfma_scale_f32_16x16x128_f8f6f4 v[94:97], v[2:9], v[170:177], v[94:97], v229, v229 op_sel_hi:[0,0,0]
	v_mfma_scale_f32_16x16x128_f8f6f4 v[90:93], v[10:17], v[170:177], v[90:93], v229, v229 op_sel_hi:[0,0,0]
	v_mfma_scale_f32_16x16x128_f8f6f4 v[86:89], v[2:9], v[178:185], v[86:89], v229, v229 op_sel_hi:[0,0,0]
	v_mfma_scale_f32_16x16x128_f8f6f4 v[78:81], v[10:17], v[178:185], v[78:81], v229, v229 op_sel_hi:[0,0,0]
	v_mfma_scale_f32_16x16x128_f8f6f4 v[70:73], v[2:9], v[206:213], v[70:73], v229, v229 op_sel_hi:[0,0,0]
	v_mfma_scale_f32_16x16x128_f8f6f4 v[62:65], v[10:17], v[206:213], v[62:65], v229, v229 op_sel_hi:[0,0,0]
	v_mfma_scale_f32_16x16x128_f8f6f4 v[54:57], v[2:9], v[214:221], v[54:57], v229, v229 op_sel_hi:[0,0,0]
	v_mfma_scale_f32_16x16x128_f8f6f4 v[46:49], v[10:17], v[214:221], v[46:49], v229, v229 op_sel_hi:[0,0,0]
	s_setprio 0
	s_setprio 1
	v_mfma_scale_f32_16x16x128_f8f6f4 v[82:85], v[18:25], v[170:177], v[82:85], v229, v229 op_sel_hi:[0,0,0]
	v_mfma_scale_f32_16x16x128_f8f6f4 v[74:77], v[26:33], v[170:177], v[74:77], v229, v229 op_sel_hi:[0,0,0]
	v_mfma_scale_f32_16x16x128_f8f6f4 v[66:69], v[18:25], v[178:185], v[66:69], v229, v229 op_sel_hi:[0,0,0]
	v_mfma_scale_f32_16x16x128_f8f6f4 v[58:61], v[26:33], v[178:185], v[58:61], v229, v229 op_sel_hi:[0,0,0]
	v_mfma_scale_f32_16x16x128_f8f6f4 v[50:53], v[18:25], v[206:213], v[50:53], v229, v229 op_sel_hi:[0,0,0]
	v_mfma_scale_f32_16x16x128_f8f6f4 v[42:45], v[26:33], v[206:213], v[42:45], v229, v229 op_sel_hi:[0,0,0]
	v_mfma_scale_f32_16x16x128_f8f6f4 v[38:41], v[18:25], v[214:221], v[38:41], v229, v229 op_sel_hi:[0,0,0]
	v_mfma_scale_f32_16x16x128_f8f6f4 v[34:37], v[26:33], v[214:221], v[34:37], v229, v229 op_sel_hi:[0,0,0]
	s_barrier
	s_setprio 0
	s_add_u32 s18, s18, 0x100
	s_addc_u32 s19, s19, 0
	s_add_u32 s72, s72, 0x100
	s_addc_u32 s73, s73, 0
	s_cmp_ge_u32 s74, s4
	s_mov_b32 s22, s74
	s_cbranch_scc0 .LBB0_1304
	s_nop 15
	s_nop 15
	s_nop 15
	s_nop 15
	s_nop 15
	s_and_b64 vcc, exec, s[10:11]
	s_cbranch_vccz .LBB0_1307
	s_barrier

; #define PG8_STAGE(bufoff, gbase, voff) do { _Pragma("unroll") for (int _i = 0; _i < 2; ++_i) \
;         __builtin_amdgcn_global_load_lds((const unsigned*)((const char*)(gbase) + (voff)[_i]), (PG8_LAS unsigned*)(lds + (bufoff) + ldsw + _i * 8192), 16, 0, 0); } while (0)
; #define PG8_WAIT_V(n) asm volatile("s_waitcnt vmcnt(" #n ")" ::: "memory")
; #define PG8_WAIT_L(n) asm volatile("s_waitcnt lgkmcnt(" #n ")" ::: "memory")
; #define PG8_BAR __builtin_amdgcn_s_barrier()
; #define PG8_SCHED __builtin_amdgcn_sched_barrier(0)
;     __device__ __forceinline__ int nt(const pg8::Unit& u) const { return u.kind == 0 ? ntiles : q_nt(u.kind - 1); }
; template <class Epi, class Sched, bool ALIGN_EPI = true, bool SP2 = true>
; __device__ __forceinline__ void gemm_phase(PG8_LAS unsigned char* lds, const int K  , const Sched& S, const Epi& E) {
;     ...
;         for (int t = 0; t < nt; t += 2) {
;             const bool last = (t == nt - 2);
;             const char* a1 = cA + (size_t)(t + 1) * kstep;
;             const char* a2 = last ? nA : cA + (size_t)(t + 2) * kstep; const char* b2 = last ? nB : cB + (size_t)(t + 2) * kstep;
;             const char* a3 = a2 + kstep; const char* b3 = b2 + kstep;
;             if constexpr (SP2) {
;             PG8_LDB(B0, 0, 0); PG8_LDB(B1, 0, 1); PG8_SCHED; PG8_LDA(At, 0, 0); PG8_STAGE(PG8_SA(1, 1), a1 + hstep, voffA);
;             PG8_WAIT_V(8); PG8_WAIT_L(0); PG8_BAR; PG8_MMA(0, 0, At, B0); PG8_MMA(0, 1, At, B1); PG8_BAR; PG8_SCHED;
;             PG8_LDA(At, 0, 1); PG8_STAGE(PG8_SB(0, 0), b2, voffB); PG8_STAGE(PG8_SB(0, 1), b2 + hstep, voffB); PG8_STAGE(PG8_SA(0, 0), a2, voffA);
.LBB0_1448:
	ds_read_b128 v[148:151], v154
	ds_read_b128 v[160:163], v154 offset:1024
	ds_read_b128 v[164:167], v154 offset:2048
	ds_read_b128 v[168:171], v154 offset:3072
	ds_read_b128 v[172:175], v155
	ds_read_b128 v[176:179], v155 offset:1024
	ds_read_b128 v[180:183], v155 offset:2048
	ds_read_b128 v[184:187], v155 offset:3072
	s_add_u32 s26, s24, 0xfff80080
	s_addc_u32 s27, s25, -1
	s_cmp_eq_u32 s50, 28
	s_cselect_b32 s29, s17, s27
	s_cselect_b32 s28, s46, s26
	s_cselect_b32 s27, s11, s49
	s_cselect_b32 s26, s47, s48
	v_lshl_add_u64 v[220:221], s[24:25], 0, v[140:141]
	s_add_i32 m0, s23, 0xc000
	ds_read_b128 v[188:191], v156
	ds_read_b128 v[192:195], v156 offset:1024
	ds_read_b128 v[196:199], v156 offset:2048
	ds_read_b128 v[200:203], v156 offset:3072
	ds_read_b128 v[204:207], v156 offset:4096
	ds_read_b128 v[208:211], v156 offset:5120
	ds_read_b128 v[212:215], v156 offset:6144
	ds_read_b128 v[216:219], v156 offset:7168
	global_load_lds_dwordx4 v[220:221], off
	v_lshl_add_u64 v[220:221], s[24:25], 0, v[142:143]
	s_add_i32 m0, s23, 0xe000
	s_nop 0
	global_load_lds_dwordx4 v[220:221], off
	s_waitcnt vmcnt(8)
	s_waitcnt lgkmcnt(0)
	s_setprio 1
	s_barrier
	v_mfma_f32_16x16x32_bf16 v[126:129], v[148:151], v[188:191], v[126:129]
	v_mfma_f32_16x16x32_bf16 v[118:121], v[164:167], v[188:191], v[118:121]
	v_mfma_f32_16x16x32_bf16 v[110:113], v[148:151], v[196:199], v[110:113]
	v_mfma_f32_16x16x32_bf16 v[102:105], v[164:167], v[196:199], v[102:105]
	v_mfma_f32_16x16x32_bf16 v[94:97], v[148:151], v[204:207], v[94:97]
	v_mfma_f32_16x16x32_bf16 v[86:89], v[164:167], v[204:207], v[86:89]
	v_mfma_f32_16x16x32_bf16 v[78:81], v[148:151], v[212:215], v[78:81]
	v_mfma_f32_16x16x32_bf16 v[70:73], v[164:167], v[212:215], v[70:73]
	v_mfma_f32_16x16x32_bf16 v[126:129], v[160:163], v[192:195], v[126:129]
	v_mfma_f32_16x16x32_bf16 v[118:121], v[168:171], v[192:195], v[118:121]
	v_mfma_f32_16x16x32_bf16 v[110:113], v[160:163], v[200:203], v[110:113]
	v_mfma_f32_16x16x32_bf16 v[102:105], v[168:171], v[200:203], v[102:105]
	v_mfma_f32_16x16x32_bf16 v[94:97], v[160:163], v[208:211], v[94:97]
	v_mfma_f32_16x16x32_bf16 v[86:89], v[168:171], v[208:211], v[86:89]
	v_mfma_f32_16x16x32_bf16 v[78:81], v[160:163], v[216:219], v[78:81]
	v_mfma_f32_16x16x32_bf16 v[70:73], v[168:171], v[216:219], v[70:73]
	s_setprio 0
	s_setprio 1
	v_mfma_f32_16x16x32_bf16 v[122:125], v[172:175], v[188:191], v[122:125]
	v_mfma_f32_16x16x32_bf16 v[114:117], v[180:183], v[188:191], v[114:117]
	v_mfma_f32_16x16x32_bf16 v[106:109], v[172:175], v[196:199], v[106:109]
	v_mfma_f32_16x16x32_bf16 v[98:101], v[180:183], v[196:199], v[98:101]
	v_mfma_f32_16x16x32_bf16 v[90:93], v[172:175], v[204:207], v[90:93]
	v_mfma_f32_16x16x32_bf16 v[82:85], v[180:183], v[204:207], v[82:85]
	v_mfma_f32_16x16x32_bf16 v[74:77], v[172:175], v[212:215], v[74:77]
	v_mfma_f32_16x16x32_bf16 v[66:69], v[180:183], v[212:215], v[66:69]
	v_mfma_f32_16x16x32_bf16 v[122:125], v[176:179], v[192:195], v[122:125]
	v_mfma_f32_16x16x32_bf16 v[114:117], v[184:187], v[192:195], v[114:117]
	v_mfma_f32_16x16x32_bf16 v[106:109], v[176:179], v[200:203], v[106:109]
	v_mfma_f32_16x16x32_bf16 v[98:101], v[184:187], v[200:203], v[98:101]
	v_mfma_f32_16x16x32_bf16 v[90:93], v[176:179], v[208:211], v[90:93]
	v_mfma_f32_16x16x32_bf16 v[82:85], v[184:187], v[208:211], v[82:85]
	v_mfma_f32_16x16x32_bf16 v[74:77], v[176:179], v[216:219], v[74:77]
	v_mfma_f32_16x16x32_bf16 v[66:69], v[184:187], v[216:219], v[66:69]
	s_barrier
	s_setprio 0
	s_add_i32 s51, s41, s31
	v_lshl_add_u64 v[220:221], s[26:27], 0, v[136:137]
	s_mov_b32 m0, s51
	ds_read_b128 v[188:191], v156 offset:16384
	ds_read_b128 v[192:195], v156 offset:17408
	ds_read_b128 v[196:199], v156 offset:18432
	ds_read_b128 v[200:203], v156 offset:19456
	ds_read_b128 v[204:207], v156 offset:20480
	ds_read_b128 v[208:211], v156 offset:21504
	ds_read_b128 v[212:215], v156 offset:22528
	ds_read_b128 v[216:219], v156 offset:23552
	global_load_lds_dwordx4 v[220:221], off
	s_add_i32 m0, s51, 0x2000
	s_add_u32 s68, s26, 0x80000
	v_lshl_add_u64 v[222:223], s[26:27], 0, v[132:133]
	s_addc_u32 s69, s27, 0
	s_add_i32 s51, s42, s31
	global_load_lds_dwordx4 v[222:223], off
	v_lshl_add_u64 v[224:225], s[68:69], 0, v[136:137]
	s_mov_b32 m0, s51
	v_lshl_add_u64 v[226:227], s[28:29], 0, v[134:135]
	global_load_lds_dwordx4 v[224:225], off
	v_lshl_add_u64 v[224:225], s[68:69], 0, v[132:133]
	s_add_i32 m0, s51, 0x2000
	s_nop 0
	global_load_lds_dwordx4 v[224:225], off
	v_lshl_add_u64 v[224:225], s[28:29], 0, v[138:139]
	s_mov_b32 m0, s23
	s_nop 0
	global_load_lds_dwordx4 v[224:225], off
	s_mov_b32 m0, s34
	s_nop 0
	global_load_lds_dwordx4 v[226:227], off
	s_waitcnt vmcnt(8)
	s_waitcnt lgkmcnt(0)
	s_setprio 1
	s_barrier
; #define PG8_STAGE(bufoff, gbase, voff) do { _Pragma("unroll") for (int _i = 0; _i < 2; ++_i) \
;         __builtin_amdgcn_global_load_lds((const unsigned*)((const char*)(gbase) + (voff)[_i]), (PG8_LAS unsigned*)(lds + (bufoff) + ldsw + _i * 8192), 16, 0, 0); } while (0)
; #define PG8_WAIT_V(n) asm volatile("s_waitcnt vmcnt(" #n ")" ::: "memory")
; #define PG8_WAIT_L(n) asm volatile("s_waitcnt lgkmcnt(" #n ")" ::: "memory")
; #define PG8_BAR __builtin_amdgcn_s_barrier()
; #define PG8_SCHED __builtin_amdgcn_sched_barrier(0)
; template <class Epi, class Sched, bool ALIGN_EPI = true, bool SP2 = true>
; __device__ __forceinline__ void gemm_phase(PG8_LAS unsigned char* lds, const int K  , const Sched& S, const Epi& E) {
;     ...
;             PG8_WAIT_V(8); PG8_WAIT_L(0); PG8_BAR; PG8_MMA(1, 0, At, B0); PG8_MMA(1, 1, At, B1); PG8_BAR; PG8_SCHED;
;             PG8_LDB(B0, 1, 0); PG8_LDB(B1, 1, 1); PG8_SCHED; PG8_LDA(At, 1, 0); PG8_STAGE(PG8_SA(0, 1), a2 + hstep, voffA);
;             PG8_WAIT_V(8); PG8_WAIT_L(0); PG8_BAR; PG8_MMA(0, 0, At, B0); PG8_MMA(0, 1, At, B1); PG8_BAR; PG8_SCHED;
	v_mfma_f32_16x16x32_bf16 v[62:65], v[148:151], v[188:191], v[62:65]
	v_mfma_f32_16x16x32_bf16 v[54:57], v[164:167], v[188:191], v[54:57]
	v_mfma_f32_16x16x32_bf16 v[46:49], v[148:151], v[196:199], v[46:49]
	v_mfma_f32_16x16x32_bf16 v[38:41], v[164:167], v[196:199], v[38:41]
	v_mfma_f32_16x16x32_bf16 v[30:33], v[148:151], v[204:207], v[30:33]
	v_mfma_f32_16x16x32_bf16 v[22:25], v[164:167], v[204:207], v[22:25]
	v_mfma_f32_16x16x32_bf16 v[14:17], v[148:151], v[212:215], v[14:17]
	v_mfma_f32_16x16x32_bf16 v[6:9], v[164:167], v[212:215], v[6:9]
	v_mfma_f32_16x16x32_bf16 v[62:65], v[160:163], v[192:195], v[62:65]
	v_mfma_f32_16x16x32_bf16 v[54:57], v[168:171], v[192:195], v[54:57]
	v_mfma_f32_16x16x32_bf16 v[46:49], v[160:163], v[200:203], v[46:49]
	v_mfma_f32_16x16x32_bf16 v[38:41], v[168:171], v[200:203], v[38:41]
	v_mfma_f32_16x16x32_bf16 v[30:33], v[160:163], v[208:211], v[30:33]
	v_mfma_f32_16x16x32_bf16 v[22:25], v[168:171], v[208:211], v[22:25]
	v_mfma_f32_16x16x32_bf16 v[14:17], v[160:163], v[216:219], v[14:17]
	v_mfma_f32_16x16x32_bf16 v[6:9], v[168:171], v[216:219], v[6:9]
	s_setprio 0
	s_setprio 1
	v_mfma_f32_16x16x32_bf16 v[58:61], v[172:175], v[188:191], v[58:61]
	v_mfma_f32_16x16x32_bf16 v[50:53], v[180:183], v[188:191], v[50:53]
	v_mfma_f32_16x16x32_bf16 v[42:45], v[172:175], v[196:199], v[42:45]
	v_mfma_f32_16x16x32_bf16 v[34:37], v[180:183], v[196:199], v[34:37]
	v_mfma_f32_16x16x32_bf16 v[26:29], v[172:175], v[204:207], v[26:29]
	v_mfma_f32_16x16x32_bf16 v[18:21], v[180:183], v[204:207], v[18:21]
	v_mfma_f32_16x16x32_bf16 v[10:13], v[172:175], v[212:215], v[10:13]
	v_mfma_f32_16x16x32_bf16 v[2:5], v[180:183], v[212:215], v[2:5]
	v_mfma_f32_16x16x32_bf16 v[58:61], v[176:179], v[192:195], v[58:61]
	v_mfma_f32_16x16x32_bf16 v[50:53], v[184:187], v[192:195], v[50:53]
	v_mfma_f32_16x16x32_bf16 v[42:45], v[176:179], v[200:203], v[42:45]
	v_mfma_f32_16x16x32_bf16 v[34:37], v[184:187], v[200:203], v[34:37]
	v_mfma_f32_16x16x32_bf16 v[26:29], v[176:179], v[208:211], v[26:29]
	v_mfma_f32_16x16x32_bf16 v[18:21], v[184:187], v[208:211], v[18:21]
	v_mfma_f32_16x16x32_bf16 v[10:13], v[176:179], v[216:219], v[10:13]
	v_mfma_f32_16x16x32_bf16 v[2:5], v[184:187], v[216:219], v[2:5]
	s_barrier
	s_setprio 0
	s_add_i32 s51, 0, 0x18000
	v_add_u32_e32 v159, s51, v152
	s_add_i32 s68, 0, 0x1c000
	ds_read_b128 v[148:151], v159
	ds_read_b128 v[160:163], v159 offset:1024
	ds_read_b128 v[164:167], v159 offset:2048
	ds_read_b128 v[168:171], v159 offset:3072
	v_add_u32_e32 v159, s68, v152
	ds_read_b128 v[172:175], v159
	ds_read_b128 v[176:179], v159 offset:1024
	ds_read_b128 v[180:183], v159 offset:2048
	ds_read_b128 v[184:187], v159 offset:3072
	s_add_u32 s28, s28, 0x80000
	s_addc_u32 s29, s29, 0
	s_mov_b32 m0, s35
	v_lshl_add_u64 v[230:231], s[28:29], 0, v[138:139]
	ds_read_b128 v[188:191], v156 offset:32768
	ds_read_b128 v[192:195], v156 offset:33792
	ds_read_b128 v[196:199], v156 offset:34816
	ds_read_b128 v[200:203], v156 offset:35840
	ds_read_b128 v[204:207], v156 offset:36864
	ds_read_b128 v[208:211], v156 offset:37888
	ds_read_b128 v[212:215], v156 offset:38912
	ds_read_b128 v[216:219], v156 offset:39936
	global_load_lds_dwordx4 v[230:231], off
	v_lshl_add_u64 v[230:231], s[28:29], 0, v[134:135]
	s_mov_b32 m0, s36
	s_nop 0
	global_load_lds_dwordx4 v[230:231], off
	s_waitcnt vmcnt(8)
	s_waitcnt lgkmcnt(0)
	s_setprio 1
	s_barrier
	v_mfma_f32_16x16x32_bf16 v[126:129], v[148:151], v[188:191], v[126:129]
	v_mfma_f32_16x16x32_bf16 v[118:121], v[164:167], v[188:191], v[118:121]
	v_mfma_f32_16x16x32_bf16 v[110:113], v[148:151], v[196:199], v[110:113]
	v_mfma_f32_16x16x32_bf16 v[102:105], v[164:167], v[196:199], v[102:105]
	v_mfma_f32_16x16x32_bf16 v[94:97], v[148:151], v[204:207], v[94:97]
	v_mfma_f32_16x16x32_bf16 v[86:89], v[164:167], v[204:207], v[86:89]
	v_mfma_f32_16x16x32_bf16 v[78:81], v[148:151], v[212:215], v[78:81]
	v_mfma_f32_16x16x32_bf16 v[70:73], v[164:167], v[212:215], v[70:73]
	v_mfma_f32_16x16x32_bf16 v[126:129], v[160:163], v[192:195], v[126:129]
	v_mfma_f32_16x16x32_bf16 v[118:121], v[168:171], v[192:195], v[118:121]
	v_mfma_f32_16x16x32_bf16 v[110:113], v[160:163], v[200:203], v[110:113]
	v_mfma_f32_16x16x32_bf16 v[102:105], v[168:171], v[200:203], v[102:105]
	v_mfma_f32_16x16x32_bf16 v[94:97], v[160:163], v[208:211], v[94:97]
	v_mfma_f32_16x16x32_bf16 v[86:89], v[168:171], v[208:211], v[86:89]
	v_mfma_f32_16x16x32_bf16 v[78:81], v[160:163], v[216:219], v[78:81]
	v_mfma_f32_16x16x32_bf16 v[70:73], v[168:171], v[216:219], v[70:73]
	s_setprio 0
	s_setprio 1
	v_mfma_f32_16x16x32_bf16 v[122:125], v[172:175], v[188:191], v[122:125]
	v_mfma_f32_16x16x32_bf16 v[114:117], v[180:183], v[188:191], v[114:117]
	v_mfma_f32_16x16x32_bf16 v[106:109], v[172:175], v[196:199], v[106:109]
	v_mfma_f32_16x16x32_bf16 v[98:101], v[180:183], v[196:199], v[98:101]
	v_mfma_f32_16x16x32_bf16 v[90:93], v[172:175], v[204:207], v[90:93]
	v_mfma_f32_16x16x32_bf16 v[82:85], v[180:183], v[204:207], v[82:85]
	v_mfma_f32_16x16x32_bf16 v[74:77], v[172:175], v[212:215], v[74:77]
	v_mfma_f32_16x16x32_bf16 v[66:69], v[180:183], v[212:215], v[66:69]
	v_mfma_f32_16x16x32_bf16 v[122:125], v[176:179], v[192:195], v[122:125]
	v_mfma_f32_16x16x32_bf16 v[114:117], v[184:187], v[192:195], v[114:117]
	v_mfma_f32_16x16x32_bf16 v[106:109], v[176:179], v[200:203], v[106:109]
	v_mfma_f32_16x16x32_bf16 v[98:101], v[184:187], v[200:203], v[98:101]
	v_mfma_f32_16x16x32_bf16 v[90:93], v[176:179], v[208:211], v[90:93]
	v_mfma_f32_16x16x32_bf16 v[82:85], v[184:187], v[208:211], v[82:85]
	v_mfma_f32_16x16x32_bf16 v[74:77], v[176:179], v[216:219], v[74:77]
	v_mfma_f32_16x16x32_bf16 v[66:69], v[184:187], v[216:219], v[66:69]
	s_barrier
; #define PG8_STAGE(bufoff, gbase, voff) do { _Pragma("unroll") for (int _i = 0; _i < 2; ++_i) \
;         __builtin_amdgcn_global_load_lds((const unsigned*)((const char*)(gbase) + (voff)[_i]), (PG8_LAS unsigned*)(lds + (bufoff) + ldsw + _i * 8192), 16, 0, 0); } while (0)
; #define PG8_WAIT_V(n) asm volatile("s_waitcnt vmcnt(" #n ")" ::: "memory")
; #define PG8_WAIT_L(n) asm volatile("s_waitcnt lgkmcnt(" #n ")" ::: "memory")
; #define PG8_BAR __builtin_amdgcn_s_barrier()
; #define PG8_SCHED __builtin_amdgcn_sched_barrier(0)
; template <class Epi, class Sched, bool ALIGN_EPI = true, bool SP2 = true>
; __device__ __forceinline__ void gemm_phase(PG8_LAS unsigned char* lds, const int K  , const Sched& S, const Epi& E) {
;     ...
;             PG8_WAIT_V(8); PG8_WAIT_L(0); PG8_BAR; PG8_MMA(0, 0, At, B0); PG8_MMA(0, 1, At, B1); PG8_BAR; PG8_SCHED;
;             PG8_LDA(At, 1, 1); PG8_STAGE(PG8_SB(1, 0), b3, voffB); PG8_STAGE(PG8_SB(1, 1), b3 + hstep, voffB); PG8_STAGE(PG8_SA(1, 0), a3, voffA);
;             PG8_WAIT_V(8); PG8_WAIT_L(0); PG8_BAR; PG8_MMA(1, 0, At, B0); PG8_MMA(1, 1, At, B1); PG8_BAR; PG8_SCHED;
;     ...
;         if constexpr (Epi::FP8) asm volatile("s_nop 15\n\ts_nop 15\n\ts_nop 15\n\ts_nop 15\n\ts_nop 15" ::: "memory");
;         if constexpr (ALIGN_EPI) { if (wr == 0) PG8_BAR; }
	s_setprio 0
	s_add_i32 s28, s51, s31
	v_lshl_add_u64 v[220:221], v[220:221], 0, s[4:5]
	s_mov_b32 m0, s28
	ds_read_b128 v[188:191], v156 offset:49152
	ds_read_b128 v[192:195], v156 offset:50176
	ds_read_b128 v[196:199], v156 offset:51200
	ds_read_b128 v[200:203], v156 offset:52224
	ds_read_b128 v[204:207], v156 offset:53248
	ds_read_b128 v[208:211], v156 offset:54272
	ds_read_b128 v[212:215], v156 offset:55296
	ds_read_b128 v[216:219], v156 offset:56320
	global_load_lds_dwordx4 v[220:221], off
	s_add_i32 m0, s28, 0x2000
	s_add_u32 s26, s26, 0x80080
	v_lshl_add_u64 v[220:221], v[222:223], 0, s[4:5]
	s_addc_u32 s27, s27, 0
	s_add_i32 s28, s68, s31
	global_load_lds_dwordx4 v[220:221], off
	v_lshl_add_u64 v[220:221], s[26:27], 0, v[136:137]
	s_mov_b32 m0, s28
	s_nop 0
	global_load_lds_dwordx4 v[220:221], off
	v_lshl_add_u64 v[220:221], s[26:27], 0, v[132:133]
	s_add_i32 m0, s28, 0x2000
	s_nop 0
	global_load_lds_dwordx4 v[220:221], off
	v_lshl_add_u64 v[220:221], v[224:225], 0, s[4:5]
	s_mov_b32 m0, s38
	s_nop 0
	global_load_lds_dwordx4 v[220:221], off
	v_lshl_add_u64 v[220:221], v[226:227], 0, s[4:5]
	s_mov_b32 m0, s39
	s_nop 0
	global_load_lds_dwordx4 v[220:221], off
	s_waitcnt vmcnt(8)
	s_waitcnt lgkmcnt(0)
	s_setprio 1
	s_barrier
	v_mfma_f32_16x16x32_bf16 v[62:65], v[148:151], v[188:191], v[62:65]
	v_mfma_f32_16x16x32_bf16 v[54:57], v[164:167], v[188:191], v[54:57]
	v_mfma_f32_16x16x32_bf16 v[46:49], v[148:151], v[196:199], v[46:49]
	v_mfma_f32_16x16x32_bf16 v[38:41], v[164:167], v[196:199], v[38:41]
	v_mfma_f32_16x16x32_bf16 v[30:33], v[148:151], v[204:207], v[30:33]
	v_mfma_f32_16x16x32_bf16 v[22:25], v[164:167], v[204:207], v[22:25]
	v_mfma_f32_16x16x32_bf16 v[14:17], v[148:151], v[212:215], v[14:17]
	v_mfma_f32_16x16x32_bf16 v[6:9], v[164:167], v[212:215], v[6:9]
	v_mfma_f32_16x16x32_bf16 v[62:65], v[160:163], v[192:195], v[62:65]
	v_mfma_f32_16x16x32_bf16 v[54:57], v[168:171], v[192:195], v[54:57]
	v_mfma_f32_16x16x32_bf16 v[46:49], v[160:163], v[200:203], v[46:49]
	v_mfma_f32_16x16x32_bf16 v[38:41], v[168:171], v[200:203], v[38:41]
	v_mfma_f32_16x16x32_bf16 v[30:33], v[160:163], v[208:211], v[30:33]
	v_mfma_f32_16x16x32_bf16 v[22:25], v[168:171], v[208:211], v[22:25]
	v_mfma_f32_16x16x32_bf16 v[14:17], v[160:163], v[216:219], v[14:17]
	v_mfma_f32_16x16x32_bf16 v[6:9], v[168:171], v[216:219], v[6:9]
	s_setprio 0
	s_setprio 1
	v_mfma_f32_16x16x32_bf16 v[58:61], v[172:175], v[188:191], v[58:61]
	v_mfma_f32_16x16x32_bf16 v[50:53], v[180:183], v[188:191], v[50:53]
	v_mfma_f32_16x16x32_bf16 v[42:45], v[172:175], v[196:199], v[42:45]
	v_mfma_f32_16x16x32_bf16 v[34:37], v[180:183], v[196:199], v[34:37]
	v_mfma_f32_16x16x32_bf16 v[26:29], v[172:175], v[204:207], v[26:29]
	v_mfma_f32_16x16x32_bf16 v[18:21], v[180:183], v[204:207], v[18:21]
	v_mfma_f32_16x16x32_bf16 v[10:13], v[172:175], v[212:215], v[10:13]
	v_mfma_f32_16x16x32_bf16 v[2:5], v[180:183], v[212:215], v[2:5]
	v_mfma_f32_16x16x32_bf16 v[58:61], v[176:179], v[192:195], v[58:61]
	v_mfma_f32_16x16x32_bf16 v[50:53], v[184:187], v[192:195], v[50:53]
	v_mfma_f32_16x16x32_bf16 v[42:45], v[176:179], v[200:203], v[42:45]
	v_mfma_f32_16x16x32_bf16 v[34:37], v[184:187], v[200:203], v[34:37]
	v_mfma_f32_16x16x32_bf16 v[26:29], v[176:179], v[208:211], v[26:29]
	v_mfma_f32_16x16x32_bf16 v[18:21], v[184:187], v[208:211], v[18:21]
	v_mfma_f32_16x16x32_bf16 v[10:13], v[176:179], v[216:219], v[10:13]
	v_mfma_f32_16x16x32_bf16 v[2:5], v[184:187], v[216:219], v[2:5]
	s_barrier
	s_setprio 0
	s_add_i32 s50, s50, 2
	s_add_u32 s24, s24, 0x100
	s_addc_u32 s25, s25, 0
	s_add_u32 s48, s48, 0x100
	s_addc_u32 s49, s49, 0
	s_cmp_gt_u32 s50, 29
	s_cbranch_scc0 .LBB0_1448
	s_and_b64 vcc, exec, s[8:9]
	s_cbranch_vccz .LBB0_1451
	s_barrier

; #define PG8_STAGE(bufoff, gbase, voff) do { _Pragma("unroll") for (int _i = 0; _i < 2; ++_i) \
;         __builtin_amdgcn_global_load_lds((const unsigned*)((const char*)(gbase) + (voff)[_i]), (PG8_LAS unsigned*)(lds + (bufoff) + ldsw + _i * 8192), 16, 0, 0); } while (0)
; #define PG8_WAIT_V(n) asm volatile("s_waitcnt vmcnt(" #n ")" ::: "memory")
; #define PG8_WAIT_L(n) asm volatile("s_waitcnt lgkmcnt(" #n ")" ::: "memory")
; #define PG8_BAR __builtin_amdgcn_s_barrier()
; #define PG8_SCHED __builtin_amdgcn_sched_barrier(0)
;     __device__ __forceinline__ int nt(const pg8::Unit& u) const { return u.kind == 0 ? ntiles : q_nt(u.kind - 1); }
; template <class Epi, class Sched, bool ALIGN_EPI = true, bool SP2 = true>
; __device__ __forceinline__ void gemm_phase(PG8_LAS unsigned char* lds, const int K  , const Sched& S, const Epi& E) {
;     ...
;         for (int t = 0; t < nt; t += 2) {
;             const bool last = (t == nt - 2);
;             const char* a1 = cA + (size_t)(t + 1) * kstep;
;             const char* a2 = last ? nA : cA + (size_t)(t + 2) * kstep; const char* b2 = last ? nB : cB + (size_t)(t + 2) * kstep;
;             const char* a3 = a2 + kstep; const char* b3 = b2 + kstep;
;             if constexpr (SP2) {
;             PG8_LDB(B0, 0, 0); PG8_LDB(B1, 0, 1); PG8_SCHED; PG8_LDA(At, 0, 0); PG8_STAGE(PG8_SA(1, 1), a1 + hstep, voffA);
;             PG8_WAIT_V(8); PG8_WAIT_L(0); PG8_BAR; PG8_MMA(0, 0, At, B0); PG8_MMA(0, 1, At, B1); PG8_BAR; PG8_SCHED;
;             PG8_LDA(At, 0, 1); PG8_STAGE(PG8_SB(0, 0), b2, voffB); PG8_STAGE(PG8_SB(0, 1), b2 + hstep, voffB); PG8_STAGE(PG8_SA(0, 0), a2, voffA);
;             PG8_WAIT_V(8); PG8_WAIT_L(0); PG8_BAR; PG8_MMA(1, 0, At, B0); PG8_MMA(1, 1, At, B1); PG8_BAR; PG8_SCHED;
.LBB0_1695:
	ds_read_b128 v[18:21], v233
	ds_read_b128 v[22:25], v233 offset:1024
	ds_read_b128 v[26:29], v233 offset:2048
	ds_read_b128 v[30:33], v233 offset:3072
	ds_read_b128 v[2:5], v234
	ds_read_b128 v[6:9], v234 offset:1024
	ds_read_b128 v[10:13], v234 offset:2048
	ds_read_b128 v[14:17], v234 offset:3072
	s_add_i32 s74, s24, 2
	s_add_u32 s22, s20, 0xfff50080
	s_addc_u32 s23, s21, -1
	s_cmp_eq_u32 s71, s24
	s_cselect_b32 s24, s16, s22
	s_cselect_b32 s25, s17, s23
	s_cselect_b32 s23, s19, s73
	s_cselect_b32 s22, s18, s72
	v_lshl_add_u64 v[186:187], s[20:21], 0, v[198:199]
	s_add_i32 m0, s28, 0xc000
	ds_read_b128 v[162:165], v235
	ds_read_b128 v[166:169], v235 offset:1024
	ds_read_b128 v[170:173], v235 offset:2048
	ds_read_b128 v[174:177], v235 offset:3072
	ds_read_b128 v[178:181], v235 offset:4096
	ds_read_b128 v[182:185], v235 offset:5120
	ds_read_b128 v[206:209], v235 offset:6144
	ds_read_b128 v[210:213], v235 offset:7168
	global_load_lds_dwordx4 v[186:187], off
	v_lshl_add_u64 v[186:187], s[20:21], 0, v[200:201]
	s_add_i32 m0, s28, 0xe000
	s_nop 0
	global_load_lds_dwordx4 v[186:187], off
	s_waitcnt vmcnt(8)
	s_waitcnt lgkmcnt(0)
	s_setprio 1
	s_barrier
	v_mfma_scale_f32_16x16x128_f8f6f4 v[158:161], v[18:25], v[162:169], v[158:161], v229, v229 op_sel_hi:[0,0,0]
	v_mfma_scale_f32_16x16x128_f8f6f4 v[154:157], v[26:33], v[162:169], v[154:157], v229, v229 op_sel_hi:[0,0,0]
	v_mfma_scale_f32_16x16x128_f8f6f4 v[150:153], v[18:25], v[170:177], v[150:153], v229, v229 op_sel_hi:[0,0,0]
	v_mfma_scale_f32_16x16x128_f8f6f4 v[142:145], v[26:33], v[170:177], v[142:145], v229, v229 op_sel_hi:[0,0,0]
	v_mfma_scale_f32_16x16x128_f8f6f4 v[134:137], v[18:25], v[178:185], v[134:137], v229, v229 op_sel_hi:[0,0,0]
	v_mfma_scale_f32_16x16x128_f8f6f4 v[126:129], v[26:33], v[178:185], v[126:129], v229, v229 op_sel_hi:[0,0,0]
	v_mfma_scale_f32_16x16x128_f8f6f4 v[118:121], v[18:25], v[206:213], v[118:121], v229, v229 op_sel_hi:[0,0,0]
	v_mfma_scale_f32_16x16x128_f8f6f4 v[110:113], v[26:33], v[206:213], v[110:113], v229, v229 op_sel_hi:[0,0,0]
	s_setprio 0
	s_setprio 1
	v_mfma_scale_f32_16x16x128_f8f6f4 v[146:149], v[2:9], v[162:169], v[146:149], v229, v229 op_sel_hi:[0,0,0]
	v_mfma_scale_f32_16x16x128_f8f6f4 v[138:141], v[10:17], v[162:169], v[138:141], v229, v229 op_sel_hi:[0,0,0]
	v_mfma_scale_f32_16x16x128_f8f6f4 v[130:133], v[2:9], v[170:177], v[130:133], v229, v229 op_sel_hi:[0,0,0]
	v_mfma_scale_f32_16x16x128_f8f6f4 v[122:125], v[10:17], v[170:177], v[122:125], v229, v229 op_sel_hi:[0,0,0]
	v_mfma_scale_f32_16x16x128_f8f6f4 v[114:117], v[2:9], v[178:185], v[114:117], v229, v229 op_sel_hi:[0,0,0]
	v_mfma_scale_f32_16x16x128_f8f6f4 v[106:109], v[10:17], v[178:185], v[106:109], v229, v229 op_sel_hi:[0,0,0]
	v_mfma_scale_f32_16x16x128_f8f6f4 v[102:105], v[2:9], v[206:213], v[102:105], v229, v229 op_sel_hi:[0,0,0]
	v_mfma_scale_f32_16x16x128_f8f6f4 v[98:101], v[10:17], v[206:213], v[98:101], v229, v229 op_sel_hi:[0,0,0]
	s_barrier
	s_setprio 0
	s_add_i32 s75, s40, s27
	v_lshl_add_u64 v[162:163], s[22:23], 0, v[192:193]
	s_mov_b32 m0, s75
	ds_read_b128 v[170:173], v235 offset:16384
	ds_read_b128 v[174:177], v235 offset:17408
	ds_read_b128 v[178:181], v235 offset:18432
	ds_read_b128 v[182:185], v235 offset:19456
	ds_read_b128 v[206:209], v235 offset:20480
	ds_read_b128 v[210:213], v235 offset:21504
	ds_read_b128 v[214:217], v235 offset:22528
	ds_read_b128 v[218:221], v235 offset:23552
	global_load_lds_dwordx4 v[162:163], off
	s_add_i32 m0, s75, 0x2000
	s_add_u32 s78, s22, 0xb0000
	v_lshl_add_u64 v[164:165], s[22:23], 0, v[196:197]
	s_addc_u32 s79, s23, 0
	s_add_i32 s75, s41, s27
	global_load_lds_dwordx4 v[164:165], off
	v_lshl_add_u64 v[166:167], s[78:79], 0, v[192:193]
	s_mov_b32 m0, s75
	v_lshl_add_u64 v[168:169], s[24:25], 0, v[194:195]
	global_load_lds_dwordx4 v[166:167], off
	v_lshl_add_u64 v[166:167], s[78:79], 0, v[196:197]
	s_add_i32 m0, s75, 0x2000
	s_nop 0
	global_load_lds_dwordx4 v[166:167], off
	v_lshl_add_u64 v[166:167], s[24:25], 0, v[190:191]
	s_mov_b32 m0, s28
	s_nop 0
	global_load_lds_dwordx4 v[166:167], off
	s_mov_b32 m0, s29
	s_nop 0
	global_load_lds_dwordx4 v[168:169], off
	s_waitcnt vmcnt(8)
	s_waitcnt lgkmcnt(0)
	s_setprio 1
	s_barrier
	v_mfma_scale_f32_16x16x128_f8f6f4 v[94:97], v[18:25], v[170:177], v[94:97], v229, v229 op_sel_hi:[0,0,0]
	v_mfma_scale_f32_16x16x128_f8f6f4 v[90:93], v[26:33], v[170:177], v[90:93], v229, v229 op_sel_hi:[0,0,0]
	v_mfma_scale_f32_16x16x128_f8f6f4 v[86:89], v[18:25], v[178:185], v[86:89], v229, v229 op_sel_hi:[0,0,0]
	v_mfma_scale_f32_16x16x128_f8f6f4 v[78:81], v[26:33], v[178:185], v[78:81], v229, v229 op_sel_hi:[0,0,0]
	v_mfma_scale_f32_16x16x128_f8f6f4 v[70:73], v[18:25], v[206:213], v[70:73], v229, v229 op_sel_hi:[0,0,0]
	v_mfma_scale_f32_16x16x128_f8f6f4 v[62:65], v[26:33], v[206:213], v[62:65], v229, v229 op_sel_hi:[0,0,0]
	v_mfma_scale_f32_16x16x128_f8f6f4 v[54:57], v[18:25], v[214:221], v[54:57], v229, v229 op_sel_hi:[0,0,0]
	v_mfma_scale_f32_16x16x128_f8f6f4 v[46:49], v[26:33], v[214:221], v[46:49], v229, v229 op_sel_hi:[0,0,0]
	s_setprio 0
	s_setprio 1
	v_mfma_scale_f32_16x16x128_f8f6f4 v[82:85], v[2:9], v[170:177], v[82:85], v229, v229 op_sel_hi:[0,0,0]
	v_mfma_scale_f32_16x16x128_f8f6f4 v[74:77], v[10:17], v[170:177], v[74:77], v229, v229 op_sel_hi:[0,0,0]
	v_mfma_scale_f32_16x16x128_f8f6f4 v[66:69], v[2:9], v[178:185], v[66:69], v229, v229 op_sel_hi:[0,0,0]
	v_mfma_scale_f32_16x16x128_f8f6f4 v[58:61], v[10:17], v[178:185], v[58:61], v229, v229 op_sel_hi:[0,0,0]
	v_mfma_scale_f32_16x16x128_f8f6f4 v[50:53], v[2:9], v[206:213], v[50:53], v229, v229 op_sel_hi:[0,0,0]
	v_mfma_scale_f32_16x16x128_f8f6f4 v[42:45], v[10:17], v[206:213], v[42:45], v229, v229 op_sel_hi:[0,0,0]
	v_mfma_scale_f32_16x16x128_f8f6f4 v[38:41], v[2:9], v[214:221], v[38:41], v229, v229 op_sel_hi:[0,0,0]
	v_mfma_scale_f32_16x16x128_f8f6f4 v[34:37], v[10:17], v[214:221], v[34:37], v229, v229 op_sel_hi:[0,0,0]
	s_barrier
; #define PG8_STAGE(bufoff, gbase, voff) do { _Pragma("unroll") for (int _i = 0; _i < 2; ++_i) \
;         __builtin_amdgcn_global_load_lds((const unsigned*)((const char*)(gbase) + (voff)[_i]), (PG8_LAS unsigned*)(lds + (bufoff) + ldsw + _i * 8192), 16, 0, 0); } while (0)
; #define PG8_WAIT_V(n) asm volatile("s_waitcnt vmcnt(" #n ")" ::: "memory")
; #define PG8_WAIT_L(n) asm volatile("s_waitcnt lgkmcnt(" #n ")" ::: "memory")
; #define PG8_BAR __builtin_amdgcn_s_barrier()
; #define PG8_SCHED __builtin_amdgcn_sched_barrier(0)
; template <class Epi, class Sched, bool ALIGN_EPI = true, bool SP2 = true>
; __device__ __forceinline__ void gemm_phase(PG8_LAS unsigned char* lds, const int K  , const Sched& S, const Epi& E) {
;     ...
;             PG8_LDB(B0, 1, 0); PG8_LDB(B1, 1, 1); PG8_SCHED; PG8_LDA(At, 1, 0); PG8_STAGE(PG8_SA(0, 1), a2 + hstep, voffA);
;             PG8_WAIT_V(8); PG8_WAIT_L(0); PG8_BAR; PG8_MMA(0, 0, At, B0); PG8_MMA(0, 1, At, B1); PG8_BAR; PG8_SCHED;
;             PG8_LDA(At, 1, 1); PG8_STAGE(PG8_SB(1, 0), b3, voffB); PG8_STAGE(PG8_SB(1, 1), b3 + hstep, voffB); PG8_STAGE(PG8_SA(1, 0), a3, voffA);
;             PG8_WAIT_V(8); PG8_WAIT_L(0); PG8_BAR; PG8_MMA(1, 0, At, B0); PG8_MMA(1, 1, At, B1); PG8_BAR; PG8_SCHED;
;     ...
;         if constexpr (Epi::FP8) asm volatile("s_nop 15\n\ts_nop 15\n\ts_nop 15\n\ts_nop 15\n\ts_nop 15" ::: "memory");
;         if constexpr (ALIGN_EPI) { if (wr == 0) PG8_BAR; }
	s_setprio 0
	s_add_i32 s75, 0, 0x18000
	s_add_i32 s78, 0, 0x1c000
	v_add_u32_e32 v14, s75, v231
	v_add_u32_e32 v30, s78, v231
	ds_read_b128 v[2:5], v14
	ds_read_b128 v[6:9], v14 offset:1024
	ds_read_b128 v[10:13], v14 offset:2048
	ds_read_b128 v[14:17], v14 offset:3072
	ds_read_b128 v[18:21], v30
	ds_read_b128 v[22:25], v30 offset:1024
	ds_read_b128 v[26:29], v30 offset:2048
	ds_read_b128 v[30:33], v30 offset:3072
	s_add_u32 s24, s24, 0xb0000
	s_addc_u32 s25, s25, 0
	s_mov_b32 m0, s30
	v_lshl_add_u64 v[186:187], s[24:25], 0, v[190:191]
	ds_read_b128 v[170:173], v235 offset:32768
	ds_read_b128 v[174:177], v235 offset:33792
	ds_read_b128 v[178:181], v235 offset:34816
	ds_read_b128 v[182:185], v235 offset:35840
	ds_read_b128 v[206:209], v235 offset:36864
	ds_read_b128 v[210:213], v235 offset:37888
	ds_read_b128 v[214:217], v235 offset:38912
	ds_read_b128 v[218:221], v235 offset:39936
	global_load_lds_dwordx4 v[186:187], off
	v_lshl_add_u64 v[186:187], s[24:25], 0, v[194:195]
	s_mov_b32 m0, s31
	s_nop 0
	global_load_lds_dwordx4 v[186:187], off
	s_waitcnt vmcnt(8)
	s_waitcnt lgkmcnt(0)
	s_setprio 1
	s_barrier
	v_mfma_scale_f32_16x16x128_f8f6f4 v[158:161], v[2:9], v[170:177], v[158:161], v229, v229 op_sel_hi:[0,0,0]
	v_mfma_scale_f32_16x16x128_f8f6f4 v[154:157], v[10:17], v[170:177], v[154:157], v229, v229 op_sel_hi:[0,0,0]
	v_mfma_scale_f32_16x16x128_f8f6f4 v[150:153], v[2:9], v[178:185], v[150:153], v229, v229 op_sel_hi:[0,0,0]
	v_mfma_scale_f32_16x16x128_f8f6f4 v[142:145], v[10:17], v[178:185], v[142:145], v229, v229 op_sel_hi:[0,0,0]
	v_mfma_scale_f32_16x16x128_f8f6f4 v[134:137], v[2:9], v[206:213], v[134:137], v229, v229 op_sel_hi:[0,0,0]
	v_mfma_scale_f32_16x16x128_f8f6f4 v[126:129], v[10:17], v[206:213], v[126:129], v229, v229 op_sel_hi:[0,0,0]
	v_mfma_scale_f32_16x16x128_f8f6f4 v[118:121], v[2:9], v[214:221], v[118:121], v229, v229 op_sel_hi:[0,0,0]
	v_mfma_scale_f32_16x16x128_f8f6f4 v[110:113], v[10:17], v[214:221], v[110:113], v229, v229 op_sel_hi:[0,0,0]
	s_setprio 0
	s_setprio 1
	v_mfma_scale_f32_16x16x128_f8f6f4 v[146:149], v[18:25], v[170:177], v[146:149], v229, v229 op_sel_hi:[0,0,0]
	v_mfma_scale_f32_16x16x128_f8f6f4 v[138:141], v[26:33], v[170:177], v[138:141], v229, v229 op_sel_hi:[0,0,0]
	v_mfma_scale_f32_16x16x128_f8f6f4 v[130:133], v[18:25], v[178:185], v[130:133], v229, v229 op_sel_hi:[0,0,0]
	v_mfma_scale_f32_16x16x128_f8f6f4 v[122:125], v[26:33], v[178:185], v[122:125], v229, v229 op_sel_hi:[0,0,0]
	v_mfma_scale_f32_16x16x128_f8f6f4 v[114:117], v[18:25], v[206:213], v[114:117], v229, v229 op_sel_hi:[0,0,0]
	v_mfma_scale_f32_16x16x128_f8f6f4 v[106:109], v[26:33], v[206:213], v[106:109], v229, v229 op_sel_hi:[0,0,0]
	v_mfma_scale_f32_16x16x128_f8f6f4 v[102:105], v[18:25], v[214:221], v[102:105], v229, v229 op_sel_hi:[0,0,0]
	v_mfma_scale_f32_16x16x128_f8f6f4 v[98:101], v[26:33], v[214:221], v[98:101], v229, v229 op_sel_hi:[0,0,0]
	s_barrier
	s_setprio 0
	s_add_i32 s24, s75, s27
	v_lshl_add_u64 v[162:163], v[162:163], 0, s[10:11]
	s_mov_b32 m0, s24
	ds_read_b128 v[170:173], v235 offset:49152
	ds_read_b128 v[174:177], v235 offset:50176
	ds_read_b128 v[178:181], v235 offset:51200
	ds_read_b128 v[182:185], v235 offset:52224
	ds_read_b128 v[206:209], v235 offset:53248
	ds_read_b128 v[210:213], v235 offset:54272
	ds_read_b128 v[214:217], v235 offset:55296
	ds_read_b128 v[218:221], v235 offset:56320
	global_load_lds_dwordx4 v[162:163], off
	s_add_i32 m0, s24, 0x2000
	s_add_u32 s22, s22, 0xb0080
	v_lshl_add_u64 v[162:163], v[164:165], 0, s[10:11]
	s_addc_u32 s23, s23, 0
	s_add_i32 s24, s78, s27
	global_load_lds_dwordx4 v[162:163], off
	v_lshl_add_u64 v[162:163], s[22:23], 0, v[192:193]
	s_mov_b32 m0, s24
	s_nop 0
	global_load_lds_dwordx4 v[162:163], off
	v_lshl_add_u64 v[162:163], s[22:23], 0, v[196:197]
	s_add_i32 m0, s24, 0x2000
	s_nop 0
	global_load_lds_dwordx4 v[162:163], off
	v_lshl_add_u64 v[162:163], v[166:167], 0, s[10:11]
	s_mov_b32 m0, s36
	s_nop 0
	global_load_lds_dwordx4 v[162:163], off
	v_lshl_add_u64 v[162:163], v[168:169], 0, s[10:11]
	s_mov_b32 m0, s37
	s_nop 0
	global_load_lds_dwordx4 v[162:163], off
	s_waitcnt vmcnt(8)
	s_waitcnt lgkmcnt(0)
	s_setprio 1
	s_barrier
	v_mfma_scale_f32_16x16x128_f8f6f4 v[94:97], v[2:9], v[170:177], v[94:97], v229, v229 op_sel_hi:[0,0,0]
	v_mfma_scale_f32_16x16x128_f8f6f4 v[90:93], v[10:17], v[170:177], v[90:93], v229, v229 op_sel_hi:[0,0,0]
	v_mfma_scale_f32_16x16x128_f8f6f4 v[86:89], v[2:9], v[178:185], v[86:89], v229, v229 op_sel_hi:[0,0,0]
	v_mfma_scale_f32_16x16x128_f8f6f4 v[78:81], v[10:17], v[178:185], v[78:81], v229, v229 op_sel_hi:[0,0,0]
	v_mfma_scale_f32_16x16x128_f8f6f4 v[70:73], v[2:9], v[206:213], v[70:73], v229, v229 op_sel_hi:[0,0,0]
	v_mfma_scale_f32_16x16x128_f8f6f4 v[62:65], v[10:17], v[206:213], v[62:65], v229, v229 op_sel_hi:[0,0,0]
	v_mfma_scale_f32_16x16x128_f8f6f4 v[54:57], v[2:9], v[214:221], v[54:57], v229, v229 op_sel_hi:[0,0,0]
	v_mfma_scale_f32_16x16x128_f8f6f4 v[46:49], v[10:17], v[214:221], v[46:49], v229, v229 op_sel_hi:[0,0,0]
	s_setprio 0
	s_setprio 1
	v_mfma_scale_f32_16x16x128_f8f6f4 v[82:85], v[18:25], v[170:177], v[82:85], v229, v229 op_sel_hi:[0,0,0]
	v_mfma_scale_f32_16x16x128_f8f6f4 v[74:77], v[26:33], v[170:177], v[74:77], v229, v229 op_sel_hi:[0,0,0]
	v_mfma_scale_f32_16x16x128_f8f6f4 v[66:69], v[18:25], v[178:185], v[66:69], v229, v229 op_sel_hi:[0,0,0]
	v_mfma_scale_f32_16x16x128_f8f6f4 v[58:61], v[26:33], v[178:185], v[58:61], v229, v229 op_sel_hi:[0,0,0]
	v_mfma_scale_f32_16x16x128_f8f6f4 v[50:53], v[18:25], v[206:213], v[50:53], v229, v229 op_sel_hi:[0,0,0]
	v_mfma_scale_f32_16x16x128_f8f6f4 v[42:45], v[26:33], v[206:213], v[42:45], v229, v229 op_sel_hi:[0,0,0]
	v_mfma_scale_f32_16x16x128_f8f6f4 v[38:41], v[18:25], v[214:221], v[38:41], v229, v229 op_sel_hi:[0,0,0]
	v_mfma_scale_f32_16x16x128_f8f6f4 v[34:37], v[26:33], v[214:221], v[34:37], v229, v229 op_sel_hi:[0,0,0]
	s_barrier
	s_setprio 0
	s_add_u32 s20, s20, 0x100
	s_addc_u32 s21, s21, 0
	s_add_u32 s72, s72, 0x100
	s_addc_u32 s73, s73, 0
	s_cmp_ge_u32 s74, s4
	s_mov_b32 s24, s74
	s_cbranch_scc0 .LBB0_1695
	s_nop 15
	s_nop 15
	s_nop 15
	s_nop 15
	s_nop 15
	s_and_b64 vcc, exec, s[12:13]
	s_cbranch_vccz .LBB0_1698
	s_barrier

; #define PG8_STAGE(bufoff, gbase, voff) do { _Pragma("unroll") for (int _i = 0; _i < 2; ++_i) \
;         __builtin_amdgcn_global_load_lds((const unsigned*)((const char*)(gbase) + (voff)[_i]), (PG8_LAS unsigned*)(lds + (bufoff) + ldsw + _i * 8192), 16, 0, 0); } while (0)
; #define PG8_WAIT_V(n) asm volatile("s_waitcnt vmcnt(" #n ")" ::: "memory")
; #define PG8_WAIT_L(n) asm volatile("s_waitcnt lgkmcnt(" #n ")" ::: "memory")
; #define PG8_BAR __builtin_amdgcn_s_barrier()
; #define PG8_SCHED __builtin_amdgcn_sched_barrier(0)
;     __device__ __forceinline__ int nt(const pg8::Unit& u) const { return u.kind == 0 ? ntiles : q_nt(u.kind - 1); }
; template <class Epi, class Sched, bool ALIGN_EPI = true, bool SP2 = true>
; __device__ __forceinline__ void gemm_phase(PG8_LAS unsigned char* lds, const int K  , const Sched& S, const Epi& E) {
;     ...
;         for (int t = 0; t < nt; t += 2) {
;             const bool last = (t == nt - 2);
;             const char* a1 = cA + (size_t)(t + 1) * kstep;
;             const char* a2 = last ? nA : cA + (size_t)(t + 2) * kstep; const char* b2 = last ? nB : cB + (size_t)(t + 2) * kstep;
;             const char* a3 = a2 + kstep; const char* b3 = b2 + kstep;
;             if constexpr (SP2) {
;             PG8_LDB(B0, 0, 0); PG8_LDB(B1, 0, 1); PG8_SCHED; PG8_LDA(At, 0, 0); PG8_STAGE(PG8_SA(1, 1), a1 + hstep, voffA);
;             PG8_WAIT_V(8); PG8_WAIT_L(0); PG8_BAR; PG8_MMA(0, 0, At, B0); PG8_MMA(0, 1, At, B1); PG8_BAR; PG8_SCHED;
;             PG8_LDA(At, 0, 1); PG8_STAGE(PG8_SB(0, 0), b2, voffB); PG8_STAGE(PG8_SB(0, 1), b2 + hstep, voffB); PG8_STAGE(PG8_SA(0, 0), a2, voffA);
.LBB0_1847:
	ds_read_b128 v[130:133], v176
	ds_read_b128 v[134:137], v176 offset:1024
	ds_read_b128 v[138:141], v176 offset:2048
	ds_read_b128 v[142:145], v176 offset:3072
	ds_read_b128 v[168:171], v177
	ds_read_b128 v[184:187], v177 offset:1024
	ds_read_b128 v[188:191], v177 offset:2048
	ds_read_b128 v[192:195], v177 offset:3072
	s_add_u32 s22, s0, 0xfff80080
	s_addc_u32 s23, s1, -1
	s_cmp_eq_u32 s51, 28
	s_cselect_b32 s25, s7, s23
	s_cselect_b32 s24, s47, s22
	s_cselect_b32 s23, s11, s50
	s_cselect_b32 s22, s48, s49
	v_lshl_add_u64 v[230:231], s[0:1], 0, v[160:161]
	s_add_i32 m0, s27, 0xc000
	ds_read_b128 v[196:199], v178
	ds_read_b128 v[200:203], v178 offset:1024
	ds_read_b128 v[204:207], v178 offset:2048
	ds_read_b128 v[208:211], v178 offset:3072
	ds_read_b128 v[212:215], v178 offset:4096
	ds_read_b128 v[216:219], v178 offset:5120
	ds_read_b128 v[220:223], v178 offset:6144
	ds_read_b128 v[224:227], v178 offset:7168
	global_load_lds_dwordx4 v[230:231], off
	v_lshl_add_u64 v[230:231], s[0:1], 0, v[162:163]
	s_add_i32 m0, s27, 0xe000
	s_nop 0
	global_load_lds_dwordx4 v[230:231], off
	s_waitcnt vmcnt(8)
	s_waitcnt lgkmcnt(0)
	s_setprio 1
	s_barrier
	v_mfma_f32_16x16x32_bf16 v[126:129], v[130:133], v[196:199], v[126:129]
	v_mfma_f32_16x16x32_bf16 v[122:125], v[138:141], v[196:199], v[122:125]
	v_mfma_f32_16x16x32_bf16 v[110:113], v[130:133], v[204:207], v[110:113]
	v_mfma_f32_16x16x32_bf16 v[106:109], v[138:141], v[204:207], v[106:109]
	v_mfma_f32_16x16x32_bf16 v[94:97], v[130:133], v[212:215], v[94:97]
	v_mfma_f32_16x16x32_bf16 v[90:93], v[138:141], v[212:215], v[90:93]
	v_mfma_f32_16x16x32_bf16 v[78:81], v[130:133], v[220:223], v[78:81]
	v_mfma_f32_16x16x32_bf16 v[74:77], v[138:141], v[220:223], v[74:77]
	v_mfma_f32_16x16x32_bf16 v[126:129], v[134:137], v[200:203], v[126:129]
	v_mfma_f32_16x16x32_bf16 v[122:125], v[142:145], v[200:203], v[122:125]
	v_mfma_f32_16x16x32_bf16 v[110:113], v[134:137], v[208:211], v[110:113]
	v_mfma_f32_16x16x32_bf16 v[106:109], v[142:145], v[208:211], v[106:109]
	v_mfma_f32_16x16x32_bf16 v[94:97], v[134:137], v[216:219], v[94:97]
	v_mfma_f32_16x16x32_bf16 v[90:93], v[142:145], v[216:219], v[90:93]
	v_mfma_f32_16x16x32_bf16 v[78:81], v[134:137], v[224:227], v[78:81]
	v_mfma_f32_16x16x32_bf16 v[74:77], v[142:145], v[224:227], v[74:77]
	s_setprio 0
	s_setprio 1
	v_mfma_f32_16x16x32_bf16 v[118:121], v[168:171], v[196:199], v[118:121]
	v_mfma_f32_16x16x32_bf16 v[114:117], v[188:191], v[196:199], v[114:117]
	v_mfma_f32_16x16x32_bf16 v[102:105], v[168:171], v[204:207], v[102:105]
	v_mfma_f32_16x16x32_bf16 v[98:101], v[188:191], v[204:207], v[98:101]
	v_mfma_f32_16x16x32_bf16 v[86:89], v[168:171], v[212:215], v[86:89]
	v_mfma_f32_16x16x32_bf16 v[82:85], v[188:191], v[212:215], v[82:85]
	v_mfma_f32_16x16x32_bf16 v[70:73], v[168:171], v[220:223], v[70:73]
	v_mfma_f32_16x16x32_bf16 v[66:69], v[188:191], v[220:223], v[66:69]
	v_mfma_f32_16x16x32_bf16 v[118:121], v[184:187], v[200:203], v[118:121]
	v_mfma_f32_16x16x32_bf16 v[114:117], v[192:195], v[200:203], v[114:117]
	v_mfma_f32_16x16x32_bf16 v[102:105], v[184:187], v[208:211], v[102:105]
	v_mfma_f32_16x16x32_bf16 v[98:101], v[192:195], v[208:211], v[98:101]
	v_mfma_f32_16x16x32_bf16 v[86:89], v[184:187], v[216:219], v[86:89]
	v_mfma_f32_16x16x32_bf16 v[82:85], v[192:195], v[216:219], v[82:85]
	v_mfma_f32_16x16x32_bf16 v[70:73], v[184:187], v[224:227], v[70:73]
	v_mfma_f32_16x16x32_bf16 v[66:69], v[192:195], v[224:227], v[66:69]
	s_barrier
	s_setprio 0
	s_add_i32 s68, s39, s26
	v_lshl_add_u64 v[230:231], s[22:23], 0, v[150:151]
	s_mov_b32 m0, s68
	ds_read_b128 v[196:199], v178 offset:16384
	ds_read_b128 v[200:203], v178 offset:17408
	ds_read_b128 v[204:207], v178 offset:18432
	ds_read_b128 v[208:211], v178 offset:19456
	ds_read_b128 v[212:215], v178 offset:20480
	ds_read_b128 v[216:219], v178 offset:21504
	ds_read_b128 v[220:223], v178 offset:22528
	ds_read_b128 v[224:227], v178 offset:23552
	global_load_lds_dwordx4 v[230:231], off
	s_add_i32 m0, s68, 0x2000
	s_add_u32 s68, s22, 0x80000
	v_lshl_add_u64 v[232:233], s[22:23], 0, v[154:155]
	s_addc_u32 s69, s23, 0
	s_add_i32 s70, s40, s26
	global_load_lds_dwordx4 v[232:233], off
	v_lshl_add_u64 v[234:235], s[68:69], 0, v[150:151]
	s_mov_b32 m0, s70
	v_lshl_add_u64 v[236:237], s[24:25], 0, v[152:153]
	global_load_lds_dwordx4 v[234:235], off
	v_lshl_add_u64 v[234:235], s[68:69], 0, v[154:155]
	s_add_i32 m0, s70, 0x2000
	s_nop 0
	global_load_lds_dwordx4 v[234:235], off
	v_lshl_add_u64 v[234:235], s[24:25], 0, v[148:149]
	s_mov_b32 m0, s27
	s_nop 0
	global_load_lds_dwordx4 v[234:235], off
	s_mov_b32 m0, s28
	s_nop 0
	global_load_lds_dwordx4 v[236:237], off
	s_waitcnt vmcnt(8)
	s_waitcnt lgkmcnt(0)
	s_setprio 1
	s_barrier
; #define PG8_STAGE(bufoff, gbase, voff) do { _Pragma("unroll") for (int _i = 0; _i < 2; ++_i) \
;         __builtin_amdgcn_global_load_lds((const unsigned*)((const char*)(gbase) + (voff)[_i]), (PG8_LAS unsigned*)(lds + (bufoff) + ldsw + _i * 8192), 16, 0, 0); } while (0)
; #define PG8_WAIT_V(n) asm volatile("s_waitcnt vmcnt(" #n ")" ::: "memory")
; #define PG8_WAIT_L(n) asm volatile("s_waitcnt lgkmcnt(" #n ")" ::: "memory")
; #define PG8_BAR __builtin_amdgcn_s_barrier()
; #define PG8_SCHED __builtin_amdgcn_sched_barrier(0)
; template <class Epi, class Sched, bool ALIGN_EPI = true, bool SP2 = true>
; __device__ __forceinline__ void gemm_phase(PG8_LAS unsigned char* lds, const int K  , const Sched& S, const Epi& E) {
;     ...
;             PG8_WAIT_V(8); PG8_WAIT_L(0); PG8_BAR; PG8_MMA(1, 0, At, B0); PG8_MMA(1, 1, At, B1); PG8_BAR; PG8_SCHED;
;             PG8_LDB(B0, 1, 0); PG8_LDB(B1, 1, 1); PG8_SCHED; PG8_LDA(At, 1, 0); PG8_STAGE(PG8_SA(0, 1), a2 + hstep, voffA);
;             PG8_WAIT_V(8); PG8_WAIT_L(0); PG8_BAR; PG8_MMA(0, 0, At, B0); PG8_MMA(0, 1, At, B1); PG8_BAR; PG8_SCHED;
	v_mfma_f32_16x16x32_bf16 v[62:65], v[130:133], v[196:199], v[62:65]
	v_mfma_f32_16x16x32_bf16 v[58:61], v[138:141], v[196:199], v[58:61]
	v_mfma_f32_16x16x32_bf16 v[46:49], v[130:133], v[204:207], v[46:49]
	v_mfma_f32_16x16x32_bf16 v[42:45], v[138:141], v[204:207], v[42:45]
	v_mfma_f32_16x16x32_bf16 v[30:33], v[130:133], v[212:215], v[30:33]
	v_mfma_f32_16x16x32_bf16 v[26:29], v[138:141], v[212:215], v[26:29]
	v_mfma_f32_16x16x32_bf16 v[14:17], v[130:133], v[220:223], v[14:17]
	v_mfma_f32_16x16x32_bf16 v[10:13], v[138:141], v[220:223], v[10:13]
	v_mfma_f32_16x16x32_bf16 v[62:65], v[134:137], v[200:203], v[62:65]
	v_mfma_f32_16x16x32_bf16 v[58:61], v[142:145], v[200:203], v[58:61]
	v_mfma_f32_16x16x32_bf16 v[46:49], v[134:137], v[208:211], v[46:49]
	v_mfma_f32_16x16x32_bf16 v[42:45], v[142:145], v[208:211], v[42:45]
	v_mfma_f32_16x16x32_bf16 v[30:33], v[134:137], v[216:219], v[30:33]
	v_mfma_f32_16x16x32_bf16 v[26:29], v[142:145], v[216:219], v[26:29]
	v_mfma_f32_16x16x32_bf16 v[14:17], v[134:137], v[224:227], v[14:17]
	v_mfma_f32_16x16x32_bf16 v[10:13], v[142:145], v[224:227], v[10:13]
	s_setprio 0
	s_setprio 1
	v_mfma_f32_16x16x32_bf16 v[54:57], v[168:171], v[196:199], v[54:57]
	v_mfma_f32_16x16x32_bf16 v[50:53], v[188:191], v[196:199], v[50:53]
	v_mfma_f32_16x16x32_bf16 v[38:41], v[168:171], v[204:207], v[38:41]
	v_mfma_f32_16x16x32_bf16 v[34:37], v[188:191], v[204:207], v[34:37]
	v_mfma_f32_16x16x32_bf16 v[22:25], v[168:171], v[212:215], v[22:25]
	v_mfma_f32_16x16x32_bf16 v[18:21], v[188:191], v[212:215], v[18:21]
	v_mfma_f32_16x16x32_bf16 v[6:9], v[168:171], v[220:223], v[6:9]
	v_mfma_f32_16x16x32_bf16 v[2:5], v[188:191], v[220:223], v[2:5]
	v_mfma_f32_16x16x32_bf16 v[54:57], v[184:187], v[200:203], v[54:57]
	v_mfma_f32_16x16x32_bf16 v[50:53], v[192:195], v[200:203], v[50:53]
	v_mfma_f32_16x16x32_bf16 v[38:41], v[184:187], v[208:211], v[38:41]
	v_mfma_f32_16x16x32_bf16 v[34:37], v[192:195], v[208:211], v[34:37]
	v_mfma_f32_16x16x32_bf16 v[22:25], v[184:187], v[216:219], v[22:25]
	v_mfma_f32_16x16x32_bf16 v[18:21], v[192:195], v[216:219], v[18:21]
	v_mfma_f32_16x16x32_bf16 v[6:9], v[184:187], v[224:227], v[6:9]
	v_mfma_f32_16x16x32_bf16 v[2:5], v[192:195], v[224:227], v[2:5]
	s_barrier
	s_setprio 0
	s_add_i32 s68, 0, 0x18000
	s_add_i32 s69, 0, 0x1c000
	v_add_u32_e32 v142, s68, v172
	v_add_u32_e32 v192, s69, v172
	ds_read_b128 v[130:133], v142
	ds_read_b128 v[134:137], v142 offset:1024
	ds_read_b128 v[138:141], v142 offset:2048
	ds_read_b128 v[142:145], v142 offset:3072
	ds_read_b128 v[168:171], v192
	ds_read_b128 v[184:187], v192 offset:1024
	ds_read_b128 v[188:191], v192 offset:2048
	ds_read_b128 v[192:195], v192 offset:3072
	s_add_u32 s24, s24, 0x80000
	s_addc_u32 s25, s25, 0
	s_mov_b32 m0, s29
	v_lshl_add_u64 v[238:239], s[24:25], 0, v[148:149]
	ds_read_b128 v[196:199], v178 offset:32768
	ds_read_b128 v[200:203], v178 offset:33792
	ds_read_b128 v[204:207], v178 offset:34816
	ds_read_b128 v[208:211], v178 offset:35840
	ds_read_b128 v[212:215], v178 offset:36864
	ds_read_b128 v[216:219], v178 offset:37888
	ds_read_b128 v[220:223], v178 offset:38912
	ds_read_b128 v[224:227], v178 offset:39936
	global_load_lds_dwordx4 v[238:239], off
	v_lshl_add_u64 v[238:239], s[24:25], 0, v[152:153]
	s_mov_b32 m0, s30
	s_nop 0
	global_load_lds_dwordx4 v[238:239], off
	s_waitcnt vmcnt(8)
	s_waitcnt lgkmcnt(0)
	s_setprio 1
	s_barrier
	v_mfma_f32_16x16x32_bf16 v[126:129], v[130:133], v[196:199], v[126:129]
	v_mfma_f32_16x16x32_bf16 v[122:125], v[138:141], v[196:199], v[122:125]
	v_mfma_f32_16x16x32_bf16 v[110:113], v[130:133], v[204:207], v[110:113]
	v_mfma_f32_16x16x32_bf16 v[106:109], v[138:141], v[204:207], v[106:109]
	v_mfma_f32_16x16x32_bf16 v[94:97], v[130:133], v[212:215], v[94:97]
	v_mfma_f32_16x16x32_bf16 v[90:93], v[138:141], v[212:215], v[90:93]
	v_mfma_f32_16x16x32_bf16 v[78:81], v[130:133], v[220:223], v[78:81]
	v_mfma_f32_16x16x32_bf16 v[74:77], v[138:141], v[220:223], v[74:77]
	v_mfma_f32_16x16x32_bf16 v[126:129], v[134:137], v[200:203], v[126:129]
	v_mfma_f32_16x16x32_bf16 v[122:125], v[142:145], v[200:203], v[122:125]
	v_mfma_f32_16x16x32_bf16 v[110:113], v[134:137], v[208:211], v[110:113]
	v_mfma_f32_16x16x32_bf16 v[106:109], v[142:145], v[208:211], v[106:109]
	v_mfma_f32_16x16x32_bf16 v[94:97], v[134:137], v[216:219], v[94:97]
	v_mfma_f32_16x16x32_bf16 v[90:93], v[142:145], v[216:219], v[90:93]
	v_mfma_f32_16x16x32_bf16 v[78:81], v[134:137], v[224:227], v[78:81]
	v_mfma_f32_16x16x32_bf16 v[74:77], v[142:145], v[224:227], v[74:77]
	s_setprio 0
	s_setprio 1
	v_mfma_f32_16x16x32_bf16 v[118:121], v[168:171], v[196:199], v[118:121]
	v_mfma_f32_16x16x32_bf16 v[114:117], v[188:191], v[196:199], v[114:117]
	v_mfma_f32_16x16x32_bf16 v[102:105], v[168:171], v[204:207], v[102:105]
	v_mfma_f32_16x16x32_bf16 v[98:101], v[188:191], v[204:207], v[98:101]
	v_mfma_f32_16x16x32_bf16 v[86:89], v[168:171], v[212:215], v[86:89]
	v_mfma_f32_16x16x32_bf16 v[82:85], v[188:191], v[212:215], v[82:85]
	v_mfma_f32_16x16x32_bf16 v[70:73], v[168:171], v[220:223], v[70:73]
	v_mfma_f32_16x16x32_bf16 v[66:69], v[188:191], v[220:223], v[66:69]
	v_mfma_f32_16x16x32_bf16 v[118:121], v[184:187], v[200:203], v[118:121]
	v_mfma_f32_16x16x32_bf16 v[114:117], v[192:195], v[200:203], v[114:117]
	v_mfma_f32_16x16x32_bf16 v[102:105], v[184:187], v[208:211], v[102:105]
	v_mfma_f32_16x16x32_bf16 v[98:101], v[192:195], v[208:211], v[98:101]
	v_mfma_f32_16x16x32_bf16 v[86:89], v[184:187], v[216:219], v[86:89]
	v_mfma_f32_16x16x32_bf16 v[82:85], v[192:195], v[216:219], v[82:85]
	v_mfma_f32_16x16x32_bf16 v[70:73], v[184:187], v[224:227], v[70:73]
	v_mfma_f32_16x16x32_bf16 v[66:69], v[192:195], v[224:227], v[66:69]
	s_barrier
; #define PG8_STAGE(bufoff, gbase, voff) do { _Pragma("unroll") for (int _i = 0; _i < 2; ++_i) \
;         __builtin_amdgcn_global_load_lds((const unsigned*)((const char*)(gbase) + (voff)[_i]), (PG8_LAS unsigned*)(lds + (bufoff) + ldsw + _i * 8192), 16, 0, 0); } while (0)
; #define PG8_WAIT_V(n) asm volatile("s_waitcnt vmcnt(" #n ")" ::: "memory")
; #define PG8_WAIT_L(n) asm volatile("s_waitcnt lgkmcnt(" #n ")" ::: "memory")
; #define PG8_BAR __builtin_amdgcn_s_barrier()
; #define PG8_SCHED __builtin_amdgcn_sched_barrier(0)
; template <class Epi, class Sched, bool ALIGN_EPI = true, bool SP2 = true>
; __device__ __forceinline__ void gemm_phase(PG8_LAS unsigned char* lds, const int K  , const Sched& S, const Epi& E) {
;     ...
;             PG8_WAIT_V(8); PG8_WAIT_L(0); PG8_BAR; PG8_MMA(0, 0, At, B0); PG8_MMA(0, 1, At, B1); PG8_BAR; PG8_SCHED;
;             PG8_LDA(At, 1, 1); PG8_STAGE(PG8_SB(1, 0), b3, voffB); PG8_STAGE(PG8_SB(1, 1), b3 + hstep, voffB); PG8_STAGE(PG8_SA(1, 0), a3, voffA);
;             PG8_WAIT_V(8); PG8_WAIT_L(0); PG8_BAR; PG8_MMA(1, 0, At, B0); PG8_MMA(1, 1, At, B1); PG8_BAR; PG8_SCHED;
;     ...
;         if constexpr (Epi::FP8) asm volatile("s_nop 15\n\ts_nop 15\n\ts_nop 15\n\ts_nop 15\n\ts_nop 15" ::: "memory");
;         if constexpr (ALIGN_EPI) { if (wr == 0) PG8_BAR; }
	s_setprio 0
	s_add_i32 s24, s68, s26
	v_lshl_add_u64 v[230:231], v[230:231], 0, s[4:5]
	s_mov_b32 m0, s24
	ds_read_b128 v[196:199], v178 offset:49152
	ds_read_b128 v[200:203], v178 offset:50176
	ds_read_b128 v[204:207], v178 offset:51200
	ds_read_b128 v[208:211], v178 offset:52224
	ds_read_b128 v[212:215], v178 offset:53248
	ds_read_b128 v[216:219], v178 offset:54272
	ds_read_b128 v[220:223], v178 offset:55296
	ds_read_b128 v[224:227], v178 offset:56320
	global_load_lds_dwordx4 v[230:231], off
	s_add_i32 m0, s24, 0x2000
	s_add_u32 s22, s22, 0x80080
	v_lshl_add_u64 v[230:231], v[232:233], 0, s[4:5]
	s_addc_u32 s23, s23, 0
	s_add_i32 s24, s69, s26
	global_load_lds_dwordx4 v[230:231], off
	v_lshl_add_u64 v[230:231], s[22:23], 0, v[150:151]
	s_mov_b32 m0, s24
	s_nop 0
	global_load_lds_dwordx4 v[230:231], off
	v_lshl_add_u64 v[230:231], s[22:23], 0, v[154:155]
	s_add_i32 m0, s24, 0x2000
	s_nop 0
	global_load_lds_dwordx4 v[230:231], off
	v_lshl_add_u64 v[230:231], v[234:235], 0, s[4:5]
	s_mov_b32 m0, s35
	s_nop 0
	global_load_lds_dwordx4 v[230:231], off
	v_lshl_add_u64 v[230:231], v[236:237], 0, s[4:5]
	s_mov_b32 m0, s36
	s_nop 0
	global_load_lds_dwordx4 v[230:231], off
	s_waitcnt vmcnt(8)
	s_waitcnt lgkmcnt(0)
	s_setprio 1
	s_barrier
	v_mfma_f32_16x16x32_bf16 v[62:65], v[130:133], v[196:199], v[62:65]
	v_mfma_f32_16x16x32_bf16 v[58:61], v[138:141], v[196:199], v[58:61]
	v_mfma_f32_16x16x32_bf16 v[46:49], v[130:133], v[204:207], v[46:49]
	v_mfma_f32_16x16x32_bf16 v[42:45], v[138:141], v[204:207], v[42:45]
	v_mfma_f32_16x16x32_bf16 v[30:33], v[130:133], v[212:215], v[30:33]
	v_mfma_f32_16x16x32_bf16 v[26:29], v[138:141], v[212:215], v[26:29]
	v_mfma_f32_16x16x32_bf16 v[14:17], v[130:133], v[220:223], v[14:17]
	v_mfma_f32_16x16x32_bf16 v[10:13], v[138:141], v[220:223], v[10:13]
	v_mfma_f32_16x16x32_bf16 v[62:65], v[134:137], v[200:203], v[62:65]
	v_mfma_f32_16x16x32_bf16 v[58:61], v[142:145], v[200:203], v[58:61]
	v_mfma_f32_16x16x32_bf16 v[46:49], v[134:137], v[208:211], v[46:49]
	v_mfma_f32_16x16x32_bf16 v[42:45], v[142:145], v[208:211], v[42:45]
	v_mfma_f32_16x16x32_bf16 v[30:33], v[134:137], v[216:219], v[30:33]
	v_mfma_f32_16x16x32_bf16 v[26:29], v[142:145], v[216:219], v[26:29]
	v_mfma_f32_16x16x32_bf16 v[14:17], v[134:137], v[224:227], v[14:17]
	v_mfma_f32_16x16x32_bf16 v[10:13], v[142:145], v[224:227], v[10:13]
	s_setprio 0
	s_setprio 1
	v_mfma_f32_16x16x32_bf16 v[54:57], v[168:171], v[196:199], v[54:57]
	v_mfma_f32_16x16x32_bf16 v[50:53], v[188:191], v[196:199], v[50:53]
	v_mfma_f32_16x16x32_bf16 v[38:41], v[168:171], v[204:207], v[38:41]
	v_mfma_f32_16x16x32_bf16 v[34:37], v[188:191], v[204:207], v[34:37]
	v_mfma_f32_16x16x32_bf16 v[22:25], v[168:171], v[212:215], v[22:25]
	v_mfma_f32_16x16x32_bf16 v[18:21], v[188:191], v[212:215], v[18:21]
	v_mfma_f32_16x16x32_bf16 v[6:9], v[168:171], v[220:223], v[6:9]
	v_mfma_f32_16x16x32_bf16 v[2:5], v[188:191], v[220:223], v[2:5]
	v_mfma_f32_16x16x32_bf16 v[54:57], v[184:187], v[200:203], v[54:57]
	v_mfma_f32_16x16x32_bf16 v[50:53], v[192:195], v[200:203], v[50:53]
	v_mfma_f32_16x16x32_bf16 v[38:41], v[184:187], v[208:211], v[38:41]
	v_mfma_f32_16x16x32_bf16 v[34:37], v[192:195], v[208:211], v[34:37]
	v_mfma_f32_16x16x32_bf16 v[22:25], v[184:187], v[216:219], v[22:25]
	v_mfma_f32_16x16x32_bf16 v[18:21], v[192:195], v[216:219], v[18:21]
	v_mfma_f32_16x16x32_bf16 v[6:9], v[184:187], v[224:227], v[6:9]
	v_mfma_f32_16x16x32_bf16 v[2:5], v[192:195], v[224:227], v[2:5]
	s_barrier
	s_setprio 0
	s_add_i32 s51, s51, 2
	s_add_u32 s0, s0, 0x100
	s_addc_u32 s1, s1, 0
	s_add_u32 s49, s49, 0x100
	s_addc_u32 s50, s50, 0
	s_cmp_gt_u32 s51, 29
	s_cbranch_scc0 .LBB0_1847
	s_and_b64 vcc, exec, s[8:9]
	s_cbranch_vccz .LBB0_1850
	s_barrier

; #define PG8_STAGE(bufoff, gbase, voff) do { _Pragma("unroll") for (int _i = 0; _i < 2; ++_i) \
;         __builtin_amdgcn_global_load_lds((const unsigned*)((const char*)(gbase) + (voff)[_i]), (PG8_LAS unsigned*)(lds + (bufoff) + ldsw + _i * 8192), 16, 0, 0); } while (0)
; #define PG8_WAIT_V(n) asm volatile("s_waitcnt vmcnt(" #n ")" ::: "memory")
; #define PG8_WAIT_L(n) asm volatile("s_waitcnt lgkmcnt(" #n ")" ::: "memory")
; #define PG8_BAR __builtin_amdgcn_s_barrier()
; #define PG8_SCHED __builtin_amdgcn_sched_barrier(0)
;     __device__ __forceinline__ int nt(const pg8::Unit& u) const { return u.kind == 0 ? ntiles : q_nt(u.kind - 1); }
; template <class Epi, class Sched, bool ALIGN_EPI = true, bool SP2 = true>
; __device__ __forceinline__ void gemm_phase(PG8_LAS unsigned char* lds, const int K  , const Sched& S, const Epi& E) {
;     ...
;         for (int t = 0; t < nt; t += 2) {
;             const bool last = (t == nt - 2);
;             const char* a1 = cA + (size_t)(t + 1) * kstep;
;             const char* a2 = last ? nA : cA + (size_t)(t + 2) * kstep; const char* b2 = last ? nB : cB + (size_t)(t + 2) * kstep;
;             const char* a3 = a2 + kstep; const char* b3 = b2 + kstep;
;             if constexpr (SP2) {
;             PG8_LDB(B0, 0, 0); PG8_LDB(B1, 0, 1); PG8_SCHED; PG8_LDA(At, 0, 0); PG8_STAGE(PG8_SA(1, 1), a1 + hstep, voffA);
;             PG8_WAIT_V(8); PG8_WAIT_L(0); PG8_BAR; PG8_MMA(0, 0, At, B0); PG8_MMA(0, 1, At, B1); PG8_BAR; PG8_SCHED;
;             PG8_LDA(At, 0, 1); PG8_STAGE(PG8_SB(0, 0), b2, voffB); PG8_STAGE(PG8_SB(0, 1), b2 + hstep, voffB); PG8_STAGE(PG8_SA(0, 0), a2, voffA);
.LBB0_2296:
	ds_read_b128 v[130:133], v203
	ds_read_b128 v[134:137], v203 offset:1024
	ds_read_b128 v[138:141], v203 offset:2048
	ds_read_b128 v[142:145], v203 offset:3072
	ds_read_b128 v[146:149], v204
	ds_read_b128 v[150:153], v204 offset:1024
	ds_read_b128 v[154:157], v204 offset:2048
	ds_read_b128 v[158:161], v204 offset:3072
	s_add_u32 s22, s20, 0xfff80080
	s_addc_u32 s23, s21, -1
	s_cmp_eq_u32 s54, 28
	s_cselect_b32 s25, s13, s23
	s_cselect_b32 s24, s50, s22
	s_cselect_b32 s23, s11, s53
	s_cselect_b32 s22, s51, s52
	v_lshl_add_u64 v[198:199], s[20:21], 0, v[190:191]
	s_add_i32 m0, s19, 0xc000
	ds_read_b128 v[162:165], v205
	ds_read_b128 v[166:169], v205 offset:1024
	ds_read_b128 v[170:173], v205 offset:2048
	ds_read_b128 v[174:177], v205 offset:3072
	ds_read_b128 v[178:181], v205 offset:4096
	ds_read_b128 v[206:209], v205 offset:5120
	ds_read_b128 v[210:213], v205 offset:6144
	ds_read_b128 v[214:217], v205 offset:7168
	global_load_lds_dwordx4 v[198:199], off
	v_lshl_add_u64 v[198:199], s[20:21], 0, v[192:193]
	s_add_i32 m0, s19, 0xe000
	s_nop 0
	global_load_lds_dwordx4 v[198:199], off
	s_waitcnt vmcnt(8)
	s_waitcnt lgkmcnt(0)
	s_setprio 1
	s_barrier
	v_mfma_f32_16x16x32_bf16 v[126:129], v[130:133], v[162:165], v[126:129]
	v_mfma_f32_16x16x32_bf16 v[122:125], v[138:141], v[162:165], v[122:125]
	v_mfma_f32_16x16x32_bf16 v[114:117], v[130:133], v[170:173], v[114:117]
	v_mfma_f32_16x16x32_bf16 v[106:109], v[138:141], v[170:173], v[106:109]
	v_mfma_f32_16x16x32_bf16 v[98:101], v[130:133], v[178:181], v[98:101]
	v_mfma_f32_16x16x32_bf16 v[90:93], v[138:141], v[178:181], v[90:93]
	v_mfma_f32_16x16x32_bf16 v[82:85], v[130:133], v[210:213], v[82:85]
	v_mfma_f32_16x16x32_bf16 v[74:77], v[138:141], v[210:213], v[74:77]
	v_mfma_f32_16x16x32_bf16 v[126:129], v[134:137], v[166:169], v[126:129]
	v_mfma_f32_16x16x32_bf16 v[122:125], v[142:145], v[166:169], v[122:125]
	v_mfma_f32_16x16x32_bf16 v[114:117], v[134:137], v[174:177], v[114:117]
	v_mfma_f32_16x16x32_bf16 v[106:109], v[142:145], v[174:177], v[106:109]
	v_mfma_f32_16x16x32_bf16 v[98:101], v[134:137], v[206:209], v[98:101]
	v_mfma_f32_16x16x32_bf16 v[90:93], v[142:145], v[206:209], v[90:93]
	v_mfma_f32_16x16x32_bf16 v[82:85], v[134:137], v[214:217], v[82:85]
	v_mfma_f32_16x16x32_bf16 v[74:77], v[142:145], v[214:217], v[74:77]
	s_setprio 0
	s_setprio 1
	v_mfma_f32_16x16x32_bf16 v[118:121], v[146:149], v[162:165], v[118:121]
	v_mfma_f32_16x16x32_bf16 v[110:113], v[154:157], v[162:165], v[110:113]
	v_mfma_f32_16x16x32_bf16 v[102:105], v[146:149], v[170:173], v[102:105]
	v_mfma_f32_16x16x32_bf16 v[94:97], v[154:157], v[170:173], v[94:97]
	v_mfma_f32_16x16x32_bf16 v[86:89], v[146:149], v[178:181], v[86:89]
	v_mfma_f32_16x16x32_bf16 v[78:81], v[154:157], v[178:181], v[78:81]
	v_mfma_f32_16x16x32_bf16 v[70:73], v[146:149], v[210:213], v[70:73]
	v_mfma_f32_16x16x32_bf16 v[66:69], v[154:157], v[210:213], v[66:69]
	v_mfma_f32_16x16x32_bf16 v[118:121], v[150:153], v[166:169], v[118:121]
	v_mfma_f32_16x16x32_bf16 v[110:113], v[158:161], v[166:169], v[110:113]
	v_mfma_f32_16x16x32_bf16 v[102:105], v[150:153], v[174:177], v[102:105]
	v_mfma_f32_16x16x32_bf16 v[94:97], v[158:161], v[174:177], v[94:97]
	v_mfma_f32_16x16x32_bf16 v[86:89], v[150:153], v[206:209], v[86:89]
	v_mfma_f32_16x16x32_bf16 v[78:81], v[158:161], v[206:209], v[78:81]
	v_mfma_f32_16x16x32_bf16 v[70:73], v[150:153], v[214:217], v[70:73]
	v_mfma_f32_16x16x32_bf16 v[66:69], v[158:161], v[214:217], v[66:69]
	s_barrier
	s_setprio 0
	s_add_i32 s55, s42, s29
	v_lshl_add_u64 v[198:199], s[22:23], 0, v[184:185]
	s_mov_b32 m0, s55
	ds_read_b128 v[162:165], v205 offset:16384
	ds_read_b128 v[166:169], v205 offset:17408
	ds_read_b128 v[170:173], v205 offset:18432
	ds_read_b128 v[174:177], v205 offset:19456
	ds_read_b128 v[178:181], v205 offset:20480
	ds_read_b128 v[206:209], v205 offset:21504
	ds_read_b128 v[210:213], v205 offset:22528
	ds_read_b128 v[214:217], v205 offset:23552
	global_load_lds_dwordx4 v[198:199], off
	s_add_i32 m0, s55, 0x2000
	s_add_u32 s56, s22, 0x80000
	v_lshl_add_u64 v[218:219], s[22:23], 0, v[188:189]
	s_addc_u32 s57, s23, 0
	s_add_i32 s55, s43, s29
	global_load_lds_dwordx4 v[218:219], off
	v_lshl_add_u64 v[220:221], s[56:57], 0, v[184:185]
	s_mov_b32 m0, s55
	v_lshl_add_u64 v[222:223], s[24:25], 0, v[186:187]
	global_load_lds_dwordx4 v[220:221], off
	v_lshl_add_u64 v[220:221], s[56:57], 0, v[188:189]
	s_add_i32 m0, s55, 0x2000
	s_nop 0
	global_load_lds_dwordx4 v[220:221], off
	v_lshl_add_u64 v[220:221], s[24:25], 0, v[182:183]
	s_mov_b32 m0, s19
	s_nop 0
	global_load_lds_dwordx4 v[220:221], off
	s_mov_b32 m0, s30
	s_nop 0
	global_load_lds_dwordx4 v[222:223], off
	s_waitcnt vmcnt(8)
	s_waitcnt lgkmcnt(0)
	s_setprio 1
	s_barrier
; #define PG8_STAGE(bufoff, gbase, voff) do { _Pragma("unroll") for (int _i = 0; _i < 2; ++_i) \
;         __builtin_amdgcn_global_load_lds((const unsigned*)((const char*)(gbase) + (voff)[_i]), (PG8_LAS unsigned*)(lds + (bufoff) + ldsw + _i * 8192), 16, 0, 0); } while (0)
; #define PG8_WAIT_V(n) asm volatile("s_waitcnt vmcnt(" #n ")" ::: "memory")
; #define PG8_WAIT_L(n) asm volatile("s_waitcnt lgkmcnt(" #n ")" ::: "memory")
; #define PG8_BAR __builtin_amdgcn_s_barrier()
; #define PG8_SCHED __builtin_amdgcn_sched_barrier(0)
; template <class Epi, class Sched, bool ALIGN_EPI = true, bool SP2 = true>
; __device__ __forceinline__ void gemm_phase(PG8_LAS unsigned char* lds, const int K  , const Sched& S, const Epi& E) {
;     ...
;             PG8_WAIT_V(8); PG8_WAIT_L(0); PG8_BAR; PG8_MMA(1, 0, At, B0); PG8_MMA(1, 1, At, B1); PG8_BAR; PG8_SCHED;
;             PG8_LDB(B0, 1, 0); PG8_LDB(B1, 1, 1); PG8_SCHED; PG8_LDA(At, 1, 0); PG8_STAGE(PG8_SA(0, 1), a2 + hstep, voffA);
;             PG8_WAIT_V(8); PG8_WAIT_L(0); PG8_BAR; PG8_MMA(0, 0, At, B0); PG8_MMA(0, 1, At, B1); PG8_BAR; PG8_SCHED;
	v_mfma_f32_16x16x32_bf16 v[62:65], v[130:133], v[162:165], v[62:65]
	v_mfma_f32_16x16x32_bf16 v[58:61], v[138:141], v[162:165], v[58:61]
	v_mfma_f32_16x16x32_bf16 v[50:53], v[130:133], v[170:173], v[50:53]
	v_mfma_f32_16x16x32_bf16 v[42:45], v[138:141], v[170:173], v[42:45]
	v_mfma_f32_16x16x32_bf16 v[34:37], v[130:133], v[178:181], v[34:37]
	v_mfma_f32_16x16x32_bf16 v[26:29], v[138:141], v[178:181], v[26:29]
	v_mfma_f32_16x16x32_bf16 v[18:21], v[130:133], v[210:213], v[18:21]
	v_mfma_f32_16x16x32_bf16 v[10:13], v[138:141], v[210:213], v[10:13]
	v_mfma_f32_16x16x32_bf16 v[62:65], v[134:137], v[166:169], v[62:65]
	v_mfma_f32_16x16x32_bf16 v[58:61], v[142:145], v[166:169], v[58:61]
	v_mfma_f32_16x16x32_bf16 v[50:53], v[134:137], v[174:177], v[50:53]
	v_mfma_f32_16x16x32_bf16 v[42:45], v[142:145], v[174:177], v[42:45]
	v_mfma_f32_16x16x32_bf16 v[34:37], v[134:137], v[206:209], v[34:37]
	v_mfma_f32_16x16x32_bf16 v[26:29], v[142:145], v[206:209], v[26:29]
	v_mfma_f32_16x16x32_bf16 v[18:21], v[134:137], v[214:217], v[18:21]
	v_mfma_f32_16x16x32_bf16 v[10:13], v[142:145], v[214:217], v[10:13]
	s_setprio 0
	s_setprio 1
	v_mfma_f32_16x16x32_bf16 v[54:57], v[146:149], v[162:165], v[54:57]
	v_mfma_f32_16x16x32_bf16 v[46:49], v[154:157], v[162:165], v[46:49]
	v_mfma_f32_16x16x32_bf16 v[38:41], v[146:149], v[170:173], v[38:41]
	v_mfma_f32_16x16x32_bf16 v[30:33], v[154:157], v[170:173], v[30:33]
	v_mfma_f32_16x16x32_bf16 v[22:25], v[146:149], v[178:181], v[22:25]
	v_mfma_f32_16x16x32_bf16 v[14:17], v[154:157], v[178:181], v[14:17]
	v_mfma_f32_16x16x32_bf16 v[6:9], v[146:149], v[210:213], v[6:9]
	v_mfma_f32_16x16x32_bf16 v[2:5], v[154:157], v[210:213], v[2:5]
	v_mfma_f32_16x16x32_bf16 v[54:57], v[150:153], v[166:169], v[54:57]
	v_mfma_f32_16x16x32_bf16 v[46:49], v[158:161], v[166:169], v[46:49]
	v_mfma_f32_16x16x32_bf16 v[38:41], v[150:153], v[174:177], v[38:41]
	v_mfma_f32_16x16x32_bf16 v[30:33], v[158:161], v[174:177], v[30:33]
	v_mfma_f32_16x16x32_bf16 v[22:25], v[150:153], v[206:209], v[22:25]
	v_mfma_f32_16x16x32_bf16 v[14:17], v[158:161], v[206:209], v[14:17]
	v_mfma_f32_16x16x32_bf16 v[6:9], v[150:153], v[214:217], v[6:9]
	v_mfma_f32_16x16x32_bf16 v[2:5], v[158:161], v[214:217], v[2:5]
	s_barrier
	s_setprio 0
	s_add_i32 s55, 0, 0x18000
	s_add_i32 s56, 0, 0x1c000
	v_add_u32_e32 v142, s55, v201
	v_add_u32_e32 v158, s56, v201
	ds_read_b128 v[130:133], v142
	ds_read_b128 v[134:137], v142 offset:1024
	ds_read_b128 v[138:141], v142 offset:2048
	ds_read_b128 v[142:145], v142 offset:3072
	ds_read_b128 v[146:149], v158
	ds_read_b128 v[150:153], v158 offset:1024
	ds_read_b128 v[154:157], v158 offset:2048
	ds_read_b128 v[158:161], v158 offset:3072
	s_add_u32 s24, s24, 0x80000
	s_addc_u32 s25, s25, 0
	s_mov_b32 m0, s31
	v_lshl_add_u64 v[224:225], s[24:25], 0, v[182:183]
	ds_read_b128 v[162:165], v205 offset:32768
	ds_read_b128 v[166:169], v205 offset:33792
	ds_read_b128 v[170:173], v205 offset:34816
	ds_read_b128 v[174:177], v205 offset:35840
	ds_read_b128 v[178:181], v205 offset:36864
	ds_read_b128 v[206:209], v205 offset:37888
	ds_read_b128 v[210:213], v205 offset:38912
	ds_read_b128 v[214:217], v205 offset:39936
	global_load_lds_dwordx4 v[224:225], off
	v_lshl_add_u64 v[224:225], s[24:25], 0, v[186:187]
	s_mov_b32 m0, s33
	s_nop 0
	global_load_lds_dwordx4 v[224:225], off
	s_waitcnt vmcnt(8)
	s_waitcnt lgkmcnt(0)
	s_setprio 1
	s_barrier
	v_mfma_f32_16x16x32_bf16 v[126:129], v[130:133], v[162:165], v[126:129]
	v_mfma_f32_16x16x32_bf16 v[122:125], v[138:141], v[162:165], v[122:125]
	v_mfma_f32_16x16x32_bf16 v[114:117], v[130:133], v[170:173], v[114:117]
	v_mfma_f32_16x16x32_bf16 v[106:109], v[138:141], v[170:173], v[106:109]
	v_mfma_f32_16x16x32_bf16 v[98:101], v[130:133], v[178:181], v[98:101]
	v_mfma_f32_16x16x32_bf16 v[90:93], v[138:141], v[178:181], v[90:93]
	v_mfma_f32_16x16x32_bf16 v[82:85], v[130:133], v[210:213], v[82:85]
	v_mfma_f32_16x16x32_bf16 v[74:77], v[138:141], v[210:213], v[74:77]
	v_mfma_f32_16x16x32_bf16 v[126:129], v[134:137], v[166:169], v[126:129]
	v_mfma_f32_16x16x32_bf16 v[122:125], v[142:145], v[166:169], v[122:125]
	v_mfma_f32_16x16x32_bf16 v[114:117], v[134:137], v[174:177], v[114:117]
	v_mfma_f32_16x16x32_bf16 v[106:109], v[142:145], v[174:177], v[106:109]
	v_mfma_f32_16x16x32_bf16 v[98:101], v[134:137], v[206:209], v[98:101]
	v_mfma_f32_16x16x32_bf16 v[90:93], v[142:145], v[206:209], v[90:93]
	v_mfma_f32_16x16x32_bf16 v[82:85], v[134:137], v[214:217], v[82:85]
	v_mfma_f32_16x16x32_bf16 v[74:77], v[142:145], v[214:217], v[74:77]
	s_setprio 0
	s_setprio 1
	v_mfma_f32_16x16x32_bf16 v[118:121], v[146:149], v[162:165], v[118:121]
	v_mfma_f32_16x16x32_bf16 v[110:113], v[154:157], v[162:165], v[110:113]
	v_mfma_f32_16x16x32_bf16 v[102:105], v[146:149], v[170:173], v[102:105]
	v_mfma_f32_16x16x32_bf16 v[94:97], v[154:157], v[170:173], v[94:97]
	v_mfma_f32_16x16x32_bf16 v[86:89], v[146:149], v[178:181], v[86:89]
	v_mfma_f32_16x16x32_bf16 v[78:81], v[154:157], v[178:181], v[78:81]
	v_mfma_f32_16x16x32_bf16 v[70:73], v[146:149], v[210:213], v[70:73]
	v_mfma_f32_16x16x32_bf16 v[66:69], v[154:157], v[210:213], v[66:69]
	v_mfma_f32_16x16x32_bf16 v[118:121], v[150:153], v[166:169], v[118:121]
	v_mfma_f32_16x16x32_bf16 v[110:113], v[158:161], v[166:169], v[110:113]
	v_mfma_f32_16x16x32_bf16 v[102:105], v[150:153], v[174:177], v[102:105]
	v_mfma_f32_16x16x32_bf16 v[94:97], v[158:161], v[174:177], v[94:97]
	v_mfma_f32_16x16x32_bf16 v[86:89], v[150:153], v[206:209], v[86:89]
	v_mfma_f32_16x16x32_bf16 v[78:81], v[158:161], v[206:209], v[78:81]
	v_mfma_f32_16x16x32_bf16 v[70:73], v[150:153], v[214:217], v[70:73]
	v_mfma_f32_16x16x32_bf16 v[66:69], v[158:161], v[214:217], v[66:69]
	s_barrier
; #define PG8_STAGE(bufoff, gbase, voff) do { _Pragma("unroll") for (int _i = 0; _i < 2; ++_i) \
;         __builtin_amdgcn_global_load_lds((const unsigned*)((const char*)(gbase) + (voff)[_i]), (PG8_LAS unsigned*)(lds + (bufoff) + ldsw + _i * 8192), 16, 0, 0); } while (0)
; #define PG8_WAIT_V(n) asm volatile("s_waitcnt vmcnt(" #n ")" ::: "memory")
; #define PG8_WAIT_L(n) asm volatile("s_waitcnt lgkmcnt(" #n ")" ::: "memory")
; #define PG8_BAR __builtin_amdgcn_s_barrier()
; #define PG8_SCHED __builtin_amdgcn_sched_barrier(0)
; template <class Epi, class Sched, bool ALIGN_EPI = true, bool SP2 = true>
; __device__ __forceinline__ void gemm_phase(PG8_LAS unsigned char* lds, const int K  , const Sched& S, const Epi& E) {
;     ...
;             PG8_WAIT_V(8); PG8_WAIT_L(0); PG8_BAR; PG8_MMA(0, 0, At, B0); PG8_MMA(0, 1, At, B1); PG8_BAR; PG8_SCHED;
;             PG8_LDA(At, 1, 1); PG8_STAGE(PG8_SB(1, 0), b3, voffB); PG8_STAGE(PG8_SB(1, 1), b3 + hstep, voffB); PG8_STAGE(PG8_SA(1, 0), a3, voffA);
;             PG8_WAIT_V(8); PG8_WAIT_L(0); PG8_BAR; PG8_MMA(1, 0, At, B0); PG8_MMA(1, 1, At, B1); PG8_BAR; PG8_SCHED;
;     ...
;         if constexpr (Epi::FP8) asm volatile("s_nop 15\n\ts_nop 15\n\ts_nop 15\n\ts_nop 15\n\ts_nop 15" ::: "memory");
;         if constexpr (ALIGN_EPI) { if (wr == 0) PG8_BAR; }
	s_setprio 0
	s_add_i32 s24, s55, s29
	v_lshl_add_u64 v[198:199], v[198:199], 0, s[6:7]
	s_mov_b32 m0, s24
	ds_read_b128 v[162:165], v205 offset:49152
	ds_read_b128 v[166:169], v205 offset:50176
	ds_read_b128 v[170:173], v205 offset:51200
	ds_read_b128 v[174:177], v205 offset:52224
	ds_read_b128 v[178:181], v205 offset:53248
	ds_read_b128 v[206:209], v205 offset:54272
	ds_read_b128 v[210:213], v205 offset:55296
	ds_read_b128 v[214:217], v205 offset:56320
	global_load_lds_dwordx4 v[198:199], off
	s_add_i32 m0, s24, 0x2000
	s_add_u32 s22, s22, 0x80080
	v_lshl_add_u64 v[198:199], v[218:219], 0, s[6:7]
	s_addc_u32 s23, s23, 0
	s_add_i32 s24, s56, s29
	global_load_lds_dwordx4 v[198:199], off
	v_lshl_add_u64 v[198:199], s[22:23], 0, v[184:185]
	s_mov_b32 m0, s24
	s_nop 0
	global_load_lds_dwordx4 v[198:199], off
	v_lshl_add_u64 v[198:199], s[22:23], 0, v[188:189]
	s_add_i32 m0, s24, 0x2000
	s_nop 0
	global_load_lds_dwordx4 v[198:199], off
	v_lshl_add_u64 v[198:199], v[220:221], 0, s[6:7]
	s_mov_b32 m0, s38
	s_nop 0
	global_load_lds_dwordx4 v[198:199], off
	v_lshl_add_u64 v[198:199], v[222:223], 0, s[6:7]
	s_mov_b32 m0, s39
	s_nop 0
	global_load_lds_dwordx4 v[198:199], off
	s_waitcnt vmcnt(8)
	s_waitcnt lgkmcnt(0)
	s_setprio 1
	s_barrier
	v_mfma_f32_16x16x32_bf16 v[62:65], v[130:133], v[162:165], v[62:65]
	v_mfma_f32_16x16x32_bf16 v[58:61], v[138:141], v[162:165], v[58:61]
	v_mfma_f32_16x16x32_bf16 v[50:53], v[130:133], v[170:173], v[50:53]
	v_mfma_f32_16x16x32_bf16 v[42:45], v[138:141], v[170:173], v[42:45]
	v_mfma_f32_16x16x32_bf16 v[34:37], v[130:133], v[178:181], v[34:37]
	v_mfma_f32_16x16x32_bf16 v[26:29], v[138:141], v[178:181], v[26:29]
	v_mfma_f32_16x16x32_bf16 v[18:21], v[130:133], v[210:213], v[18:21]
	v_mfma_f32_16x16x32_bf16 v[10:13], v[138:141], v[210:213], v[10:13]
	v_mfma_f32_16x16x32_bf16 v[62:65], v[134:137], v[166:169], v[62:65]
	v_mfma_f32_16x16x32_bf16 v[58:61], v[142:145], v[166:169], v[58:61]
	v_mfma_f32_16x16x32_bf16 v[50:53], v[134:137], v[174:177], v[50:53]
	v_mfma_f32_16x16x32_bf16 v[42:45], v[142:145], v[174:177], v[42:45]
	v_mfma_f32_16x16x32_bf16 v[34:37], v[134:137], v[206:209], v[34:37]
	v_mfma_f32_16x16x32_bf16 v[26:29], v[142:145], v[206:209], v[26:29]
	v_mfma_f32_16x16x32_bf16 v[18:21], v[134:137], v[214:217], v[18:21]
	v_mfma_f32_16x16x32_bf16 v[10:13], v[142:145], v[214:217], v[10:13]
	s_setprio 0
	s_setprio 1
	v_mfma_f32_16x16x32_bf16 v[54:57], v[146:149], v[162:165], v[54:57]
	v_mfma_f32_16x16x32_bf16 v[46:49], v[154:157], v[162:165], v[46:49]
	v_mfma_f32_16x16x32_bf16 v[38:41], v[146:149], v[170:173], v[38:41]
	v_mfma_f32_16x16x32_bf16 v[30:33], v[154:157], v[170:173], v[30:33]
	v_mfma_f32_16x16x32_bf16 v[22:25], v[146:149], v[178:181], v[22:25]
	v_mfma_f32_16x16x32_bf16 v[14:17], v[154:157], v[178:181], v[14:17]
	v_mfma_f32_16x16x32_bf16 v[6:9], v[146:149], v[210:213], v[6:9]
	v_mfma_f32_16x16x32_bf16 v[2:5], v[154:157], v[210:213], v[2:5]
	v_mfma_f32_16x16x32_bf16 v[54:57], v[150:153], v[166:169], v[54:57]
	v_mfma_f32_16x16x32_bf16 v[46:49], v[158:161], v[166:169], v[46:49]
	v_mfma_f32_16x16x32_bf16 v[38:41], v[150:153], v[174:177], v[38:41]
	v_mfma_f32_16x16x32_bf16 v[30:33], v[158:161], v[174:177], v[30:33]
	v_mfma_f32_16x16x32_bf16 v[22:25], v[150:153], v[206:209], v[22:25]
	v_mfma_f32_16x16x32_bf16 v[14:17], v[158:161], v[206:209], v[14:17]
	v_mfma_f32_16x16x32_bf16 v[6:9], v[150:153], v[214:217], v[6:9]
	v_mfma_f32_16x16x32_bf16 v[2:5], v[158:161], v[214:217], v[2:5]
	s_barrier
	s_setprio 0
	s_add_i32 s54, s54, 2
	s_add_u32 s20, s20, 0x100
	s_addc_u32 s21, s21, 0
	s_add_u32 s52, s52, 0x100
	s_addc_u32 s53, s53, 0
	s_cmp_gt_u32 s54, 29
	s_cbranch_scc0 .LBB0_2296
	s_and_b64 vcc, exec, s[8:9]
	s_cbranch_vccz .LBB0_2299
	s_barrier

; #define PG8_STAGE(bufoff, gbase, voff) do { _Pragma("unroll") for (int _i = 0; _i < 2; ++_i) \
;         __builtin_amdgcn_global_load_lds((const unsigned*)((const char*)(gbase) + (voff)[_i]), (PG8_LAS unsigned*)(lds + (bufoff) + ldsw + _i * 8192), 16, 0, 0); } while (0)
; #define PG8_WAIT_V(n) asm volatile("s_waitcnt vmcnt(" #n ")" ::: "memory")
; #define PG8_WAIT_L(n) asm volatile("s_waitcnt lgkmcnt(" #n ")" ::: "memory")
; #define PG8_BAR __builtin_amdgcn_s_barrier()
; #define PG8_SCHED __builtin_amdgcn_sched_barrier(0)
;     __device__ __forceinline__ int nt(const pg8::Unit& u) const { return u.kind == 0 ? ntiles : q_nt(u.kind - 1); }
; template <class Epi, class Sched, bool ALIGN_EPI = true, bool SP2 = true>
; __device__ __forceinline__ void gemm_phase(PG8_LAS unsigned char* lds, const int K  , const Sched& S, const Epi& E) {
;     ...
;         for (int t = 0; t < nt; t += 2) {
;             const bool last = (t == nt - 2);
;             const char* a1 = cA + (size_t)(t + 1) * kstep;
;             const char* a2 = last ? nA : cA + (size_t)(t + 2) * kstep; const char* b2 = last ? nB : cB + (size_t)(t + 2) * kstep;
;             const char* a3 = a2 + kstep; const char* b3 = b2 + kstep;
;             if constexpr (SP2) {
;             PG8_LDB(B0, 0, 0); PG8_LDB(B1, 0, 1); PG8_SCHED; PG8_LDA(At, 0, 0); PG8_STAGE(PG8_SA(1, 1), a1 + hstep, voffA);
;             PG8_WAIT_V(8); PG8_WAIT_L(0); PG8_BAR; PG8_MMA(0, 0, At, B0); PG8_MMA(0, 1, At, B1); PG8_BAR; PG8_SCHED;
;             PG8_LDA(At, 0, 1); PG8_STAGE(PG8_SB(0, 0), b2, voffB); PG8_STAGE(PG8_SB(0, 1), b2 + hstep, voffB); PG8_STAGE(PG8_SA(0, 0), a2, voffA);
.LBB0_2433:
	ds_read_b128 v[146:149], v152
	ds_read_b128 v[158:161], v152 offset:1024
	ds_read_b128 v[162:165], v152 offset:2048
	ds_read_b128 v[166:169], v152 offset:3072
	ds_read_b128 v[170:173], v153
	ds_read_b128 v[174:177], v153 offset:1024
	ds_read_b128 v[178:181], v153 offset:2048
	ds_read_b128 v[182:185], v153 offset:3072
	s_add_u32 s22, s20, 0xfff80080
	s_addc_u32 s23, s21, -1
	s_cmp_eq_u32 s48, 28
	s_cselect_b32 s25, s13, s23
	s_cselect_b32 s24, s44, s22
	s_cselect_b32 s23, s11, s47
	s_cselect_b32 s22, s45, s46
	v_lshl_add_u64 v[218:219], s[20:21], 0, v[138:139]
	s_add_i32 m0, s19, 0xc000
	ds_read_b128 v[186:189], v154
	ds_read_b128 v[190:193], v154 offset:1024
	ds_read_b128 v[194:197], v154 offset:2048
	ds_read_b128 v[198:201], v154 offset:3072
	ds_read_b128 v[202:205], v154 offset:4096
	ds_read_b128 v[206:209], v154 offset:5120
	ds_read_b128 v[210:213], v154 offset:6144
	ds_read_b128 v[214:217], v154 offset:7168
	global_load_lds_dwordx4 v[218:219], off
	v_lshl_add_u64 v[218:219], s[20:21], 0, v[140:141]
	s_add_i32 m0, s19, 0xe000
	s_nop 0
	global_load_lds_dwordx4 v[218:219], off
	s_waitcnt vmcnt(8)
	s_waitcnt lgkmcnt(0)
	s_setprio 1
	s_barrier
	v_mfma_f32_16x16x32_bf16 v[126:129], v[146:149], v[186:189], v[126:129]
	v_mfma_f32_16x16x32_bf16 v[118:121], v[162:165], v[186:189], v[118:121]
	v_mfma_f32_16x16x32_bf16 v[110:113], v[146:149], v[194:197], v[110:113]
	v_mfma_f32_16x16x32_bf16 v[102:105], v[162:165], v[194:197], v[102:105]
	v_mfma_f32_16x16x32_bf16 v[94:97], v[146:149], v[202:205], v[94:97]
	v_mfma_f32_16x16x32_bf16 v[86:89], v[162:165], v[202:205], v[86:89]
	v_mfma_f32_16x16x32_bf16 v[78:81], v[146:149], v[210:213], v[78:81]
	v_mfma_f32_16x16x32_bf16 v[70:73], v[162:165], v[210:213], v[70:73]
	v_mfma_f32_16x16x32_bf16 v[126:129], v[158:161], v[190:193], v[126:129]
	v_mfma_f32_16x16x32_bf16 v[118:121], v[166:169], v[190:193], v[118:121]
	v_mfma_f32_16x16x32_bf16 v[110:113], v[158:161], v[198:201], v[110:113]
	v_mfma_f32_16x16x32_bf16 v[102:105], v[166:169], v[198:201], v[102:105]
	v_mfma_f32_16x16x32_bf16 v[94:97], v[158:161], v[206:209], v[94:97]
	v_mfma_f32_16x16x32_bf16 v[86:89], v[166:169], v[206:209], v[86:89]
	v_mfma_f32_16x16x32_bf16 v[78:81], v[158:161], v[214:217], v[78:81]
	v_mfma_f32_16x16x32_bf16 v[70:73], v[166:169], v[214:217], v[70:73]
	s_setprio 0
	s_setprio 1
	v_mfma_f32_16x16x32_bf16 v[122:125], v[170:173], v[186:189], v[122:125]
	v_mfma_f32_16x16x32_bf16 v[114:117], v[178:181], v[186:189], v[114:117]
	v_mfma_f32_16x16x32_bf16 v[106:109], v[170:173], v[194:197], v[106:109]
	v_mfma_f32_16x16x32_bf16 v[98:101], v[178:181], v[194:197], v[98:101]
	v_mfma_f32_16x16x32_bf16 v[90:93], v[170:173], v[202:205], v[90:93]
	v_mfma_f32_16x16x32_bf16 v[82:85], v[178:181], v[202:205], v[82:85]
	v_mfma_f32_16x16x32_bf16 v[74:77], v[170:173], v[210:213], v[74:77]
	v_mfma_f32_16x16x32_bf16 v[66:69], v[178:181], v[210:213], v[66:69]
	v_mfma_f32_16x16x32_bf16 v[122:125], v[174:177], v[190:193], v[122:125]
	v_mfma_f32_16x16x32_bf16 v[114:117], v[182:185], v[190:193], v[114:117]
	v_mfma_f32_16x16x32_bf16 v[106:109], v[174:177], v[198:201], v[106:109]
	v_mfma_f32_16x16x32_bf16 v[98:101], v[182:185], v[198:201], v[98:101]
	v_mfma_f32_16x16x32_bf16 v[90:93], v[174:177], v[206:209], v[90:93]
	v_mfma_f32_16x16x32_bf16 v[82:85], v[182:185], v[206:209], v[82:85]
	v_mfma_f32_16x16x32_bf16 v[74:77], v[174:177], v[214:217], v[74:77]
	v_mfma_f32_16x16x32_bf16 v[66:69], v[182:185], v[214:217], v[66:69]
	s_barrier
	s_setprio 0
	s_add_i32 s49, s39, s28
	v_lshl_add_u64 v[218:219], s[22:23], 0, v[134:135]
	s_mov_b32 m0, s49
	ds_read_b128 v[186:189], v154 offset:16384
	ds_read_b128 v[190:193], v154 offset:17408
	ds_read_b128 v[194:197], v154 offset:18432
	ds_read_b128 v[198:201], v154 offset:19456
	ds_read_b128 v[202:205], v154 offset:20480
	ds_read_b128 v[206:209], v154 offset:21504
	ds_read_b128 v[210:213], v154 offset:22528
	ds_read_b128 v[214:217], v154 offset:23552
	global_load_lds_dwordx4 v[218:219], off
	s_add_i32 m0, s49, 0x2000
	s_add_u32 s50, s22, 0x80000
	v_lshl_add_u64 v[220:221], s[22:23], 0, v[130:131]
	s_addc_u32 s51, s23, 0
	s_add_i32 s49, s40, s28
	global_load_lds_dwordx4 v[220:221], off
	v_lshl_add_u64 v[222:223], s[50:51], 0, v[134:135]
	s_mov_b32 m0, s49
	v_lshl_add_u64 v[224:225], s[24:25], 0, v[132:133]
	global_load_lds_dwordx4 v[222:223], off
	v_lshl_add_u64 v[222:223], s[50:51], 0, v[130:131]
	s_add_i32 m0, s49, 0x2000
	s_nop 0
	global_load_lds_dwordx4 v[222:223], off
	v_lshl_add_u64 v[222:223], s[24:25], 0, v[136:137]
	s_mov_b32 m0, s19
	s_nop 0
	global_load_lds_dwordx4 v[222:223], off
	s_mov_b32 m0, s31
	s_nop 0
	global_load_lds_dwordx4 v[224:225], off
	s_waitcnt vmcnt(8)
	s_waitcnt lgkmcnt(0)
	s_setprio 1
	s_barrier
; #define PG8_STAGE(bufoff, gbase, voff) do { _Pragma("unroll") for (int _i = 0; _i < 2; ++_i) \
;         __builtin_amdgcn_global_load_lds((const unsigned*)((const char*)(gbase) + (voff)[_i]), (PG8_LAS unsigned*)(lds + (bufoff) + ldsw + _i * 8192), 16, 0, 0); } while (0)
; #define PG8_WAIT_V(n) asm volatile("s_waitcnt vmcnt(" #n ")" ::: "memory")
; #define PG8_WAIT_L(n) asm volatile("s_waitcnt lgkmcnt(" #n ")" ::: "memory")
; #define PG8_BAR __builtin_amdgcn_s_barrier()
; #define PG8_SCHED __builtin_amdgcn_sched_barrier(0)
; template <class Epi, class Sched, bool ALIGN_EPI = true, bool SP2 = true>
; __device__ __forceinline__ void gemm_phase(PG8_LAS unsigned char* lds, const int K  , const Sched& S, const Epi& E) {
;     ...
;             PG8_WAIT_V(8); PG8_WAIT_L(0); PG8_BAR; PG8_MMA(1, 0, At, B0); PG8_MMA(1, 1, At, B1); PG8_BAR; PG8_SCHED;
;             PG8_LDB(B0, 1, 0); PG8_LDB(B1, 1, 1); PG8_SCHED; PG8_LDA(At, 1, 0); PG8_STAGE(PG8_SA(0, 1), a2 + hstep, voffA);
;             PG8_WAIT_V(8); PG8_WAIT_L(0); PG8_BAR; PG8_MMA(0, 0, At, B0); PG8_MMA(0, 1, At, B1); PG8_BAR; PG8_SCHED;
	v_mfma_f32_16x16x32_bf16 v[62:65], v[146:149], v[186:189], v[62:65]
	v_mfma_f32_16x16x32_bf16 v[54:57], v[162:165], v[186:189], v[54:57]
	v_mfma_f32_16x16x32_bf16 v[46:49], v[146:149], v[194:197], v[46:49]
	v_mfma_f32_16x16x32_bf16 v[38:41], v[162:165], v[194:197], v[38:41]
	v_mfma_f32_16x16x32_bf16 v[30:33], v[146:149], v[202:205], v[30:33]
	v_mfma_f32_16x16x32_bf16 v[22:25], v[162:165], v[202:205], v[22:25]
	v_mfma_f32_16x16x32_bf16 v[14:17], v[146:149], v[210:213], v[14:17]
	v_mfma_f32_16x16x32_bf16 v[6:9], v[162:165], v[210:213], v[6:9]
	v_mfma_f32_16x16x32_bf16 v[62:65], v[158:161], v[190:193], v[62:65]
	v_mfma_f32_16x16x32_bf16 v[54:57], v[166:169], v[190:193], v[54:57]
	v_mfma_f32_16x16x32_bf16 v[46:49], v[158:161], v[198:201], v[46:49]
	v_mfma_f32_16x16x32_bf16 v[38:41], v[166:169], v[198:201], v[38:41]
	v_mfma_f32_16x16x32_bf16 v[30:33], v[158:161], v[206:209], v[30:33]
	v_mfma_f32_16x16x32_bf16 v[22:25], v[166:169], v[206:209], v[22:25]
	v_mfma_f32_16x16x32_bf16 v[14:17], v[158:161], v[214:217], v[14:17]
	v_mfma_f32_16x16x32_bf16 v[6:9], v[166:169], v[214:217], v[6:9]
	s_setprio 0
	s_setprio 1
	v_mfma_f32_16x16x32_bf16 v[58:61], v[170:173], v[186:189], v[58:61]
	v_mfma_f32_16x16x32_bf16 v[50:53], v[178:181], v[186:189], v[50:53]
	v_mfma_f32_16x16x32_bf16 v[42:45], v[170:173], v[194:197], v[42:45]
	v_mfma_f32_16x16x32_bf16 v[34:37], v[178:181], v[194:197], v[34:37]
	v_mfma_f32_16x16x32_bf16 v[26:29], v[170:173], v[202:205], v[26:29]
	v_mfma_f32_16x16x32_bf16 v[18:21], v[178:181], v[202:205], v[18:21]
	v_mfma_f32_16x16x32_bf16 v[10:13], v[170:173], v[210:213], v[10:13]
	v_mfma_f32_16x16x32_bf16 v[2:5], v[178:181], v[210:213], v[2:5]
	v_mfma_f32_16x16x32_bf16 v[58:61], v[174:177], v[190:193], v[58:61]
	v_mfma_f32_16x16x32_bf16 v[50:53], v[182:185], v[190:193], v[50:53]
	v_mfma_f32_16x16x32_bf16 v[42:45], v[174:177], v[198:201], v[42:45]
	v_mfma_f32_16x16x32_bf16 v[34:37], v[182:185], v[198:201], v[34:37]
	v_mfma_f32_16x16x32_bf16 v[26:29], v[174:177], v[206:209], v[26:29]
	v_mfma_f32_16x16x32_bf16 v[18:21], v[182:185], v[206:209], v[18:21]
	v_mfma_f32_16x16x32_bf16 v[10:13], v[174:177], v[214:217], v[10:13]
	v_mfma_f32_16x16x32_bf16 v[2:5], v[182:185], v[214:217], v[2:5]
	s_barrier
	s_setprio 0
	s_add_i32 s49, 0, 0x18000
	v_add_u32_e32 v157, s49, v150
	s_add_i32 s50, 0, 0x1c000
	ds_read_b128 v[146:149], v157
	ds_read_b128 v[158:161], v157 offset:1024
	ds_read_b128 v[162:165], v157 offset:2048
	ds_read_b128 v[166:169], v157 offset:3072
	v_add_u32_e32 v157, s50, v150
	ds_read_b128 v[170:173], v157
	ds_read_b128 v[174:177], v157 offset:1024
	ds_read_b128 v[178:181], v157 offset:2048
	ds_read_b128 v[182:185], v157 offset:3072
	s_add_u32 s24, s24, 0x80000
	s_addc_u32 s25, s25, 0
	s_mov_b32 m0, s33
	v_lshl_add_u64 v[226:227], s[24:25], 0, v[136:137]
	ds_read_b128 v[186:189], v154 offset:32768
	ds_read_b128 v[190:193], v154 offset:33792
	ds_read_b128 v[194:197], v154 offset:34816
	ds_read_b128 v[198:201], v154 offset:35840
	ds_read_b128 v[202:205], v154 offset:36864
	ds_read_b128 v[206:209], v154 offset:37888
	ds_read_b128 v[210:213], v154 offset:38912
	ds_read_b128 v[214:217], v154 offset:39936
	global_load_lds_dwordx4 v[226:227], off
	v_lshl_add_u64 v[226:227], s[24:25], 0, v[132:133]
	s_mov_b32 m0, s34
	s_nop 0
	global_load_lds_dwordx4 v[226:227], off
	s_waitcnt vmcnt(8)
	s_waitcnt lgkmcnt(0)
	s_setprio 1
	s_barrier
	v_mfma_f32_16x16x32_bf16 v[126:129], v[146:149], v[186:189], v[126:129]
	v_mfma_f32_16x16x32_bf16 v[118:121], v[162:165], v[186:189], v[118:121]
	v_mfma_f32_16x16x32_bf16 v[110:113], v[146:149], v[194:197], v[110:113]
	v_mfma_f32_16x16x32_bf16 v[102:105], v[162:165], v[194:197], v[102:105]
	v_mfma_f32_16x16x32_bf16 v[94:97], v[146:149], v[202:205], v[94:97]
	v_mfma_f32_16x16x32_bf16 v[86:89], v[162:165], v[202:205], v[86:89]
	v_mfma_f32_16x16x32_bf16 v[78:81], v[146:149], v[210:213], v[78:81]
	v_mfma_f32_16x16x32_bf16 v[70:73], v[162:165], v[210:213], v[70:73]
	v_mfma_f32_16x16x32_bf16 v[126:129], v[158:161], v[190:193], v[126:129]
	v_mfma_f32_16x16x32_bf16 v[118:121], v[166:169], v[190:193], v[118:121]
	v_mfma_f32_16x16x32_bf16 v[110:113], v[158:161], v[198:201], v[110:113]
	v_mfma_f32_16x16x32_bf16 v[102:105], v[166:169], v[198:201], v[102:105]
	v_mfma_f32_16x16x32_bf16 v[94:97], v[158:161], v[206:209], v[94:97]
	v_mfma_f32_16x16x32_bf16 v[86:89], v[166:169], v[206:209], v[86:89]
	v_mfma_f32_16x16x32_bf16 v[78:81], v[158:161], v[214:217], v[78:81]
	v_mfma_f32_16x16x32_bf16 v[70:73], v[166:169], v[214:217], v[70:73]
	s_setprio 0
	s_setprio 1
	v_mfma_f32_16x16x32_bf16 v[122:125], v[170:173], v[186:189], v[122:125]
	v_mfma_f32_16x16x32_bf16 v[114:117], v[178:181], v[186:189], v[114:117]
	v_mfma_f32_16x16x32_bf16 v[106:109], v[170:173], v[194:197], v[106:109]
	v_mfma_f32_16x16x32_bf16 v[98:101], v[178:181], v[194:197], v[98:101]
	v_mfma_f32_16x16x32_bf16 v[90:93], v[170:173], v[202:205], v[90:93]
	v_mfma_f32_16x16x32_bf16 v[82:85], v[178:181], v[202:205], v[82:85]
	v_mfma_f32_16x16x32_bf16 v[74:77], v[170:173], v[210:213], v[74:77]
	v_mfma_f32_16x16x32_bf16 v[66:69], v[178:181], v[210:213], v[66:69]
	v_mfma_f32_16x16x32_bf16 v[122:125], v[174:177], v[190:193], v[122:125]
	v_mfma_f32_16x16x32_bf16 v[114:117], v[182:185], v[190:193], v[114:117]
	v_mfma_f32_16x16x32_bf16 v[106:109], v[174:177], v[198:201], v[106:109]
	v_mfma_f32_16x16x32_bf16 v[98:101], v[182:185], v[198:201], v[98:101]
	v_mfma_f32_16x16x32_bf16 v[90:93], v[174:177], v[206:209], v[90:93]
	v_mfma_f32_16x16x32_bf16 v[82:85], v[182:185], v[206:209], v[82:85]
	v_mfma_f32_16x16x32_bf16 v[74:77], v[174:177], v[214:217], v[74:77]
	v_mfma_f32_16x16x32_bf16 v[66:69], v[182:185], v[214:217], v[66:69]
	s_barrier
; #define PG8_STAGE(bufoff, gbase, voff) do { _Pragma("unroll") for (int _i = 0; _i < 2; ++_i) \
;         __builtin_amdgcn_global_load_lds((const unsigned*)((const char*)(gbase) + (voff)[_i]), (PG8_LAS unsigned*)(lds + (bufoff) + ldsw + _i * 8192), 16, 0, 0); } while (0)
; #define PG8_WAIT_V(n) asm volatile("s_waitcnt vmcnt(" #n ")" ::: "memory")
; #define PG8_WAIT_L(n) asm volatile("s_waitcnt lgkmcnt(" #n ")" ::: "memory")
; #define PG8_BAR __builtin_amdgcn_s_barrier()
; #define PG8_SCHED __builtin_amdgcn_sched_barrier(0)
; template <class Epi, class Sched, bool ALIGN_EPI = true, bool SP2 = true>
; __device__ __forceinline__ void gemm_phase(PG8_LAS unsigned char* lds, const int K  , const Sched& S, const Epi& E) {
;     ...
;             PG8_WAIT_V(8); PG8_WAIT_L(0); PG8_BAR; PG8_MMA(0, 0, At, B0); PG8_MMA(0, 1, At, B1); PG8_BAR; PG8_SCHED;
;             PG8_LDA(At, 1, 1); PG8_STAGE(PG8_SB(1, 0), b3, voffB); PG8_STAGE(PG8_SB(1, 1), b3 + hstep, voffB); PG8_STAGE(PG8_SA(1, 0), a3, voffA);
;             PG8_WAIT_V(8); PG8_WAIT_L(0); PG8_BAR; PG8_MMA(1, 0, At, B0); PG8_MMA(1, 1, At, B1); PG8_BAR; PG8_SCHED;
;     ...
;         if constexpr (Epi::FP8) asm volatile("s_nop 15\n\ts_nop 15\n\ts_nop 15\n\ts_nop 15\n\ts_nop 15" ::: "memory");
;         if constexpr (ALIGN_EPI) { if (wr == 0) PG8_BAR; }
	s_setprio 0
	s_add_i32 s24, s49, s28
	v_lshl_add_u64 v[218:219], v[218:219], 0, s[6:7]
	s_mov_b32 m0, s24
	ds_read_b128 v[186:189], v154 offset:49152
	ds_read_b128 v[190:193], v154 offset:50176
	ds_read_b128 v[194:197], v154 offset:51200
	ds_read_b128 v[198:201], v154 offset:52224
	ds_read_b128 v[202:205], v154 offset:53248
	ds_read_b128 v[206:209], v154 offset:54272
	ds_read_b128 v[210:213], v154 offset:55296
	ds_read_b128 v[214:217], v154 offset:56320
	global_load_lds_dwordx4 v[218:219], off
	s_add_i32 m0, s24, 0x2000
	s_add_u32 s22, s22, 0x80080
	v_lshl_add_u64 v[218:219], v[220:221], 0, s[6:7]
	s_addc_u32 s23, s23, 0
	s_add_i32 s24, s50, s28
	global_load_lds_dwordx4 v[218:219], off
	v_lshl_add_u64 v[218:219], s[22:23], 0, v[134:135]
	s_mov_b32 m0, s24
	s_nop 0
	global_load_lds_dwordx4 v[218:219], off
	v_lshl_add_u64 v[218:219], s[22:23], 0, v[130:131]
	s_add_i32 m0, s24, 0x2000
	s_nop 0
	global_load_lds_dwordx4 v[218:219], off
	v_lshl_add_u64 v[218:219], v[222:223], 0, s[6:7]
	s_mov_b32 m0, s36
	s_nop 0
	global_load_lds_dwordx4 v[218:219], off
	v_lshl_add_u64 v[218:219], v[224:225], 0, s[6:7]
	s_mov_b32 m0, s37
	s_nop 0
	global_load_lds_dwordx4 v[218:219], off
	s_waitcnt vmcnt(8)
	s_waitcnt lgkmcnt(0)
	s_setprio 1
	s_barrier
	v_mfma_f32_16x16x32_bf16 v[62:65], v[146:149], v[186:189], v[62:65]
	v_mfma_f32_16x16x32_bf16 v[54:57], v[162:165], v[186:189], v[54:57]
	v_mfma_f32_16x16x32_bf16 v[46:49], v[146:149], v[194:197], v[46:49]
	v_mfma_f32_16x16x32_bf16 v[38:41], v[162:165], v[194:197], v[38:41]
	v_mfma_f32_16x16x32_bf16 v[30:33], v[146:149], v[202:205], v[30:33]
	v_mfma_f32_16x16x32_bf16 v[22:25], v[162:165], v[202:205], v[22:25]
	v_mfma_f32_16x16x32_bf16 v[14:17], v[146:149], v[210:213], v[14:17]
	v_mfma_f32_16x16x32_bf16 v[6:9], v[162:165], v[210:213], v[6:9]
	v_mfma_f32_16x16x32_bf16 v[62:65], v[158:161], v[190:193], v[62:65]
	v_mfma_f32_16x16x32_bf16 v[54:57], v[166:169], v[190:193], v[54:57]
	v_mfma_f32_16x16x32_bf16 v[46:49], v[158:161], v[198:201], v[46:49]
	v_mfma_f32_16x16x32_bf16 v[38:41], v[166:169], v[198:201], v[38:41]
	v_mfma_f32_16x16x32_bf16 v[30:33], v[158:161], v[206:209], v[30:33]
	v_mfma_f32_16x16x32_bf16 v[22:25], v[166:169], v[206:209], v[22:25]
	v_mfma_f32_16x16x32_bf16 v[14:17], v[158:161], v[214:217], v[14:17]
	v_mfma_f32_16x16x32_bf16 v[6:9], v[166:169], v[214:217], v[6:9]
	s_setprio 0
	s_setprio 1
	v_mfma_f32_16x16x32_bf16 v[58:61], v[170:173], v[186:189], v[58:61]
	v_mfma_f32_16x16x32_bf16 v[50:53], v[178:181], v[186:189], v[50:53]
	v_mfma_f32_16x16x32_bf16 v[42:45], v[170:173], v[194:197], v[42:45]
	v_mfma_f32_16x16x32_bf16 v[34:37], v[178:181], v[194:197], v[34:37]
	v_mfma_f32_16x16x32_bf16 v[26:29], v[170:173], v[202:205], v[26:29]
	v_mfma_f32_16x16x32_bf16 v[18:21], v[178:181], v[202:205], v[18:21]
	v_mfma_f32_16x16x32_bf16 v[10:13], v[170:173], v[210:213], v[10:13]
	v_mfma_f32_16x16x32_bf16 v[2:5], v[178:181], v[210:213], v[2:5]
	v_mfma_f32_16x16x32_bf16 v[58:61], v[174:177], v[190:193], v[58:61]
	v_mfma_f32_16x16x32_bf16 v[50:53], v[182:185], v[190:193], v[50:53]
	v_mfma_f32_16x16x32_bf16 v[42:45], v[174:177], v[198:201], v[42:45]
	v_mfma_f32_16x16x32_bf16 v[34:37], v[182:185], v[198:201], v[34:37]
	v_mfma_f32_16x16x32_bf16 v[26:29], v[174:177], v[206:209], v[26:29]
	v_mfma_f32_16x16x32_bf16 v[18:21], v[182:185], v[206:209], v[18:21]
	v_mfma_f32_16x16x32_bf16 v[10:13], v[174:177], v[214:217], v[10:13]
	v_mfma_f32_16x16x32_bf16 v[2:5], v[182:185], v[214:217], v[2:5]
	s_barrier
	s_setprio 0
	s_add_i32 s48, s48, 2
	s_add_u32 s20, s20, 0x100
	s_addc_u32 s21, s21, 0
	s_add_u32 s46, s46, 0x100
	s_addc_u32 s47, s47, 0
	s_cmp_gt_u32 s48, 29
	s_cbranch_scc0 .LBB0_2433
	s_and_b64 vcc, exec, s[8:9]
	s_cbranch_vccz .LBB0_2436
	s_barrier

; #define PG8_STAGE(bufoff, gbase, voff) do { _Pragma("unroll") for (int _i = 0; _i < 2; ++_i) \
;         __builtin_amdgcn_global_load_lds((const unsigned*)((const char*)(gbase) + (voff)[_i]), (PG8_LAS unsigned*)(lds + (bufoff) + ldsw + _i * 8192), 16, 0, 0); } while (0)
; #define PG8_WAIT_V(n) asm volatile("s_waitcnt vmcnt(" #n ")" ::: "memory")
; #define PG8_WAIT_L(n) asm volatile("s_waitcnt lgkmcnt(" #n ")" ::: "memory")
; #define PG8_BAR __builtin_amdgcn_s_barrier()
; #define PG8_SCHED __builtin_amdgcn_sched_barrier(0)
;     __device__ __forceinline__ int nt(const pg8::Unit& u) const { return u.kind == 0 ? ntiles : q_nt(u.kind - 1); }
; template <class Epi, class Sched, bool ALIGN_EPI = true, bool SP2 = true>
; __device__ __forceinline__ void gemm_phase(PG8_LAS unsigned char* lds, const int K  , const Sched& S, const Epi& E) {
;     ...
;         for (int t = 0; t < nt; t += 2) {
;             const bool last = (t == nt - 2);
;             const char* a1 = cA + (size_t)(t + 1) * kstep;
;             const char* a2 = last ? nA : cA + (size_t)(t + 2) * kstep; const char* b2 = last ? nB : cB + (size_t)(t + 2) * kstep;
;             const char* a3 = a2 + kstep; const char* b3 = b2 + kstep;
;             if constexpr (SP2) {
;             PG8_LDB(B0, 0, 0); PG8_LDB(B1, 0, 1); PG8_SCHED; PG8_LDA(At, 0, 0); PG8_STAGE(PG8_SA(1, 1), a1 + hstep, voffA);
;             PG8_WAIT_V(8); PG8_WAIT_L(0); PG8_BAR; PG8_MMA(0, 0, At, B0); PG8_MMA(0, 1, At, B1); PG8_BAR; PG8_SCHED;
;             PG8_LDA(At, 0, 1); PG8_STAGE(PG8_SB(0, 0), b2, voffB); PG8_STAGE(PG8_SB(0, 1), b2 + hstep, voffB); PG8_STAGE(PG8_SA(0, 0), a2, voffA);
;             PG8_WAIT_V(8); PG8_WAIT_L(0); PG8_BAR; PG8_MMA(1, 0, At, B0); PG8_MMA(1, 1, At, B1); PG8_BAR; PG8_SCHED;
.LBB0_2516:
	ds_read_b128 v[16:19], v206
	ds_read_b128 v[20:23], v206 offset:1024
	ds_read_b128 v[24:27], v206 offset:2048
	ds_read_b128 v[28:31], v206 offset:3072
	ds_read_b128 v[0:3], v207
	ds_read_b128 v[4:7], v207 offset:1024
	ds_read_b128 v[8:11], v207 offset:2048
	ds_read_b128 v[12:15], v207 offset:3072
	s_add_u32 s18, s16, 0xfff50080
	s_addc_u32 s19, s17, -1
	s_cmp_eq_u32 s57, 40
	s_cselect_b32 s21, s7, s19
	s_cselect_b32 s20, s6, s18
	s_cselect_b32 s19, s15, s56
	s_cselect_b32 s18, s14, s55
	v_lshl_add_u64 v[200:201], s[16:17], 0, v[176:177]
	s_add_i32 m0, s25, 0xc000
	ds_read_b128 v[160:163], v208
	ds_read_b128 v[164:167], v208 offset:1024
	ds_read_b128 v[184:187], v208 offset:2048
	ds_read_b128 v[188:191], v208 offset:3072
	ds_read_b128 v[192:195], v208 offset:4096
	ds_read_b128 v[196:199], v208 offset:5120
	ds_read_b128 v[210:213], v208 offset:6144
	ds_read_b128 v[214:217], v208 offset:7168
	global_load_lds_dwordx4 v[200:201], off
	v_lshl_add_u64 v[200:201], s[16:17], 0, v[178:179]
	s_add_i32 m0, s25, 0xe000
	s_nop 0
	global_load_lds_dwordx4 v[200:201], off
	s_waitcnt vmcnt(8)
	s_waitcnt lgkmcnt(0)
	s_setprio 1
	s_barrier
	v_mfma_scale_f32_16x16x128_f8f6f4 v[156:159], v[16:23], v[160:167], v[156:159], v202, v202 op_sel_hi:[0,0,0]
	v_mfma_scale_f32_16x16x128_f8f6f4 v[152:155], v[24:31], v[160:167], v[152:155], v202, v202 op_sel_hi:[0,0,0]
	v_mfma_scale_f32_16x16x128_f8f6f4 v[140:143], v[16:23], v[184:191], v[140:143], v202, v202 op_sel_hi:[0,0,0]
	v_mfma_scale_f32_16x16x128_f8f6f4 v[136:139], v[24:31], v[184:191], v[136:139], v202, v202 op_sel_hi:[0,0,0]
	v_mfma_scale_f32_16x16x128_f8f6f4 v[124:127], v[16:23], v[192:199], v[124:127], v202, v202 op_sel_hi:[0,0,0]
	v_mfma_scale_f32_16x16x128_f8f6f4 v[120:123], v[24:31], v[192:199], v[120:123], v202, v202 op_sel_hi:[0,0,0]
	v_mfma_scale_f32_16x16x128_f8f6f4 v[108:111], v[16:23], v[210:217], v[108:111], v202, v202 op_sel_hi:[0,0,0]
	v_mfma_scale_f32_16x16x128_f8f6f4 v[104:107], v[24:31], v[210:217], v[104:107], v202, v202 op_sel_hi:[0,0,0]
	s_setprio 0
	s_setprio 1
	v_mfma_scale_f32_16x16x128_f8f6f4 v[148:151], v[0:7], v[160:167], v[148:151], v202, v202 op_sel_hi:[0,0,0]
	v_mfma_scale_f32_16x16x128_f8f6f4 v[144:147], v[8:15], v[160:167], v[144:147], v202, v202 op_sel_hi:[0,0,0]
	v_mfma_scale_f32_16x16x128_f8f6f4 v[132:135], v[0:7], v[184:191], v[132:135], v202, v202 op_sel_hi:[0,0,0]
	v_mfma_scale_f32_16x16x128_f8f6f4 v[128:131], v[8:15], v[184:191], v[128:131], v202, v202 op_sel_hi:[0,0,0]
	v_mfma_scale_f32_16x16x128_f8f6f4 v[116:119], v[0:7], v[192:199], v[116:119], v202, v202 op_sel_hi:[0,0,0]
	v_mfma_scale_f32_16x16x128_f8f6f4 v[112:115], v[8:15], v[192:199], v[112:115], v202, v202 op_sel_hi:[0,0,0]
	v_mfma_scale_f32_16x16x128_f8f6f4 v[100:103], v[0:7], v[210:217], v[100:103], v202, v202 op_sel_hi:[0,0,0]
	v_mfma_scale_f32_16x16x128_f8f6f4 v[96:99], v[8:15], v[210:217], v[96:99], v202, v202 op_sel_hi:[0,0,0]
	s_barrier
	s_setprio 0
	s_add_i32 s58, s38, s24
	v_lshl_add_u64 v[160:161], s[18:19], 0, v[170:171]
	s_mov_b32 m0, s58
	ds_read_b128 v[184:187], v208 offset:16384
	ds_read_b128 v[188:191], v208 offset:17408
	ds_read_b128 v[192:195], v208 offset:18432
	ds_read_b128 v[196:199], v208 offset:19456
	ds_read_b128 v[210:213], v208 offset:20480
	ds_read_b128 v[214:217], v208 offset:21504
	ds_read_b128 v[218:221], v208 offset:22528
	ds_read_b128 v[222:225], v208 offset:23552
	global_load_lds_dwordx4 v[160:161], off
	s_add_i32 m0, s58, 0x2000
	s_add_u32 s58, s18, 0xb0000
	v_lshl_add_u64 v[162:163], s[18:19], 0, v[174:175]
	s_addc_u32 s59, s19, 0
	s_add_i32 s60, s39, s24
	global_load_lds_dwordx4 v[162:163], off
	v_lshl_add_u64 v[164:165], s[58:59], 0, v[170:171]
	s_mov_b32 m0, s60
	v_lshl_add_u64 v[166:167], s[20:21], 0, v[172:173]
	global_load_lds_dwordx4 v[164:165], off
	v_lshl_add_u64 v[164:165], s[58:59], 0, v[174:175]
	s_add_i32 m0, s60, 0x2000
	s_nop 0
	global_load_lds_dwordx4 v[164:165], off
	v_lshl_add_u64 v[164:165], s[20:21], 0, v[168:169]
	s_mov_b32 m0, s25
	s_nop 0
	global_load_lds_dwordx4 v[164:165], off
	s_mov_b32 m0, s26
	s_nop 0
	global_load_lds_dwordx4 v[166:167], off
	s_waitcnt vmcnt(8)
	s_waitcnt lgkmcnt(0)
	s_setprio 1
	s_barrier
	v_mfma_scale_f32_16x16x128_f8f6f4 v[92:95], v[16:23], v[184:191], v[92:95], v202, v202 op_sel_hi:[0,0,0]
	v_mfma_scale_f32_16x16x128_f8f6f4 v[88:91], v[24:31], v[184:191], v[88:91], v202, v202 op_sel_hi:[0,0,0]
	v_mfma_scale_f32_16x16x128_f8f6f4 v[76:79], v[16:23], v[192:199], v[76:79], v202, v202 op_sel_hi:[0,0,0]
	v_mfma_scale_f32_16x16x128_f8f6f4 v[72:75], v[24:31], v[192:199], v[72:75], v202, v202 op_sel_hi:[0,0,0]
	v_mfma_scale_f32_16x16x128_f8f6f4 v[60:63], v[16:23], v[210:217], v[60:63], v202, v202 op_sel_hi:[0,0,0]
	v_mfma_scale_f32_16x16x128_f8f6f4 v[56:59], v[24:31], v[210:217], v[56:59], v202, v202 op_sel_hi:[0,0,0]
	v_mfma_scale_f32_16x16x128_f8f6f4 v[44:47], v[16:23], v[218:225], v[44:47], v202, v202 op_sel_hi:[0,0,0]
	v_mfma_scale_f32_16x16x128_f8f6f4 v[40:43], v[24:31], v[218:225], v[40:43], v202, v202 op_sel_hi:[0,0,0]
	s_setprio 0
	s_setprio 1
	v_mfma_scale_f32_16x16x128_f8f6f4 v[84:87], v[0:7], v[184:191], v[84:87], v202, v202 op_sel_hi:[0,0,0]
	v_mfma_scale_f32_16x16x128_f8f6f4 v[80:83], v[8:15], v[184:191], v[80:83], v202, v202 op_sel_hi:[0,0,0]
	v_mfma_scale_f32_16x16x128_f8f6f4 v[68:71], v[0:7], v[192:199], v[68:71], v202, v202 op_sel_hi:[0,0,0]
	v_mfma_scale_f32_16x16x128_f8f6f4 v[64:67], v[8:15], v[192:199], v[64:67], v202, v202 op_sel_hi:[0,0,0]
	v_mfma_scale_f32_16x16x128_f8f6f4 v[52:55], v[0:7], v[210:217], v[52:55], v202, v202 op_sel_hi:[0,0,0]
	v_mfma_scale_f32_16x16x128_f8f6f4 v[48:51], v[8:15], v[210:217], v[48:51], v202, v202 op_sel_hi:[0,0,0]
	v_mfma_scale_f32_16x16x128_f8f6f4 v[36:39], v[0:7], v[218:225], v[36:39], v202, v202 op_sel_hi:[0,0,0]
	v_mfma_scale_f32_16x16x128_f8f6f4 v[32:35], v[8:15], v[218:225], v[32:35], v202, v202 op_sel_hi:[0,0,0]
	s_barrier
; #define PG8_STAGE(bufoff, gbase, voff) do { _Pragma("unroll") for (int _i = 0; _i < 2; ++_i) \
;         __builtin_amdgcn_global_load_lds((const unsigned*)((const char*)(gbase) + (voff)[_i]), (PG8_LAS unsigned*)(lds + (bufoff) + ldsw + _i * 8192), 16, 0, 0); } while (0)
; #define PG8_WAIT_V(n) asm volatile("s_waitcnt vmcnt(" #n ")" ::: "memory")
; #define PG8_WAIT_L(n) asm volatile("s_waitcnt lgkmcnt(" #n ")" ::: "memory")
; #define PG8_BAR __builtin_amdgcn_s_barrier()
; #define PG8_SCHED __builtin_amdgcn_sched_barrier(0)
; template <class Epi, class Sched, bool ALIGN_EPI = true, bool SP2 = true>
; __device__ __forceinline__ void gemm_phase(PG8_LAS unsigned char* lds, const int K  , const Sched& S, const Epi& E) {
;     ...
;             PG8_LDB(B0, 1, 0); PG8_LDB(B1, 1, 1); PG8_SCHED; PG8_LDA(At, 1, 0); PG8_STAGE(PG8_SA(0, 1), a2 + hstep, voffA);
;             PG8_WAIT_V(8); PG8_WAIT_L(0); PG8_BAR; PG8_MMA(0, 0, At, B0); PG8_MMA(0, 1, At, B1); PG8_BAR; PG8_SCHED;
;             PG8_LDA(At, 1, 1); PG8_STAGE(PG8_SB(1, 0), b3, voffB); PG8_STAGE(PG8_SB(1, 1), b3 + hstep, voffB); PG8_STAGE(PG8_SA(1, 0), a3, voffA);
;             PG8_WAIT_V(8); PG8_WAIT_L(0); PG8_BAR; PG8_MMA(1, 0, At, B0); PG8_MMA(1, 1, At, B1); PG8_BAR; PG8_SCHED;
;     ...
;         if constexpr (Epi::FP8) asm volatile("s_nop 15\n\ts_nop 15\n\ts_nop 15\n\ts_nop 15\n\ts_nop 15" ::: "memory");
;         if constexpr (ALIGN_EPI) { if (wr == 0) PG8_BAR; }
	s_setprio 0
	s_add_i32 s58, 0, 0x18000
	s_add_i32 s59, 0, 0x1c000
	v_add_u32_e32 v12, s58, v204
	v_add_u32_e32 v28, s59, v204
	ds_read_b128 v[0:3], v12
	ds_read_b128 v[4:7], v12 offset:1024
	ds_read_b128 v[8:11], v12 offset:2048
	ds_read_b128 v[12:15], v12 offset:3072
	ds_read_b128 v[16:19], v28
	ds_read_b128 v[20:23], v28 offset:1024
	ds_read_b128 v[24:27], v28 offset:2048
	ds_read_b128 v[28:31], v28 offset:3072
	s_add_u32 s20, s20, 0xb0000
	s_addc_u32 s21, s21, 0
	s_mov_b32 m0, s27
	v_lshl_add_u64 v[200:201], s[20:21], 0, v[168:169]
	ds_read_b128 v[184:187], v208 offset:32768
	ds_read_b128 v[188:191], v208 offset:33792
	ds_read_b128 v[192:195], v208 offset:34816
	ds_read_b128 v[196:199], v208 offset:35840
	ds_read_b128 v[210:213], v208 offset:36864
	ds_read_b128 v[214:217], v208 offset:37888
	ds_read_b128 v[218:221], v208 offset:38912
	ds_read_b128 v[222:225], v208 offset:39936
	global_load_lds_dwordx4 v[200:201], off
	v_lshl_add_u64 v[200:201], s[20:21], 0, v[172:173]
	s_mov_b32 m0, s28
	s_nop 0
	global_load_lds_dwordx4 v[200:201], off
	s_waitcnt vmcnt(8)
	s_waitcnt lgkmcnt(0)
	s_setprio 1
	s_barrier
	v_mfma_scale_f32_16x16x128_f8f6f4 v[156:159], v[0:7], v[184:191], v[156:159], v202, v202 op_sel_hi:[0,0,0]
	v_mfma_scale_f32_16x16x128_f8f6f4 v[152:155], v[8:15], v[184:191], v[152:155], v202, v202 op_sel_hi:[0,0,0]
	v_mfma_scale_f32_16x16x128_f8f6f4 v[140:143], v[0:7], v[192:199], v[140:143], v202, v202 op_sel_hi:[0,0,0]
	v_mfma_scale_f32_16x16x128_f8f6f4 v[136:139], v[8:15], v[192:199], v[136:139], v202, v202 op_sel_hi:[0,0,0]
	v_mfma_scale_f32_16x16x128_f8f6f4 v[124:127], v[0:7], v[210:217], v[124:127], v202, v202 op_sel_hi:[0,0,0]
	v_mfma_scale_f32_16x16x128_f8f6f4 v[120:123], v[8:15], v[210:217], v[120:123], v202, v202 op_sel_hi:[0,0,0]
	v_mfma_scale_f32_16x16x128_f8f6f4 v[108:111], v[0:7], v[218:225], v[108:111], v202, v202 op_sel_hi:[0,0,0]
	v_mfma_scale_f32_16x16x128_f8f6f4 v[104:107], v[8:15], v[218:225], v[104:107], v202, v202 op_sel_hi:[0,0,0]
	s_setprio 0
	s_setprio 1
	v_mfma_scale_f32_16x16x128_f8f6f4 v[148:151], v[16:23], v[184:191], v[148:151], v202, v202 op_sel_hi:[0,0,0]
	v_mfma_scale_f32_16x16x128_f8f6f4 v[144:147], v[24:31], v[184:191], v[144:147], v202, v202 op_sel_hi:[0,0,0]
	v_mfma_scale_f32_16x16x128_f8f6f4 v[132:135], v[16:23], v[192:199], v[132:135], v202, v202 op_sel_hi:[0,0,0]
	v_mfma_scale_f32_16x16x128_f8f6f4 v[128:131], v[24:31], v[192:199], v[128:131], v202, v202 op_sel_hi:[0,0,0]
	v_mfma_scale_f32_16x16x128_f8f6f4 v[116:119], v[16:23], v[210:217], v[116:119], v202, v202 op_sel_hi:[0,0,0]
	v_mfma_scale_f32_16x16x128_f8f6f4 v[112:115], v[24:31], v[210:217], v[112:115], v202, v202 op_sel_hi:[0,0,0]
	v_mfma_scale_f32_16x16x128_f8f6f4 v[100:103], v[16:23], v[218:225], v[100:103], v202, v202 op_sel_hi:[0,0,0]
	v_mfma_scale_f32_16x16x128_f8f6f4 v[96:99], v[24:31], v[218:225], v[96:99], v202, v202 op_sel_hi:[0,0,0]
	s_barrier
	s_setprio 0
	s_add_i32 s20, s58, s24
	v_lshl_add_u64 v[160:161], v[160:161], 0, s[8:9]
	s_mov_b32 m0, s20
	ds_read_b128 v[184:187], v208 offset:49152
	ds_read_b128 v[188:191], v208 offset:50176
	ds_read_b128 v[192:195], v208 offset:51200
	ds_read_b128 v[196:199], v208 offset:52224
	ds_read_b128 v[210:213], v208 offset:53248
	ds_read_b128 v[214:217], v208 offset:54272
	ds_read_b128 v[218:221], v208 offset:55296
	ds_read_b128 v[222:225], v208 offset:56320
	global_load_lds_dwordx4 v[160:161], off
	s_add_i32 m0, s20, 0x2000
	s_add_u32 s18, s18, 0xb0080
	v_lshl_add_u64 v[160:161], v[162:163], 0, s[8:9]
	s_addc_u32 s19, s19, 0
	s_add_i32 s20, s59, s24
	global_load_lds_dwordx4 v[160:161], off
	v_lshl_add_u64 v[160:161], s[18:19], 0, v[170:171]
	s_mov_b32 m0, s20
	s_nop 0
	global_load_lds_dwordx4 v[160:161], off
	v_lshl_add_u64 v[160:161], s[18:19], 0, v[174:175]
	s_add_i32 m0, s20, 0x2000
	s_nop 0
	global_load_lds_dwordx4 v[160:161], off
	v_lshl_add_u64 v[160:161], v[164:165], 0, s[8:9]
	s_mov_b32 m0, s35
	s_nop 0
	global_load_lds_dwordx4 v[160:161], off
	v_lshl_add_u64 v[160:161], v[166:167], 0, s[8:9]
	s_mov_b32 m0, s36
	s_nop 0
	global_load_lds_dwordx4 v[160:161], off
	s_waitcnt vmcnt(8)
	s_waitcnt lgkmcnt(0)
	s_setprio 1
	s_barrier
	v_mfma_scale_f32_16x16x128_f8f6f4 v[92:95], v[0:7], v[184:191], v[92:95], v202, v202 op_sel_hi:[0,0,0]
	v_mfma_scale_f32_16x16x128_f8f6f4 v[88:91], v[8:15], v[184:191], v[88:91], v202, v202 op_sel_hi:[0,0,0]
	v_mfma_scale_f32_16x16x128_f8f6f4 v[76:79], v[0:7], v[192:199], v[76:79], v202, v202 op_sel_hi:[0,0,0]
	v_mfma_scale_f32_16x16x128_f8f6f4 v[72:75], v[8:15], v[192:199], v[72:75], v202, v202 op_sel_hi:[0,0,0]
	v_mfma_scale_f32_16x16x128_f8f6f4 v[60:63], v[0:7], v[210:217], v[60:63], v202, v202 op_sel_hi:[0,0,0]
	v_mfma_scale_f32_16x16x128_f8f6f4 v[56:59], v[8:15], v[210:217], v[56:59], v202, v202 op_sel_hi:[0,0,0]
	v_mfma_scale_f32_16x16x128_f8f6f4 v[44:47], v[0:7], v[218:225], v[44:47], v202, v202 op_sel_hi:[0,0,0]
	v_mfma_scale_f32_16x16x128_f8f6f4 v[40:43], v[8:15], v[218:225], v[40:43], v202, v202 op_sel_hi:[0,0,0]
	s_setprio 0
	s_setprio 1
	v_mfma_scale_f32_16x16x128_f8f6f4 v[84:87], v[16:23], v[184:191], v[84:87], v202, v202 op_sel_hi:[0,0,0]
	v_mfma_scale_f32_16x16x128_f8f6f4 v[80:83], v[24:31], v[184:191], v[80:83], v202, v202 op_sel_hi:[0,0,0]
	v_mfma_scale_f32_16x16x128_f8f6f4 v[68:71], v[16:23], v[192:199], v[68:71], v202, v202 op_sel_hi:[0,0,0]
	v_mfma_scale_f32_16x16x128_f8f6f4 v[64:67], v[24:31], v[192:199], v[64:67], v202, v202 op_sel_hi:[0,0,0]
	v_mfma_scale_f32_16x16x128_f8f6f4 v[52:55], v[16:23], v[210:217], v[52:55], v202, v202 op_sel_hi:[0,0,0]
	v_mfma_scale_f32_16x16x128_f8f6f4 v[48:51], v[24:31], v[210:217], v[48:51], v202, v202 op_sel_hi:[0,0,0]
	v_mfma_scale_f32_16x16x128_f8f6f4 v[36:39], v[16:23], v[218:225], v[36:39], v202, v202 op_sel_hi:[0,0,0]
	v_mfma_scale_f32_16x16x128_f8f6f4 v[32:35], v[24:31], v[218:225], v[32:35], v202, v202 op_sel_hi:[0,0,0]
	s_barrier
	s_setprio 0
	s_add_i32 s57, s57, 2
	s_add_u32 s16, s16, 0x100
	s_addc_u32 s17, s17, 0
	s_add_u32 s55, s55, 0x100
	s_addc_u32 s56, s56, 0
	s_cmp_gt_u32 s57, 41
	s_cbranch_scc0 .LBB0_2516
	s_nop 15
	s_nop 15
	s_nop 15
	s_nop 15
	s_nop 15
	s_and_b64 vcc, exec, s[10:11]
	s_cbranch_vccz .LBB0_2519
	s_barrier
